# v37 + K-loop counted tile-load wait of waves 0-3 moved behind their MFMA block (to the last barrier before the readers), waves 4-7 unchanged
# speedup vs baseline: 1.0011x; 1.0005x over previous
;     __device__ __forceinline__ void operator()(const f32x4 (&acc)[2][2][4][2], const Unit& u, int wr, int wc, int fr, int fq) const {
;     ...
;         { f32x4 pa[2][4], pb[2][4];
; #pragma unroll
;           for (int ai = 0; ai < 2; ++ai)
; #pragma unroll
;             for (int m = 0; m < 4; ++m) { const float* p_ = st2 + (size_t)(row0 + ai * HALF + m * 16) * 8; pa[ai][m] = *(const f32x4*)p_; pb[ai][m] = *(const f32x4*)(p_ + 4); }
;           __builtin_amdgcn_sched_barrier(0);
; #pragma unroll
;           for (int ai = 0; ai < 2; ++ai)
; #pragma unroll
;             for (int m = 0; m < 4; ++m) { const f32x4 t_ = pa[ai][m] + pb[ai][m]; rs8[ai][m] = __builtin_amdgcn_rsqf(((t_[0] + t_[1]) + (t_[2] + t_[3])) * (1.0f / (float)D) + 1e-6f); }
;           __builtin_amdgcn_sched_barrier(0); }
.Lmy_rsfill_done:
	s_or_b64 exec, exec, s[100:101]
	s_mov_b32 s100, s54
	s_waitcnt lgkmcnt(0)
	s_barrier
	v_readlane_b32 s19, v253, 54
	s_branch .LBB0_134
	s_nop 0
	s_nop 0
	s_nop 0
	s_nop 0
	s_nop 0
	s_nop 0
	s_nop 0
	s_nop 0
	s_nop 0
	s_nop 0
	s_nop 0
	s_nop 0
	s_nop 0
	s_nop 0
	s_nop 0
	s_nop 0
	s_nop 0
	s_nop 0
	s_nop 0
	s_nop 0
	s_nop 0
	s_nop 0
	s_nop 0
	s_nop 0
	s_nop 0
	s_nop 0
	s_nop 0
	s_nop 0
	s_nop 0
	s_nop 0
	s_nop 0
.LBB0_132:
	s_mov_b64 s[26:27], 0

; #define PG8_STAGE(bufoff, gbase, voff) do { _Pragma("unroll") for (int _i = 0; _i < 2; ++_i) \
;         __builtin_amdgcn_global_load_lds((const unsigned*)((const char*)(gbase) + (voff)[_i]), (LAS unsigned*)(lds + (bufoff) + ldsw + _i * 8192), 16, 0, 0); } while (0)
; #define PG8_LDA(dst, b, h) do { _Pragma("unroll") for (int m = 0; m < 4; ++m) _Pragma("unroll") for (int k = 0; k < 2; ++k) dst[m][k] = *(const LAS bf16x8*)(lds + PG8_SA(b, h) + aoff + m * 2048 + k * 1024); } while (0)
; #define PG8_LDB(dst, b, h) do { _Pragma("unroll") for (int n = 0; n < 2; ++n) _Pragma("unroll") for (int k = 0; k < 2; ++k) dst[n][k] = *(const LAS bf16x8*)(lds + PG8_SB(b, h) + boff + n * 2048 + k * 1024); } while (0)
; #define PG8_WAIT_V(n) asm volatile("s_waitcnt vmcnt(" #n ")" ::: "memory")
; #define PG8_WAIT_L(n) asm volatile("s_waitcnt lgkmcnt(" #n ")" ::: "memory")
; #define PG8_BAR __builtin_amdgcn_s_barrier()
; #define PG8_SCHED __builtin_amdgcn_sched_barrier(0)
; template <class Epi, class Sched>
; __device__ __forceinline__ void gemm_phase(LAS unsigned char* lds, const Gemm g, const Sched& S, const Epi& E) {
;     ...
;         const bool has_next = S.next(ui + 1, nxt);
;         const char* nA = has_next ? (const char*)g.A + (size_t)nxt.pm * tstepA + (size_t)nxt.ka * 2 : cA; const char* nB = has_next ? (const char*)g.Bt + (size_t)nxt.pn * tstepB : cB;
;         for (int t = 0; t < nt; t += 2) {
;             const bool last = (t == nt - 2);
;             const char* a1 = cA + (size_t)(t + 1) * kstep;
;             const char* a2 = last ? nA : cA + (size_t)(t + 2) * kstep; const char* b2 = last ? nB : cB + (size_t)(t + 2) * kstep;
;             const char* a3 = a2 + kstep; const char* b3 = b2 + kstep;
;             if (last && has_next) S.a_ready(nxt);
;             PG8_LDB(B0, 0, 0); PG8_LDB(B1, 0, 1); PG8_SCHED; PG8_LDA(At, 0, 0); PG8_STAGE(PG8_SA(1, 1), a1 + hstepA, voffA);
;             PG8_WAIT_V(8); PG8_WAIT_L(0); PG8_BAR; PG8_MMA(0, 0, At, B0); PG8_MMA(0, 1, At, B1); PG8_BAR; PG8_SCHED;
;     ...
; #pragma unroll
;         for (int a = 0; a < 2; ++a)
; #pragma unroll
;             for (int b = 0; b < 2; ++b)
; #pragma unroll
;                 for (int m = 0; m < 4; ++m)
; #pragma unroll
;                     for (int n = 0; n < 2; ++n) acc[a][b][m][n] = (f32x4){0.f, 0.f, 0.f, 0.f};
.LBB0_136:
	s_ashr_i32 s21, s20, 31
	s_lshl_b64 s[22:23], s[20:21], 20
	s_add_u32 s22, s34, s22
	s_addc_u32 s23, s42, s23
	s_and_b64 s[24:25], s[38:39], exec
	s_cselect_b32 s21, s23, s27
	s_cselect_b32 s55, s22, s26
	s_ashr_i32 s19, s18, 31
	s_lshl_b64 s[24:25], s[18:19], 20
	s_add_u32 s24, s43, s24
	s_addc_u32 s25, s44, s25
	s_and_b64 s[40:41], s[38:39], exec
	s_cselect_b32 s19, s25, s29
	s_cselect_b32 s56, s24, s28
	s_add_u32 s26, s26, 0x80080
	s_addc_u32 s27, s27, 0
	s_add_u32 s57, s28, 0x100
	v_mov_b32_e32 v6, 0
	s_addc_u32 s58, s29, 0
	s_mov_b32 s59, -2
	v_mov_b32_e32 v7, v6
	v_mov_b32_e32 v8, v6
	v_mov_b32_e32 v9, v6
	v_mov_b32_e32 v14, v6
	v_mov_b32_e32 v15, v6
	v_mov_b32_e32 v16, v6
	v_mov_b32_e32 v17, v6
	v_mov_b32_e32 v22, v6
	v_mov_b32_e32 v23, v6
	v_mov_b32_e32 v24, v6
	v_mov_b32_e32 v25, v6
	v_mov_b32_e32 v30, v6
	v_mov_b32_e32 v31, v6
	v_mov_b32_e32 v32, v6
	v_mov_b32_e32 v33, v6
	v_mov_b32_e32 v38, v6
	v_mov_b32_e32 v39, v6
	v_mov_b32_e32 v40, v6
	v_mov_b32_e32 v41, v6
	v_mov_b32_e32 v46, v6
	v_mov_b32_e32 v47, v6
	v_mov_b32_e32 v48, v6
	v_mov_b32_e32 v49, v6
	v_mov_b32_e32 v54, v6
	v_mov_b32_e32 v55, v6
	v_mov_b32_e32 v56, v6
	v_mov_b32_e32 v57, v6
	v_mov_b32_e32 v62, v6
	v_mov_b32_e32 v63, v6
	v_mov_b32_e32 v64, v6
	v_mov_b32_e32 v65, v6
	v_mov_b32_e32 v10, v6
	v_mov_b32_e32 v11, v6
	v_mov_b32_e32 v12, v6
	v_mov_b32_e32 v13, v6
	v_mov_b32_e32 v18, v6
	v_mov_b32_e32 v19, v6
	v_mov_b32_e32 v20, v6
	v_mov_b32_e32 v21, v6
	v_mov_b32_e32 v26, v6
	v_mov_b32_e32 v27, v6
	v_mov_b32_e32 v28, v6
	v_mov_b32_e32 v29, v6
	v_mov_b32_e32 v34, v6
	v_mov_b32_e32 v35, v6
	v_mov_b32_e32 v36, v6
	v_mov_b32_e32 v37, v6
	v_mov_b32_e32 v42, v6
	v_mov_b32_e32 v43, v6
	v_mov_b32_e32 v44, v6
	v_mov_b32_e32 v45, v6
	v_mov_b32_e32 v50, v6
	v_mov_b32_e32 v51, v6
	v_mov_b32_e32 v52, v6
	v_mov_b32_e32 v53, v6
	v_mov_b32_e32 v58, v6
	v_mov_b32_e32 v59, v6
	v_mov_b32_e32 v60, v6
	v_mov_b32_e32 v61, v6
	v_mov_b32_e32 v66, v6
	v_mov_b32_e32 v67, v6
	v_mov_b32_e32 v68, v6
	v_mov_b32_e32 v69, v6
	v_mov_b32_e32 v70, v6
	v_mov_b32_e32 v71, v6
	v_mov_b32_e32 v72, v6
	v_mov_b32_e32 v73, v6
	v_mov_b32_e32 v78, v6
	v_mov_b32_e32 v79, v6
	v_mov_b32_e32 v80, v6
	v_mov_b32_e32 v81, v6
	v_mov_b32_e32 v86, v6
	v_mov_b32_e32 v87, v6
	v_mov_b32_e32 v88, v6
	v_mov_b32_e32 v89, v6
	v_mov_b32_e32 v94, v6
	v_mov_b32_e32 v95, v6
	v_mov_b32_e32 v96, v6
	v_mov_b32_e32 v97, v6
	v_mov_b32_e32 v102, v6
	v_mov_b32_e32 v103, v6
	v_mov_b32_e32 v104, v6
	v_mov_b32_e32 v105, v6
	v_mov_b32_e32 v110, v6
	v_mov_b32_e32 v111, v6
	v_mov_b32_e32 v112, v6
	v_mov_b32_e32 v113, v6
	v_mov_b32_e32 v118, v6
	v_mov_b32_e32 v119, v6
	v_mov_b32_e32 v120, v6
	v_mov_b32_e32 v121, v6
	v_mov_b32_e32 v126, v6
	v_mov_b32_e32 v127, v6
	v_mov_b32_e32 v128, v6
	v_mov_b32_e32 v129, v6
	v_mov_b32_e32 v74, v6
	v_mov_b32_e32 v75, v6
	v_mov_b32_e32 v76, v6
	v_mov_b32_e32 v77, v6
	v_mov_b32_e32 v82, v6
	v_mov_b32_e32 v83, v6
	v_mov_b32_e32 v84, v6
	v_mov_b32_e32 v85, v6
	v_mov_b32_e32 v90, v6
	v_mov_b32_e32 v91, v6
	v_mov_b32_e32 v92, v6
	v_mov_b32_e32 v93, v6
	v_mov_b32_e32 v98, v6
	v_mov_b32_e32 v99, v6
	v_mov_b32_e32 v100, v6
	v_mov_b32_e32 v101, v6
	v_mov_b32_e32 v106, v6
	v_mov_b32_e32 v107, v6
	v_mov_b32_e32 v108, v6
	v_mov_b32_e32 v109, v6
	v_mov_b32_e32 v114, v6
	v_mov_b32_e32 v115, v6
	v_mov_b32_e32 v116, v6
	v_mov_b32_e32 v117, v6
	v_mov_b32_e32 v122, v6
	v_mov_b32_e32 v123, v6
	v_mov_b32_e32 v124, v6
	v_mov_b32_e32 v125, v6
	v_mov_b32_e32 v130, v6
	v_mov_b32_e32 v131, v6
	v_mov_b32_e32 v132, v6
	v_mov_b32_e32 v133, v6
	v_readfirstlane_b32 s101, v0
.LBB0_137:
	s_add_u32 s28, s26, 0xfff80080
	s_addc_u32 s29, s27, -1
	s_add_i32 s60, 0, 0x10000
	s_cmp_eq_u32 s59, 28
	s_cselect_b32 s41, s21, s29
	s_cselect_b32 s40, s55, s28
	s_cselect_b32 s29, s19, s58
	s_cselect_b32 s28, s56, s57
	s_add_i32 s62, 0, 0x14000
	v_add_u32_e32 v154, s60, v159
	v_add_u32_e32 v174, s62, v159
	ds_read_b128 v[142:145], v154
	ds_read_b128 v[146:149], v154 offset:1024
	ds_read_b128 v[150:153], v154 offset:2048
	ds_read_b128 v[154:157], v154 offset:3072
	ds_read_b128 v[162:165], v174
	ds_read_b128 v[166:169], v174 offset:1024
	ds_read_b128 v[170:173], v174 offset:2048
	ds_read_b128 v[174:177], v174 offset:3072
	v_lshl_add_u64 v[224:225], s[26:27], 0, v[138:139]
	s_add_i32 m0, s46, 0xc000
	ds_read_b128 v[178:181], v161
	ds_read_b128 v[182:185], v161 offset:1024
	ds_read_b128 v[186:189], v161 offset:2048
	ds_read_b128 v[190:193], v161 offset:3072
	ds_read_b128 v[194:197], v161 offset:4096
	ds_read_b128 v[212:215], v161 offset:5120
	ds_read_b128 v[216:219], v161 offset:6144
	ds_read_b128 v[220:223], v161 offset:7168
	global_load_lds_dwordx4 v[224:225], off
	v_lshl_add_u64 v[224:225], s[26:27], 0, v[140:141]
	s_add_i32 m0, s46, 0xe000
	s_nop 0
	global_load_lds_dwordx4 v[224:225], off
	s_bitcmp1_b32 s101, 8
	s_cbranch_scc0 .Lmy_wv_4238
	s_waitcnt vmcnt(8)
; #define PG8_STAGE(bufoff, gbase, voff) do { _Pragma("unroll") for (int _i = 0; _i < 2; ++_i) \
;         __builtin_amdgcn_global_load_lds((const unsigned*)((const char*)(gbase) + (voff)[_i]), (LAS unsigned*)(lds + (bufoff) + ldsw + _i * 8192), 16, 0, 0); } while (0)
; #define PG8_LDA(dst, b, h) do { _Pragma("unroll") for (int m = 0; m < 4; ++m) _Pragma("unroll") for (int k = 0; k < 2; ++k) dst[m][k] = *(const LAS bf16x8*)(lds + PG8_SA(b, h) + aoff + m * 2048 + k * 1024); } while (0)
; #define PG8_LDB(dst, b, h) do { _Pragma("unroll") for (int n = 0; n < 2; ++n) _Pragma("unroll") for (int k = 0; k < 2; ++k) dst[n][k] = *(const LAS bf16x8*)(lds + PG8_SB(b, h) + boff + n * 2048 + k * 1024); } while (0)
; #define PG8_MMA(ai, bj, At, Bt) do { __builtin_amdgcn_s_setprio(1); _Pragma("unroll") for (int m = 0; m < 4; ++m) _Pragma("unroll") for (int n = 0; n < 2; ++n) _Pragma("unroll") for (int k = 0; k < 2; ++k) \
;         acc[ai][bj][m][n] = __builtin_amdgcn_mfma_f32_16x16x32_bf16(Bt[n][k], At[m][k], acc[ai][bj][m][n], 0, 0, 0); __builtin_amdgcn_s_setprio(0); } while (0)
; #define PG8_WAIT_V(n) asm volatile("s_waitcnt vmcnt(" #n ")" ::: "memory")
; #define PG8_WAIT_L(n) asm volatile("s_waitcnt lgkmcnt(" #n ")" ::: "memory")
; #define PG8_BAR __builtin_amdgcn_s_barrier()
; #define PG8_SCHED __builtin_amdgcn_sched_barrier(0)
; template <class Epi, class Sched>
; __device__ __forceinline__ void gemm_phase(LAS unsigned char* lds, const Gemm g, const Sched& S, const Epi& E) {
;     ...
;             PG8_WAIT_V(8); PG8_WAIT_L(0); PG8_BAR; PG8_MMA(0, 0, At, B0); PG8_MMA(0, 1, At, B1); PG8_BAR; PG8_SCHED;
;             PG8_LDA(At, 0, 1); PG8_STAGE(PG8_SB(0, 0), b2, voffB); PG8_STAGE(PG8_SB(0, 1), b2 + hstepB, voffB); PG8_STAGE(PG8_SA(0, 0), a2, voffA);
;             PG8_WAIT_V(8); PG8_WAIT_L(0); PG8_BAR; PG8_MMA(1, 0, At, B0); PG8_MMA(1, 1, At, B1); PG8_BAR; PG8_SCHED;
;             PG8_LDB(B0, 1, 0); PG8_LDB(B1, 1, 1); PG8_SCHED; PG8_LDA(At, 1, 0); PG8_STAGE(PG8_SA(0, 1), a2 + hstepA, voffA);
;             PG8_WAIT_V(8); PG8_WAIT_L(0); PG8_BAR; PG8_MMA(0, 0, At, B0); PG8_MMA(0, 1, At, B1); PG8_BAR; PG8_SCHED;
.Lmy_wv_4238:
	s_waitcnt lgkmcnt(0)
	s_barrier
	s_waitcnt lgkmcnt(0)
	v_mfma_f32_16x16x32_bf16 v[130:133], v[142:145], v[178:181], v[130:133]
	v_mfma_f32_16x16x32_bf16 v[122:125], v[150:153], v[178:181], v[122:125]
	v_mfma_f32_16x16x32_bf16 v[114:117], v[142:145], v[186:189], v[114:117]
	v_mfma_f32_16x16x32_bf16 v[106:109], v[150:153], v[186:189], v[106:109]
	v_mfma_f32_16x16x32_bf16 v[98:101], v[142:145], v[194:197], v[98:101]
	v_mfma_f32_16x16x32_bf16 v[90:93], v[150:153], v[194:197], v[90:93]
	v_mfma_f32_16x16x32_bf16 v[82:85], v[142:145], v[216:219], v[82:85]
	v_mfma_f32_16x16x32_bf16 v[74:77], v[150:153], v[216:219], v[74:77]
	v_mfma_f32_16x16x32_bf16 v[130:133], v[146:149], v[182:185], v[130:133]
	v_mfma_f32_16x16x32_bf16 v[122:125], v[154:157], v[182:185], v[122:125]
	v_mfma_f32_16x16x32_bf16 v[114:117], v[146:149], v[190:193], v[114:117]
	v_mfma_f32_16x16x32_bf16 v[106:109], v[154:157], v[190:193], v[106:109]
	v_mfma_f32_16x16x32_bf16 v[98:101], v[146:149], v[212:215], v[98:101]
	v_mfma_f32_16x16x32_bf16 v[90:93], v[154:157], v[212:215], v[90:93]
	v_mfma_f32_16x16x32_bf16 v[82:85], v[146:149], v[220:223], v[82:85]
	v_mfma_f32_16x16x32_bf16 v[74:77], v[154:157], v[220:223], v[74:77]
	v_mfma_f32_16x16x32_bf16 v[126:129], v[162:165], v[178:181], v[126:129]
	v_mfma_f32_16x16x32_bf16 v[118:121], v[170:173], v[178:181], v[118:121]
	v_mfma_f32_16x16x32_bf16 v[110:113], v[162:165], v[186:189], v[110:113]
	v_mfma_f32_16x16x32_bf16 v[102:105], v[170:173], v[186:189], v[102:105]
	v_mfma_f32_16x16x32_bf16 v[94:97], v[162:165], v[194:197], v[94:97]
	v_mfma_f32_16x16x32_bf16 v[86:89], v[170:173], v[194:197], v[86:89]
	v_mfma_f32_16x16x32_bf16 v[78:81], v[162:165], v[216:219], v[78:81]
	v_mfma_f32_16x16x32_bf16 v[70:73], v[170:173], v[216:219], v[70:73]
	v_mfma_f32_16x16x32_bf16 v[126:129], v[166:169], v[182:185], v[126:129]
	v_mfma_f32_16x16x32_bf16 v[118:121], v[174:177], v[182:185], v[118:121]
	v_mfma_f32_16x16x32_bf16 v[110:113], v[166:169], v[190:193], v[110:113]
	v_mfma_f32_16x16x32_bf16 v[102:105], v[174:177], v[190:193], v[102:105]
	v_mfma_f32_16x16x32_bf16 v[94:97], v[166:169], v[212:215], v[94:97]
	v_mfma_f32_16x16x32_bf16 v[86:89], v[174:177], v[212:215], v[86:89]
	v_mfma_f32_16x16x32_bf16 v[78:81], v[166:169], v[220:223], v[78:81]
	v_mfma_f32_16x16x32_bf16 v[70:73], v[174:177], v[220:223], v[70:73]
	s_waitcnt vmcnt(8)
	s_barrier
	s_add_i32 s60, s60, s45
	v_lshl_add_u64 v[224:225], s[28:29], 0, v[4:5]
	s_mov_b32 m0, s60
	ds_read_b128 v[178:181], v161 offset:16384
	ds_read_b128 v[182:185], v161 offset:17408
	ds_read_b128 v[186:189], v161 offset:18432
	ds_read_b128 v[190:193], v161 offset:19456
	ds_read_b128 v[194:197], v161 offset:20480
	ds_read_b128 v[212:215], v161 offset:21504
	ds_read_b128 v[216:219], v161 offset:22528
	ds_read_b128 v[220:223], v161 offset:23552
	global_load_lds_dwordx4 v[224:225], off
	s_add_i32 m0, s60, 0x2000
	s_add_u32 s60, s28, 0x80000
	v_lshl_add_u64 v[226:227], s[28:29], 0, v[2:3]
	s_addc_u32 s61, s29, 0
	s_add_i32 s62, s62, s45
	global_load_lds_dwordx4 v[226:227], off
	v_lshl_add_u64 v[228:229], s[60:61], 0, v[4:5]
	s_mov_b32 m0, s62
	v_lshl_add_u64 v[230:231], s[40:41], 0, v[134:135]
	global_load_lds_dwordx4 v[228:229], off
	v_lshl_add_u64 v[228:229], s[60:61], 0, v[2:3]
	s_add_i32 m0, s62, 0x2000
	s_nop 0
	global_load_lds_dwordx4 v[228:229], off
	v_lshl_add_u64 v[228:229], s[40:41], 0, v[136:137]
	s_mov_b32 m0, s46
	s_nop 0
	global_load_lds_dwordx4 v[228:229], off
	s_mov_b32 m0, s47
	s_nop 0
	global_load_lds_dwordx4 v[230:231], off
	s_bitcmp1_b32 s101, 8
	s_cbranch_scc0 .Lmy_wv_4317
	s_waitcnt vmcnt(8)
.Lmy_wv_4317:
	s_waitcnt lgkmcnt(0)
	s_barrier
	s_waitcnt lgkmcnt(0)
	v_mfma_f32_16x16x32_bf16 v[66:69], v[142:145], v[178:181], v[66:69]
	v_mfma_f32_16x16x32_bf16 v[58:61], v[150:153], v[178:181], v[58:61]
	v_mfma_f32_16x16x32_bf16 v[50:53], v[142:145], v[186:189], v[50:53]
	v_mfma_f32_16x16x32_bf16 v[42:45], v[150:153], v[186:189], v[42:45]
	v_mfma_f32_16x16x32_bf16 v[34:37], v[142:145], v[194:197], v[34:37]
	v_mfma_f32_16x16x32_bf16 v[26:29], v[150:153], v[194:197], v[26:29]
	v_mfma_f32_16x16x32_bf16 v[18:21], v[142:145], v[216:219], v[18:21]
	v_mfma_f32_16x16x32_bf16 v[10:13], v[150:153], v[216:219], v[10:13]
	v_mfma_f32_16x16x32_bf16 v[66:69], v[146:149], v[182:185], v[66:69]
	v_mfma_f32_16x16x32_bf16 v[58:61], v[154:157], v[182:185], v[58:61]
	v_mfma_f32_16x16x32_bf16 v[50:53], v[146:149], v[190:193], v[50:53]
	v_mfma_f32_16x16x32_bf16 v[42:45], v[154:157], v[190:193], v[42:45]
	v_mfma_f32_16x16x32_bf16 v[34:37], v[146:149], v[212:215], v[34:37]
	v_mfma_f32_16x16x32_bf16 v[26:29], v[154:157], v[212:215], v[26:29]
	v_mfma_f32_16x16x32_bf16 v[18:21], v[146:149], v[220:223], v[18:21]
	v_mfma_f32_16x16x32_bf16 v[10:13], v[154:157], v[220:223], v[10:13]
	v_mfma_f32_16x16x32_bf16 v[62:65], v[162:165], v[178:181], v[62:65]
	v_mfma_f32_16x16x32_bf16 v[54:57], v[170:173], v[178:181], v[54:57]
	v_mfma_f32_16x16x32_bf16 v[46:49], v[162:165], v[186:189], v[46:49]
	v_mfma_f32_16x16x32_bf16 v[38:41], v[170:173], v[186:189], v[38:41]
	v_mfma_f32_16x16x32_bf16 v[30:33], v[162:165], v[194:197], v[30:33]
	v_mfma_f32_16x16x32_bf16 v[22:25], v[170:173], v[194:197], v[22:25]
	v_mfma_f32_16x16x32_bf16 v[14:17], v[162:165], v[216:219], v[14:17]
	v_mfma_f32_16x16x32_bf16 v[6:9], v[170:173], v[216:219], v[6:9]
	v_mfma_f32_16x16x32_bf16 v[62:65], v[166:169], v[182:185], v[62:65]
	v_mfma_f32_16x16x32_bf16 v[54:57], v[174:177], v[182:185], v[54:57]
	v_mfma_f32_16x16x32_bf16 v[46:49], v[166:169], v[190:193], v[46:49]
	v_mfma_f32_16x16x32_bf16 v[38:41], v[174:177], v[190:193], v[38:41]
	v_mfma_f32_16x16x32_bf16 v[30:33], v[166:169], v[212:215], v[30:33]
	v_mfma_f32_16x16x32_bf16 v[22:25], v[174:177], v[212:215], v[22:25]
	v_mfma_f32_16x16x32_bf16 v[14:17], v[166:169], v[220:223], v[14:17]
	v_mfma_f32_16x16x32_bf16 v[6:9], v[174:177], v[220:223], v[6:9]
	s_waitcnt vmcnt(8)
	s_barrier
	s_add_i32 s60, 0, 0x18000
	s_add_i32 s61, 0, 0x1c000
	v_add_u32_e32 v154, s60, v159
	v_add_u32_e32 v174, s61, v159
	ds_read_b128 v[142:145], v154
	ds_read_b128 v[146:149], v154 offset:1024
	ds_read_b128 v[150:153], v154 offset:2048
	ds_read_b128 v[154:157], v154 offset:3072
	ds_read_b128 v[162:165], v174
	ds_read_b128 v[166:169], v174 offset:1024
	ds_read_b128 v[170:173], v174 offset:2048
	ds_read_b128 v[174:177], v174 offset:3072
	s_add_u32 s40, s40, 0x80000
	s_addc_u32 s41, s41, 0
	s_mov_b32 m0, s48
	v_lshl_add_u64 v[236:237], s[40:41], 0, v[136:137]
	ds_read_b128 v[178:181], v161 offset:32768
	ds_read_b128 v[182:185], v161 offset:33792
	ds_read_b128 v[186:189], v161 offset:34816
	ds_read_b128 v[190:193], v161 offset:35840
	ds_read_b128 v[194:197], v161 offset:36864
	ds_read_b128 v[212:215], v161 offset:37888
	ds_read_b128 v[216:219], v161 offset:38912
	ds_read_b128 v[220:223], v161 offset:39936
	global_load_lds_dwordx4 v[236:237], off
	v_lshl_add_u64 v[236:237], s[40:41], 0, v[134:135]
	s_mov_b32 m0, s49
	s_nop 0
	global_load_lds_dwordx4 v[236:237], off
	s_bitcmp1_b32 s101, 8
	s_cbranch_scc0 .Lmy_wv_4393
	s_waitcnt vmcnt(8)
; #define PG8_STAGE(bufoff, gbase, voff) do { _Pragma("unroll") for (int _i = 0; _i < 2; ++_i) \
;         __builtin_amdgcn_global_load_lds((const unsigned*)((const char*)(gbase) + (voff)[_i]), (LAS unsigned*)(lds + (bufoff) + ldsw + _i * 8192), 16, 0, 0); } while (0)
; #define PG8_LDA(dst, b, h) do { _Pragma("unroll") for (int m = 0; m < 4; ++m) _Pragma("unroll") for (int k = 0; k < 2; ++k) dst[m][k] = *(const LAS bf16x8*)(lds + PG8_SA(b, h) + aoff + m * 2048 + k * 1024); } while (0)
; #define PG8_MMA(ai, bj, At, Bt) do { __builtin_amdgcn_s_setprio(1); _Pragma("unroll") for (int m = 0; m < 4; ++m) _Pragma("unroll") for (int n = 0; n < 2; ++n) _Pragma("unroll") for (int k = 0; k < 2; ++k) \
;         acc[ai][bj][m][n] = __builtin_amdgcn_mfma_f32_16x16x32_bf16(Bt[n][k], At[m][k], acc[ai][bj][m][n], 0, 0, 0); __builtin_amdgcn_s_setprio(0); } while (0)
; #define PG8_WAIT_V(n) asm volatile("s_waitcnt vmcnt(" #n ")" ::: "memory")
; #define PG8_WAIT_L(n) asm volatile("s_waitcnt lgkmcnt(" #n ")" ::: "memory")
; #define PG8_BAR __builtin_amdgcn_s_barrier()
; #define PG8_SCHED __builtin_amdgcn_sched_barrier(0)
; template <class Epi, class Sched>
; __device__ __forceinline__ void gemm_phase(LAS unsigned char* lds, const Gemm g, const Sched& S, const Epi& E) {
;     ...
;             PG8_WAIT_V(8); PG8_WAIT_L(0); PG8_BAR; PG8_MMA(0, 0, At, B0); PG8_MMA(0, 1, At, B1); PG8_BAR; PG8_SCHED;
;             PG8_LDA(At, 1, 1); PG8_STAGE(PG8_SB(1, 0), b3, voffB); PG8_STAGE(PG8_SB(1, 1), b3 + hstepB, voffB); PG8_STAGE(PG8_SA(1, 0), a3, voffA);
;             PG8_WAIT_V(8); PG8_WAIT_L(0); PG8_BAR; PG8_MMA(1, 0, At, B0); PG8_MMA(1, 1, At, B1); PG8_BAR; PG8_SCHED;
;         }
.Lmy_wv_4393:
	s_waitcnt lgkmcnt(0)
	s_barrier
	s_waitcnt lgkmcnt(0)
	v_mfma_f32_16x16x32_bf16 v[130:133], v[142:145], v[178:181], v[130:133]
	v_mfma_f32_16x16x32_bf16 v[122:125], v[150:153], v[178:181], v[122:125]
	v_mfma_f32_16x16x32_bf16 v[114:117], v[142:145], v[186:189], v[114:117]
	v_mfma_f32_16x16x32_bf16 v[106:109], v[150:153], v[186:189], v[106:109]
	v_mfma_f32_16x16x32_bf16 v[98:101], v[142:145], v[194:197], v[98:101]
	v_mfma_f32_16x16x32_bf16 v[90:93], v[150:153], v[194:197], v[90:93]
	v_mfma_f32_16x16x32_bf16 v[82:85], v[142:145], v[216:219], v[82:85]
	v_mfma_f32_16x16x32_bf16 v[74:77], v[150:153], v[216:219], v[74:77]
	v_mfma_f32_16x16x32_bf16 v[130:133], v[146:149], v[182:185], v[130:133]
	v_mfma_f32_16x16x32_bf16 v[122:125], v[154:157], v[182:185], v[122:125]
	v_mfma_f32_16x16x32_bf16 v[114:117], v[146:149], v[190:193], v[114:117]
	v_mfma_f32_16x16x32_bf16 v[106:109], v[154:157], v[190:193], v[106:109]
	v_mfma_f32_16x16x32_bf16 v[98:101], v[146:149], v[212:215], v[98:101]
	v_mfma_f32_16x16x32_bf16 v[90:93], v[154:157], v[212:215], v[90:93]
	v_mfma_f32_16x16x32_bf16 v[82:85], v[146:149], v[220:223], v[82:85]
	v_mfma_f32_16x16x32_bf16 v[74:77], v[154:157], v[220:223], v[74:77]
	v_mfma_f32_16x16x32_bf16 v[126:129], v[162:165], v[178:181], v[126:129]
	v_mfma_f32_16x16x32_bf16 v[118:121], v[170:173], v[178:181], v[118:121]
	v_mfma_f32_16x16x32_bf16 v[110:113], v[162:165], v[186:189], v[110:113]
	v_mfma_f32_16x16x32_bf16 v[102:105], v[170:173], v[186:189], v[102:105]
	v_mfma_f32_16x16x32_bf16 v[94:97], v[162:165], v[194:197], v[94:97]
	v_mfma_f32_16x16x32_bf16 v[86:89], v[170:173], v[194:197], v[86:89]
	v_mfma_f32_16x16x32_bf16 v[78:81], v[162:165], v[216:219], v[78:81]
	v_mfma_f32_16x16x32_bf16 v[70:73], v[170:173], v[216:219], v[70:73]
	v_mfma_f32_16x16x32_bf16 v[126:129], v[166:169], v[182:185], v[126:129]
	v_mfma_f32_16x16x32_bf16 v[118:121], v[174:177], v[182:185], v[118:121]
	v_mfma_f32_16x16x32_bf16 v[110:113], v[166:169], v[190:193], v[110:113]
	v_mfma_f32_16x16x32_bf16 v[102:105], v[174:177], v[190:193], v[102:105]
	v_mfma_f32_16x16x32_bf16 v[94:97], v[166:169], v[212:215], v[94:97]
	v_mfma_f32_16x16x32_bf16 v[86:89], v[174:177], v[212:215], v[86:89]
	v_mfma_f32_16x16x32_bf16 v[78:81], v[166:169], v[220:223], v[78:81]
	v_mfma_f32_16x16x32_bf16 v[70:73], v[174:177], v[220:223], v[70:73]
	s_waitcnt vmcnt(8)
	s_barrier
	s_add_i32 s40, s60, s45
	v_lshl_add_u64 v[224:225], v[224:225], 0, s[36:37]
	s_mov_b32 m0, s40
	ds_read_b128 v[178:181], v161 offset:49152
	ds_read_b128 v[182:185], v161 offset:50176
	ds_read_b128 v[186:189], v161 offset:51200
	ds_read_b128 v[190:193], v161 offset:52224
	ds_read_b128 v[194:197], v161 offset:53248
	ds_read_b128 v[212:215], v161 offset:54272
	ds_read_b128 v[216:219], v161 offset:55296
	ds_read_b128 v[220:223], v161 offset:56320
	global_load_lds_dwordx4 v[224:225], off
	s_add_i32 m0, s40, 0x2000
	s_add_u32 s28, s28, 0x80080
	v_lshl_add_u64 v[224:225], v[226:227], 0, s[36:37]
	s_addc_u32 s29, s29, 0
	s_add_i32 s40, s61, s45
	global_load_lds_dwordx4 v[224:225], off
	v_lshl_add_u64 v[224:225], s[28:29], 0, v[4:5]
	s_mov_b32 m0, s40
	s_nop 0
	global_load_lds_dwordx4 v[224:225], off
	v_lshl_add_u64 v[224:225], s[28:29], 0, v[2:3]
	s_add_i32 m0, s40, 0x2000
	s_nop 0
	global_load_lds_dwordx4 v[224:225], off
	v_lshl_add_u64 v[224:225], v[228:229], 0, s[36:37]
	s_mov_b32 m0, s50
	s_nop 0
	global_load_lds_dwordx4 v[224:225], off
	v_lshl_add_u64 v[224:225], v[230:231], 0, s[36:37]
	s_mov_b32 m0, s51
	s_nop 0
	global_load_lds_dwordx4 v[224:225], off
	s_bitcmp1_b32 s101, 8
	s_cbranch_scc0 .Lmy_wv_4473
	s_waitcnt vmcnt(8)
.Lmy_wv_4473:
	s_waitcnt lgkmcnt(0)
	s_barrier
	s_waitcnt lgkmcnt(0)
	v_mfma_f32_16x16x32_bf16 v[66:69], v[142:145], v[178:181], v[66:69]
	v_mfma_f32_16x16x32_bf16 v[58:61], v[150:153], v[178:181], v[58:61]
	v_mfma_f32_16x16x32_bf16 v[50:53], v[142:145], v[186:189], v[50:53]
	v_mfma_f32_16x16x32_bf16 v[42:45], v[150:153], v[186:189], v[42:45]
	v_mfma_f32_16x16x32_bf16 v[34:37], v[142:145], v[194:197], v[34:37]
	v_mfma_f32_16x16x32_bf16 v[26:29], v[150:153], v[194:197], v[26:29]
	v_mfma_f32_16x16x32_bf16 v[18:21], v[142:145], v[216:219], v[18:21]
	v_mfma_f32_16x16x32_bf16 v[10:13], v[150:153], v[216:219], v[10:13]
	v_mfma_f32_16x16x32_bf16 v[66:69], v[146:149], v[182:185], v[66:69]
	v_mfma_f32_16x16x32_bf16 v[58:61], v[154:157], v[182:185], v[58:61]
	v_mfma_f32_16x16x32_bf16 v[50:53], v[146:149], v[190:193], v[50:53]
	v_mfma_f32_16x16x32_bf16 v[42:45], v[154:157], v[190:193], v[42:45]
	v_mfma_f32_16x16x32_bf16 v[34:37], v[146:149], v[212:215], v[34:37]
	v_mfma_f32_16x16x32_bf16 v[26:29], v[154:157], v[212:215], v[26:29]
	v_mfma_f32_16x16x32_bf16 v[18:21], v[146:149], v[220:223], v[18:21]
	v_mfma_f32_16x16x32_bf16 v[10:13], v[154:157], v[220:223], v[10:13]
	v_mfma_f32_16x16x32_bf16 v[62:65], v[162:165], v[178:181], v[62:65]
	v_mfma_f32_16x16x32_bf16 v[54:57], v[170:173], v[178:181], v[54:57]
	v_mfma_f32_16x16x32_bf16 v[46:49], v[162:165], v[186:189], v[46:49]
	v_mfma_f32_16x16x32_bf16 v[38:41], v[170:173], v[186:189], v[38:41]
	v_mfma_f32_16x16x32_bf16 v[30:33], v[162:165], v[194:197], v[30:33]
	v_mfma_f32_16x16x32_bf16 v[22:25], v[170:173], v[194:197], v[22:25]
	v_mfma_f32_16x16x32_bf16 v[14:17], v[162:165], v[216:219], v[14:17]
	v_mfma_f32_16x16x32_bf16 v[6:9], v[170:173], v[216:219], v[6:9]
	v_mfma_f32_16x16x32_bf16 v[62:65], v[166:169], v[182:185], v[62:65]
	v_mfma_f32_16x16x32_bf16 v[54:57], v[174:177], v[182:185], v[54:57]
	v_mfma_f32_16x16x32_bf16 v[46:49], v[166:169], v[190:193], v[46:49]
	v_mfma_f32_16x16x32_bf16 v[38:41], v[174:177], v[190:193], v[38:41]
	v_mfma_f32_16x16x32_bf16 v[30:33], v[166:169], v[212:215], v[30:33]
	v_mfma_f32_16x16x32_bf16 v[22:25], v[174:177], v[212:215], v[22:25]
	v_mfma_f32_16x16x32_bf16 v[14:17], v[166:169], v[220:223], v[14:17]
	v_mfma_f32_16x16x32_bf16 v[6:9], v[174:177], v[220:223], v[6:9]
	s_waitcnt vmcnt(8)
	s_barrier
	s_add_i32 s59, s59, 2
	s_add_u32 s26, s26, 0x100
	s_addc_u32 s27, s27, 0
	s_add_u32 s57, s57, 0x100
	s_addc_u32 s58, s58, 0
	s_cmp_gt_u32 s59, 29
	s_cbranch_scc0 .LBB0_137
	s_and_b64 vcc, exec, s[16:17]
	s_cbranch_vccz .LBB0_140
	s_barrier

; #define PG8_STAGE(bufoff, gbase, voff) do { _Pragma("unroll") for (int _i = 0; _i < 2; ++_i) \
;         __builtin_amdgcn_global_load_lds((const unsigned*)((const char*)(gbase) + (voff)[_i]), (LAS unsigned*)(lds + (bufoff) + ldsw + _i * 8192), 16, 0, 0); } while (0)
; #define PG8_WAIT_V(n) asm volatile("s_waitcnt vmcnt(" #n ")" ::: "memory")
; #define PG8_BAR __builtin_amdgcn_s_barrier()
; template <class Epi, class Sched>
; __device__ __forceinline__ void gemm_phase(LAS unsigned char* lds, const Gemm g, const Sched& S, const Epi& E) {
;     ...
;     f32x4 acc[2][2][4][2];
; #pragma unroll
;     for (int a = 0; a < 2; ++a)
; #pragma unroll
;         for (int b = 0; b < 2; ++b)
; #pragma unroll
;             for (int m = 0; m < 4; ++m)
; #pragma unroll
;                 for (int n = 0; n < 2; ++n) acc[a][b][m][n] = (f32x4){0.f, 0.f, 0.f, 0.f};
;     bf16x8 At[4][2], B0[2][2], B1[2][2];
;     const char* cA = (const char*)g.A + (size_t)cur.pm * tstepA + (size_t)cur.ka * 2; const char* cB = (const char*)g.Bt + (size_t)cur.pn * tstepB;
;     S.a_ready(cur);
;     PG8_STAGE(PG8_SB(0, 0), cB, voffB); PG8_STAGE(PG8_SB(0, 1), cB + hstepB, voffB); PG8_STAGE(PG8_SA(0, 0), cA, voffA); PG8_STAGE(PG8_SA(0, 1), cA + hstepA, voffA);
;     if (wr == 1) PG8_BAR;
;     PG8_WAIT_V(2); PG8_BAR;
;     PG8_STAGE(PG8_SB(1, 0), cB + kstep, voffB); PG8_STAGE(PG8_SA(1, 0), cA + kstep, voffA); PG8_STAGE(PG8_SB(1, 1), cB + hstepB + kstep, voffB);
;     PG8_WAIT_V(6); PG8_BAR;
.LBB0_267:
	v_lshl_add_u64 v[14:15], s[24:25], 0, v[4:5]
	v_mov_b32_e32 v3, v5
	v_and_b32_e32 v142, 15, v143
	v_and_b32_e32 v22, 48, v143
	v_lshlrev_b32_e32 v23, 2, v143
	v_lshl_add_u64 v[16:17], s[24:25], 0, v[2:3]
	s_and_b32 s48, s44, 3
	v_lshl_or_b32 v22, v142, 6, v22
	s_lshl_b32 s4, s47, 13
	v_and_b32_e32 v23, 32, v23
	s_add_i32 m0, s50, 0x18000
	v_lshl_add_u64 v[14:15], v[14:15], 0, s[36:37]
	v_lshl_add_u64 v[18:19], s[20:21], 0, v[4:5]
	v_bitop3_b32 v24, v22, s4, v23 bitop3:0xde
	s_lshl_b32 s4, s48, 12
	s_waitcnt vmcnt(2)
	s_barrier
	global_load_lds_dwordx4 v[14:15], off
	v_lshl_add_u64 v[14:15], v[16:17], 0, s[36:37]
	s_add_i32 m0, s50, 0x1a000
	s_add_i32 s54, s50, 0x8000
	s_add_i32 s55, s50, 0xa000
	v_lshl_add_u64 v[20:21], s[20:21], 0, v[2:3]
	v_bitop3_b32 v144, v22, s4, v23 bitop3:0xde
	global_load_lds_dwordx4 v[14:15], off
	v_lshl_add_u64 v[14:15], v[18:19], 0, s[36:37]
	s_mov_b32 m0, s54
	s_add_u32 s4, s24, 0x158080
	global_load_lds_dwordx4 v[14:15], off
	v_lshl_add_u64 v[14:15], v[20:21], 0, s[36:37]
	s_mov_b32 m0, s55
	s_addc_u32 s5, s25, 0
	global_load_lds_dwordx4 v[14:15], off
	s_add_i32 m0, s50, 0x1c000
	v_lshl_add_u64 v[14:15], s[4:5], 0, v[4:5]
	global_load_lds_dwordx4 v[14:15], off
	v_lshl_add_u64 v[14:15], s[4:5], 0, v[2:3]
	s_add_i32 m0, s50, 0x1e000
	s_movk_i32 s10, 0x1580
	global_load_lds_dwordx4 v[14:15], off
	v_lshrrev_b32_e32 v11, 1, v11
	v_mul_lo_u32 v10, v10, s10
	s_mov_b32 s22, 0x15800
	v_mad_u64_u32 v[10:11], s[4:5], v11, s22, v[10:11]
	v_or_b32_e32 v10, v10, v12
	v_add_lshl_u32 v134, v10, v13, 1
	v_lshrrev_b32_e32 v10, 1, v6
	v_mul_lo_u32 v6, v7, s10
	v_mad_u64_u32 v[6:7], s[4:5], v10, s22, v[6:7]
	s_waitcnt vmcnt(6)
	v_or_b32_e32 v6, v6, v8
	s_cmpk_lt_u32 s45, 0x100
	v_add_lshl_u32 v136, v6, v9, 1
	v_mov_b32_e32 v6, 0
	v_readlane_b32 s4, v254, 13
	s_cselect_b64 s[18:19], -1, 0
	v_mov_b32_e32 v135, v5
	v_mov_b32_e32 v137, v5
	s_mov_b32 s59, 0
	v_add_u32_e32 v145, 0, v24
	s_mov_b32 s10, s4
	v_readlane_b32 s46, v253, 61
	v_mov_b32_e32 v7, v6
	v_mov_b32_e32 v8, v6
	v_mov_b32_e32 v9, v6
	v_mov_b32_e32 v10, v6
	v_mov_b32_e32 v11, v6
	v_mov_b32_e32 v12, v6
	v_mov_b32_e32 v13, v6
	v_mov_b32_e32 v14, v6
	v_mov_b32_e32 v15, v6
	v_mov_b32_e32 v16, v6
	v_mov_b32_e32 v17, v6
	v_mov_b32_e32 v18, v6
	v_mov_b32_e32 v19, v6
	v_mov_b32_e32 v20, v6
	v_mov_b32_e32 v21, v6
	v_mov_b32_e32 v22, v6
	v_mov_b32_e32 v23, v6
	v_mov_b32_e32 v24, v6
	v_mov_b32_e32 v25, v6
	v_mov_b32_e32 v30, v6
	v_mov_b32_e32 v31, v6
	v_mov_b32_e32 v32, v6
	v_mov_b32_e32 v33, v6
	v_mov_b32_e32 v38, v6
	v_mov_b32_e32 v39, v6
	v_mov_b32_e32 v40, v6
	v_mov_b32_e32 v41, v6
	v_mov_b32_e32 v46, v6
	v_mov_b32_e32 v47, v6
	v_mov_b32_e32 v48, v6
	v_mov_b32_e32 v49, v6
	v_mov_b32_e32 v26, v6
	v_mov_b32_e32 v27, v6
	v_mov_b32_e32 v28, v6
	v_mov_b32_e32 v29, v6
	v_mov_b32_e32 v34, v6
	v_mov_b32_e32 v35, v6
	v_mov_b32_e32 v36, v6
	v_mov_b32_e32 v37, v6
	v_mov_b32_e32 v42, v6
	v_mov_b32_e32 v43, v6
	v_mov_b32_e32 v44, v6
	v_mov_b32_e32 v45, v6
	v_mov_b32_e32 v50, v6
	v_mov_b32_e32 v51, v6
	v_mov_b32_e32 v52, v6
	v_mov_b32_e32 v53, v6
	v_mov_b32_e32 v54, v6
	v_mov_b32_e32 v55, v6
	v_mov_b32_e32 v56, v6
	v_mov_b32_e32 v57, v6
	v_mov_b32_e32 v58, v6
	v_mov_b32_e32 v59, v6
	v_mov_b32_e32 v60, v6
	v_mov_b32_e32 v61, v6
	v_mov_b32_e32 v62, v6
	v_mov_b32_e32 v63, v6
	v_mov_b32_e32 v64, v6
	v_mov_b32_e32 v65, v6
	v_mov_b32_e32 v66, v6
	v_mov_b32_e32 v67, v6
	v_mov_b32_e32 v68, v6
	v_mov_b32_e32 v69, v6
	v_mov_b32_e32 v70, v6
	v_mov_b32_e32 v71, v6
	v_mov_b32_e32 v72, v6
	v_mov_b32_e32 v73, v6
	v_mov_b32_e32 v74, v6
	v_mov_b32_e32 v75, v6
	v_mov_b32_e32 v76, v6
	v_mov_b32_e32 v77, v6
	v_mov_b32_e32 v78, v6
	v_mov_b32_e32 v79, v6
	v_mov_b32_e32 v80, v6
	v_mov_b32_e32 v81, v6
	v_mov_b32_e32 v82, v6
	v_mov_b32_e32 v83, v6
	v_mov_b32_e32 v84, v6
	v_mov_b32_e32 v85, v6
	v_mov_b32_e32 v86, v6
	v_mov_b32_e32 v87, v6
	v_mov_b32_e32 v88, v6
	v_mov_b32_e32 v89, v6
	v_mov_b32_e32 v94, v6
	v_mov_b32_e32 v95, v6
	v_mov_b32_e32 v96, v6
	v_mov_b32_e32 v97, v6
	v_mov_b32_e32 v102, v6
	v_mov_b32_e32 v103, v6
	v_mov_b32_e32 v104, v6
	v_mov_b32_e32 v105, v6
	v_mov_b32_e32 v114, v6
	v_mov_b32_e32 v115, v6
	v_mov_b32_e32 v116, v6
	v_mov_b32_e32 v117, v6
	v_mov_b32_e32 v90, v6
	v_mov_b32_e32 v91, v6
	v_mov_b32_e32 v92, v6
	v_mov_b32_e32 v93, v6
	v_mov_b32_e32 v98, v6
	v_mov_b32_e32 v99, v6
	v_mov_b32_e32 v100, v6
	v_mov_b32_e32 v101, v6
	v_mov_b32_e32 v106, v6
	v_mov_b32_e32 v107, v6
	v_mov_b32_e32 v108, v6
	v_mov_b32_e32 v109, v6
	v_mov_b32_e32 v110, v6
	v_mov_b32_e32 v111, v6
	v_mov_b32_e32 v112, v6
	v_mov_b32_e32 v113, v6
	v_mov_b32_e32 v118, v6
	v_mov_b32_e32 v119, v6
	v_mov_b32_e32 v120, v6
	v_mov_b32_e32 v121, v6
	v_mov_b32_e32 v122, v6
	v_mov_b32_e32 v123, v6
	v_mov_b32_e32 v124, v6
	v_mov_b32_e32 v125, v6
	v_mov_b32_e32 v126, v6
	v_mov_b32_e32 v127, v6
	v_mov_b32_e32 v128, v6
	v_mov_b32_e32 v129, v6
	v_mov_b32_e32 v130, v6
	v_mov_b32_e32 v131, v6
	v_mov_b32_e32 v132, v6
	v_mov_b32_e32 v133, v6
	s_barrier
	s_branch .LBB0_270
	s_nop 0
	s_nop 0
	s_nop 0
	s_nop 0
	s_nop 0
	s_nop 0
	s_nop 0
	s_nop 0
	s_nop 0
	s_nop 0
	s_nop 0
	s_nop 0
	s_nop 0
	s_nop 0
	s_nop 0
	s_nop 0
	s_nop 0
	s_nop 0
	s_nop 0
	s_nop 0
	s_nop 0
	s_nop 0
	s_nop 0
	s_nop 0
	s_nop 0
.LBB0_268:
	s_mov_b64 s[22:23], s[24:25]
	s_mov_b64 s[4:5], s[20:21]
	s_mov_b32 s58, s59
	s_andn2_b64 vcc, exec, s[38:39]
	s_cbranch_vccz .LBB0_288

; #define PG8_STAGE(bufoff, gbase, voff) do { _Pragma("unroll") for (int _i = 0; _i < 2; ++_i) \
;         __builtin_amdgcn_global_load_lds((const unsigned*)((const char*)(gbase) + (voff)[_i]), (LAS unsigned*)(lds + (bufoff) + ldsw + _i * 8192), 16, 0, 0); } while (0)
; #define PG8_LDA(dst, b, h) do { _Pragma("unroll") for (int m = 0; m < 4; ++m) _Pragma("unroll") for (int k = 0; k < 2; ++k) dst[m][k] = *(const LAS bf16x8*)(lds + PG8_SA(b, h) + aoff + m * 2048 + k * 1024); } while (0)
; #define PG8_LDB(dst, b, h) do { _Pragma("unroll") for (int n = 0; n < 2; ++n) _Pragma("unroll") for (int k = 0; k < 2; ++k) dst[n][k] = *(const LAS bf16x8*)(lds + PG8_SB(b, h) + boff + n * 2048 + k * 1024); } while (0)
; #define PG8_MMA(ai, bj, At, Bt) do { __builtin_amdgcn_s_setprio(1); _Pragma("unroll") for (int m = 0; m < 4; ++m) _Pragma("unroll") for (int n = 0; n < 2; ++n) _Pragma("unroll") for (int k = 0; k < 2; ++k) \
;         acc[ai][bj][m][n] = __builtin_amdgcn_mfma_f32_16x16x32_bf16(Bt[n][k], At[m][k], acc[ai][bj][m][n], 0, 0, 0); __builtin_amdgcn_s_setprio(0); } while (0)
; #define PG8_WAIT_V(n) asm volatile("s_waitcnt vmcnt(" #n ")" ::: "memory")
; #define PG8_WAIT_L(n) asm volatile("s_waitcnt lgkmcnt(" #n ")" ::: "memory")
; #define PG8_BAR __builtin_amdgcn_s_barrier()
; #define PG8_SCHED __builtin_amdgcn_sched_barrier(0)
; template <class Epi, class Sched>
; __device__ __forceinline__ void gemm_phase(LAS unsigned char* lds, const Gemm g, const Sched& S, const Epi& E) {
;     ...
;         for (int t = 0; t < nt; t += 2) {
;             const bool last = (t == nt - 2);
;             const char* a1 = cA + (size_t)(t + 1) * kstep;
;             const char* a2 = last ? nA : cA + (size_t)(t + 2) * kstep; const char* b2 = last ? nB : cB + (size_t)(t + 2) * kstep;
;             const char* a3 = a2 + kstep; const char* b3 = b2 + kstep;
;             if (last && has_next) S.a_ready(nxt);
;             PG8_LDB(B0, 0, 0); PG8_LDB(B1, 0, 1); PG8_SCHED; PG8_LDA(At, 0, 0); PG8_STAGE(PG8_SA(1, 1), a1 + hstepA, voffA);
;             PG8_WAIT_V(8); PG8_WAIT_L(0); PG8_BAR; PG8_MMA(0, 0, At, B0); PG8_MMA(0, 1, At, B1); PG8_BAR; PG8_SCHED;
.LBB0_280:
	s_add_u32 s60, s24, 0x100
	s_addc_u32 s61, s25, 0
	s_add_u32 s24, s20, 0x158080
	s_addc_u32 s25, s21, 0
	v_lshl_add_u64 v[138:139], s[24:25], 0, v[134:135]
	v_lshl_add_u64 v[140:141], s[24:25], 0, v[136:137]
	s_mov_b32 s62, -2
	s_mov_b64 s[24:25], 0
	v_readfirstlane_b32 s101, v0
.LBB0_281:
	s_add_u32 s26, s20, s24
	s_addc_u32 s27, s21, s25
	s_add_u32 s26, s26, 0x100
	s_addc_u32 s27, s27, 0
	s_add_u32 s63, s60, s24
	s_addc_u32 s65, s61, s25
	s_add_i32 s67, 0, 0x10000
	s_cmpk_eq_i32 s24, 0x2a00
	s_cselect_b32 s29, s5, s27
	s_cselect_b32 s28, s4, s26
	s_cselect_b32 s27, s23, s65
	s_cselect_b32 s26, s22, s63
	s_add_i32 s63, 0, 0x14000
	v_add_u32_e32 v158, s67, v144
	v_add_u32_e32 v174, s63, v144
	ds_read_b128 v[146:149], v158
	ds_read_b128 v[150:153], v158 offset:1024
	ds_read_b128 v[154:157], v158 offset:2048
	ds_read_b128 v[158:161], v158 offset:3072
	ds_read_b128 v[162:165], v174
	ds_read_b128 v[166:169], v174 offset:1024
	ds_read_b128 v[170:173], v174 offset:2048
	ds_read_b128 v[174:177], v174 offset:3072
	v_lshl_add_u64 v[224:225], v[138:139], 0, s[24:25]
	s_add_i32 m0, s50, 0xc000
	ds_read_b128 v[178:181], v145
	ds_read_b128 v[182:185], v145 offset:1024
	ds_read_b128 v[186:189], v145 offset:2048
	ds_read_b128 v[190:193], v145 offset:3072
	ds_read_b128 v[194:197], v145 offset:4096
	ds_read_b128 v[212:215], v145 offset:5120
	ds_read_b128 v[216:219], v145 offset:6144
	ds_read_b128 v[220:223], v145 offset:7168
	global_load_lds_dwordx4 v[224:225], off
	v_lshl_add_u64 v[224:225], v[140:141], 0, s[24:25]
	s_add_i32 m0, s50, 0xe000
	s_nop 0
	global_load_lds_dwordx4 v[224:225], off
	s_bitcmp1_b32 s101, 8
	s_cbranch_scc0 .Lmy_wv_7169
	s_waitcnt vmcnt(8)
.Lmy_wv_7169:
	s_waitcnt lgkmcnt(0)
	s_barrier
	s_waitcnt lgkmcnt(0)
	v_mfma_f32_16x16x32_bf16 v[130:133], v[146:149], v[178:181], v[130:133]
	v_mfma_f32_16x16x32_bf16 v[126:129], v[154:157], v[178:181], v[126:129]
	v_mfma_f32_16x16x32_bf16 v[122:125], v[146:149], v[186:189], v[122:125]
	v_mfma_f32_16x16x32_bf16 v[118:121], v[154:157], v[186:189], v[118:121]
	v_mfma_f32_16x16x32_bf16 v[110:113], v[146:149], v[194:197], v[110:113]
	v_mfma_f32_16x16x32_bf16 v[106:109], v[154:157], v[194:197], v[106:109]
	v_mfma_f32_16x16x32_bf16 v[98:101], v[146:149], v[216:219], v[98:101]
	v_mfma_f32_16x16x32_bf16 v[90:93], v[154:157], v[216:219], v[90:93]
	v_mfma_f32_16x16x32_bf16 v[130:133], v[150:153], v[182:185], v[130:133]
	v_mfma_f32_16x16x32_bf16 v[126:129], v[158:161], v[182:185], v[126:129]
	v_mfma_f32_16x16x32_bf16 v[122:125], v[150:153], v[190:193], v[122:125]
	v_mfma_f32_16x16x32_bf16 v[118:121], v[158:161], v[190:193], v[118:121]
	v_mfma_f32_16x16x32_bf16 v[110:113], v[150:153], v[212:215], v[110:113]
	v_mfma_f32_16x16x32_bf16 v[106:109], v[158:161], v[212:215], v[106:109]
	v_mfma_f32_16x16x32_bf16 v[98:101], v[150:153], v[220:223], v[98:101]
	v_mfma_f32_16x16x32_bf16 v[90:93], v[158:161], v[220:223], v[90:93]
	v_mfma_f32_16x16x32_bf16 v[114:117], v[162:165], v[178:181], v[114:117]
	v_mfma_f32_16x16x32_bf16 v[102:105], v[170:173], v[178:181], v[102:105]
	v_mfma_f32_16x16x32_bf16 v[94:97], v[162:165], v[186:189], v[94:97]
	v_mfma_f32_16x16x32_bf16 v[86:89], v[170:173], v[186:189], v[86:89]
	v_mfma_f32_16x16x32_bf16 v[82:85], v[162:165], v[194:197], v[82:85]
	v_mfma_f32_16x16x32_bf16 v[78:81], v[170:173], v[194:197], v[78:81]
	v_mfma_f32_16x16x32_bf16 v[74:77], v[162:165], v[216:219], v[74:77]
	v_mfma_f32_16x16x32_bf16 v[70:73], v[170:173], v[216:219], v[70:73]
	v_mfma_f32_16x16x32_bf16 v[114:117], v[166:169], v[182:185], v[114:117]
	v_mfma_f32_16x16x32_bf16 v[102:105], v[174:177], v[182:185], v[102:105]
	v_mfma_f32_16x16x32_bf16 v[94:97], v[166:169], v[190:193], v[94:97]
	v_mfma_f32_16x16x32_bf16 v[86:89], v[174:177], v[190:193], v[86:89]
	v_mfma_f32_16x16x32_bf16 v[82:85], v[166:169], v[212:215], v[82:85]
	v_mfma_f32_16x16x32_bf16 v[78:81], v[174:177], v[212:215], v[78:81]
	v_mfma_f32_16x16x32_bf16 v[74:77], v[166:169], v[220:223], v[74:77]
	v_mfma_f32_16x16x32_bf16 v[70:73], v[174:177], v[220:223], v[70:73]
	s_waitcnt vmcnt(8)
	s_barrier
	s_add_i32 s65, s67, s11
	v_lshl_add_u64 v[224:225], s[26:27], 0, v[4:5]
	s_mov_b32 m0, s65
	ds_read_b128 v[178:181], v145 offset:16384
	ds_read_b128 v[182:185], v145 offset:17408
	ds_read_b128 v[186:189], v145 offset:18432
	ds_read_b128 v[190:193], v145 offset:19456
	ds_read_b128 v[194:197], v145 offset:20480
	ds_read_b128 v[212:215], v145 offset:21504
	ds_read_b128 v[216:219], v145 offset:22528
	ds_read_b128 v[220:223], v145 offset:23552
	global_load_lds_dwordx4 v[224:225], off
	s_add_i32 m0, s65, 0x2000
	s_add_u32 s68, s26, 0x158000
	v_lshl_add_u64 v[226:227], s[26:27], 0, v[2:3]
	s_addc_u32 s69, s27, 0
	s_add_i32 s63, s63, s11
	global_load_lds_dwordx4 v[226:227], off
	v_lshl_add_u64 v[228:229], s[68:69], 0, v[4:5]
	s_mov_b32 m0, s63
	v_lshl_add_u64 v[230:231], s[28:29], 0, v[2:3]
	global_load_lds_dwordx4 v[228:229], off
	v_lshl_add_u64 v[228:229], s[68:69], 0, v[2:3]
	s_add_i32 m0, s63, 0x2000
	s_nop 0
	global_load_lds_dwordx4 v[228:229], off
	v_lshl_add_u64 v[228:229], s[28:29], 0, v[4:5]
	s_mov_b32 m0, s50
	s_nop 0
	global_load_lds_dwordx4 v[228:229], off
	s_mov_b32 m0, s51
	s_nop 0
	global_load_lds_dwordx4 v[230:231], off
	s_bitcmp1_b32 s101, 8
	s_cbranch_scc0 .Lmy_wv_7248
	s_waitcnt vmcnt(8)
; #define PG8_STAGE(bufoff, gbase, voff) do { _Pragma("unroll") for (int _i = 0; _i < 2; ++_i) \
;         __builtin_amdgcn_global_load_lds((const unsigned*)((const char*)(gbase) + (voff)[_i]), (LAS unsigned*)(lds + (bufoff) + ldsw + _i * 8192), 16, 0, 0); } while (0)
; #define PG8_LDA(dst, b, h) do { _Pragma("unroll") for (int m = 0; m < 4; ++m) _Pragma("unroll") for (int k = 0; k < 2; ++k) dst[m][k] = *(const LAS bf16x8*)(lds + PG8_SA(b, h) + aoff + m * 2048 + k * 1024); } while (0)
; #define PG8_LDB(dst, b, h) do { _Pragma("unroll") for (int n = 0; n < 2; ++n) _Pragma("unroll") for (int k = 0; k < 2; ++k) dst[n][k] = *(const LAS bf16x8*)(lds + PG8_SB(b, h) + boff + n * 2048 + k * 1024); } while (0)
; #define PG8_MMA(ai, bj, At, Bt) do { __builtin_amdgcn_s_setprio(1); _Pragma("unroll") for (int m = 0; m < 4; ++m) _Pragma("unroll") for (int n = 0; n < 2; ++n) _Pragma("unroll") for (int k = 0; k < 2; ++k) \
;         acc[ai][bj][m][n] = __builtin_amdgcn_mfma_f32_16x16x32_bf16(Bt[n][k], At[m][k], acc[ai][bj][m][n], 0, 0, 0); __builtin_amdgcn_s_setprio(0); } while (0)
; #define PG8_WAIT_V(n) asm volatile("s_waitcnt vmcnt(" #n ")" ::: "memory")
; #define PG8_WAIT_L(n) asm volatile("s_waitcnt lgkmcnt(" #n ")" ::: "memory")
; #define PG8_BAR __builtin_amdgcn_s_barrier()
; #define PG8_SCHED __builtin_amdgcn_sched_barrier(0)
; template <class Epi, class Sched>
; __device__ __forceinline__ void gemm_phase(LAS unsigned char* lds, const Gemm g, const Sched& S, const Epi& E) {
;     ...
;             PG8_WAIT_V(8); PG8_WAIT_L(0); PG8_BAR; PG8_MMA(0, 0, At, B0); PG8_MMA(0, 1, At, B1); PG8_BAR; PG8_SCHED;
;             PG8_LDA(At, 0, 1); PG8_STAGE(PG8_SB(0, 0), b2, voffB); PG8_STAGE(PG8_SB(0, 1), b2 + hstepB, voffB); PG8_STAGE(PG8_SA(0, 0), a2, voffA);
;             PG8_WAIT_V(8); PG8_WAIT_L(0); PG8_BAR; PG8_MMA(1, 0, At, B0); PG8_MMA(1, 1, At, B1); PG8_BAR; PG8_SCHED;
;             PG8_LDB(B0, 1, 0); PG8_LDB(B1, 1, 1); PG8_SCHED; PG8_LDA(At, 1, 0); PG8_STAGE(PG8_SA(0, 1), a2 + hstepA, voffA);
.Lmy_wv_7248:
	s_waitcnt lgkmcnt(0)
	s_barrier
	s_waitcnt lgkmcnt(0)
	v_mfma_f32_16x16x32_bf16 v[66:69], v[146:149], v[178:181], v[66:69]
	v_mfma_f32_16x16x32_bf16 v[62:65], v[154:157], v[178:181], v[62:65]
	v_mfma_f32_16x16x32_bf16 v[58:61], v[146:149], v[186:189], v[58:61]
	v_mfma_f32_16x16x32_bf16 v[54:57], v[154:157], v[186:189], v[54:57]
	v_mfma_f32_16x16x32_bf16 v[50:53], v[146:149], v[194:197], v[50:53]
	v_mfma_f32_16x16x32_bf16 v[42:45], v[154:157], v[194:197], v[42:45]
	v_mfma_f32_16x16x32_bf16 v[34:37], v[146:149], v[216:219], v[34:37]
	v_mfma_f32_16x16x32_bf16 v[26:29], v[154:157], v[216:219], v[26:29]
	v_mfma_f32_16x16x32_bf16 v[66:69], v[150:153], v[182:185], v[66:69]
	v_mfma_f32_16x16x32_bf16 v[62:65], v[158:161], v[182:185], v[62:65]
	v_mfma_f32_16x16x32_bf16 v[58:61], v[150:153], v[190:193], v[58:61]
	v_mfma_f32_16x16x32_bf16 v[54:57], v[158:161], v[190:193], v[54:57]
	v_mfma_f32_16x16x32_bf16 v[50:53], v[150:153], v[212:215], v[50:53]
	v_mfma_f32_16x16x32_bf16 v[42:45], v[158:161], v[212:215], v[42:45]
	v_mfma_f32_16x16x32_bf16 v[34:37], v[150:153], v[220:223], v[34:37]
	v_mfma_f32_16x16x32_bf16 v[26:29], v[158:161], v[220:223], v[26:29]
	v_mfma_f32_16x16x32_bf16 v[46:49], v[162:165], v[178:181], v[46:49]
	v_mfma_f32_16x16x32_bf16 v[38:41], v[170:173], v[178:181], v[38:41]
	v_mfma_f32_16x16x32_bf16 v[30:33], v[162:165], v[186:189], v[30:33]
	v_mfma_f32_16x16x32_bf16 v[22:25], v[170:173], v[186:189], v[22:25]
	v_mfma_f32_16x16x32_bf16 v[18:21], v[162:165], v[194:197], v[18:21]
	v_mfma_f32_16x16x32_bf16 v[14:17], v[170:173], v[194:197], v[14:17]
	v_mfma_f32_16x16x32_bf16 v[10:13], v[162:165], v[216:219], v[10:13]
	v_mfma_f32_16x16x32_bf16 v[6:9], v[170:173], v[216:219], v[6:9]
	v_mfma_f32_16x16x32_bf16 v[46:49], v[166:169], v[182:185], v[46:49]
	v_mfma_f32_16x16x32_bf16 v[38:41], v[174:177], v[182:185], v[38:41]
	v_mfma_f32_16x16x32_bf16 v[30:33], v[166:169], v[190:193], v[30:33]
	v_mfma_f32_16x16x32_bf16 v[22:25], v[174:177], v[190:193], v[22:25]
	v_mfma_f32_16x16x32_bf16 v[18:21], v[166:169], v[212:215], v[18:21]
	v_mfma_f32_16x16x32_bf16 v[14:17], v[174:177], v[212:215], v[14:17]
	v_mfma_f32_16x16x32_bf16 v[10:13], v[166:169], v[220:223], v[10:13]
	v_mfma_f32_16x16x32_bf16 v[6:9], v[174:177], v[220:223], v[6:9]
	s_waitcnt vmcnt(8)
	s_barrier
	s_add_i32 s63, 0, 0x18000
	s_add_i32 s65, 0, 0x1c000
	v_add_u32_e32 v158, s63, v144
	v_add_u32_e32 v174, s65, v144
	ds_read_b128 v[146:149], v158
	ds_read_b128 v[150:153], v158 offset:1024
	ds_read_b128 v[154:157], v158 offset:2048
	ds_read_b128 v[158:161], v158 offset:3072
	ds_read_b128 v[162:165], v174
	ds_read_b128 v[166:169], v174 offset:1024
	ds_read_b128 v[170:173], v174 offset:2048
	ds_read_b128 v[174:177], v174 offset:3072
	s_add_u32 s28, s28, 0x158000
	s_addc_u32 s29, s29, 0
	s_mov_b32 m0, s52
	v_lshl_add_u64 v[236:237], s[28:29], 0, v[4:5]
	ds_read_b128 v[178:181], v145 offset:32768
	ds_read_b128 v[182:185], v145 offset:33792
	ds_read_b128 v[186:189], v145 offset:34816
	ds_read_b128 v[190:193], v145 offset:35840
	ds_read_b128 v[194:197], v145 offset:36864
	ds_read_b128 v[212:215], v145 offset:37888
	ds_read_b128 v[216:219], v145 offset:38912
	ds_read_b128 v[220:223], v145 offset:39936
	global_load_lds_dwordx4 v[236:237], off
	v_lshl_add_u64 v[236:237], s[28:29], 0, v[2:3]
	s_mov_b32 m0, s53
	s_nop 0
	global_load_lds_dwordx4 v[236:237], off
	s_bitcmp1_b32 s101, 8
	s_cbranch_scc0 .Lmy_wv_7324
	s_waitcnt vmcnt(8)
; #define PG8_STAGE(bufoff, gbase, voff) do { _Pragma("unroll") for (int _i = 0; _i < 2; ++_i) \
;         __builtin_amdgcn_global_load_lds((const unsigned*)((const char*)(gbase) + (voff)[_i]), (LAS unsigned*)(lds + (bufoff) + ldsw + _i * 8192), 16, 0, 0); } while (0)
; #define PG8_LDA(dst, b, h) do { _Pragma("unroll") for (int m = 0; m < 4; ++m) _Pragma("unroll") for (int k = 0; k < 2; ++k) dst[m][k] = *(const LAS bf16x8*)(lds + PG8_SA(b, h) + aoff + m * 2048 + k * 1024); } while (0)
; #define PG8_LDB(dst, b, h) do { _Pragma("unroll") for (int n = 0; n < 2; ++n) _Pragma("unroll") for (int k = 0; k < 2; ++k) dst[n][k] = *(const LAS bf16x8*)(lds + PG8_SB(b, h) + boff + n * 2048 + k * 1024); } while (0)
; #define PG8_MMA(ai, bj, At, Bt) do { __builtin_amdgcn_s_setprio(1); _Pragma("unroll") for (int m = 0; m < 4; ++m) _Pragma("unroll") for (int n = 0; n < 2; ++n) _Pragma("unroll") for (int k = 0; k < 2; ++k) \
;         acc[ai][bj][m][n] = __builtin_amdgcn_mfma_f32_16x16x32_bf16(Bt[n][k], At[m][k], acc[ai][bj][m][n], 0, 0, 0); __builtin_amdgcn_s_setprio(0); } while (0)
; #define PG8_WAIT_V(n) asm volatile("s_waitcnt vmcnt(" #n ")" ::: "memory")
; #define PG8_WAIT_L(n) asm volatile("s_waitcnt lgkmcnt(" #n ")" ::: "memory")
; #define PG8_BAR __builtin_amdgcn_s_barrier()
; #define PG8_SCHED __builtin_amdgcn_sched_barrier(0)
; template <class Epi, class Sched>
; __device__ __forceinline__ void gemm_phase(LAS unsigned char* lds, const Gemm g, const Sched& S, const Epi& E) {
;     ...
;             PG8_LDB(B0, 1, 0); PG8_LDB(B1, 1, 1); PG8_SCHED; PG8_LDA(At, 1, 0); PG8_STAGE(PG8_SA(0, 1), a2 + hstepA, voffA);
;             PG8_WAIT_V(8); PG8_WAIT_L(0); PG8_BAR; PG8_MMA(0, 0, At, B0); PG8_MMA(0, 1, At, B1); PG8_BAR; PG8_SCHED;
;             PG8_LDA(At, 1, 1); PG8_STAGE(PG8_SB(1, 0), b3, voffB); PG8_STAGE(PG8_SB(1, 1), b3 + hstepB, voffB); PG8_STAGE(PG8_SA(1, 0), a3, voffA);
;             PG8_WAIT_V(8); PG8_WAIT_L(0); PG8_BAR; PG8_MMA(1, 0, At, B0); PG8_MMA(1, 1, At, B1); PG8_BAR; PG8_SCHED;
;         }
.Lmy_wv_7324:
	s_waitcnt lgkmcnt(0)
	s_barrier
	s_waitcnt lgkmcnt(0)
	v_mfma_f32_16x16x32_bf16 v[130:133], v[146:149], v[178:181], v[130:133]
	v_mfma_f32_16x16x32_bf16 v[126:129], v[154:157], v[178:181], v[126:129]
	v_mfma_f32_16x16x32_bf16 v[122:125], v[146:149], v[186:189], v[122:125]
	v_mfma_f32_16x16x32_bf16 v[118:121], v[154:157], v[186:189], v[118:121]
	v_mfma_f32_16x16x32_bf16 v[110:113], v[146:149], v[194:197], v[110:113]
	v_mfma_f32_16x16x32_bf16 v[106:109], v[154:157], v[194:197], v[106:109]
	v_mfma_f32_16x16x32_bf16 v[98:101], v[146:149], v[216:219], v[98:101]
	v_mfma_f32_16x16x32_bf16 v[90:93], v[154:157], v[216:219], v[90:93]
	v_mfma_f32_16x16x32_bf16 v[130:133], v[150:153], v[182:185], v[130:133]
	v_mfma_f32_16x16x32_bf16 v[126:129], v[158:161], v[182:185], v[126:129]
	v_mfma_f32_16x16x32_bf16 v[122:125], v[150:153], v[190:193], v[122:125]
	v_mfma_f32_16x16x32_bf16 v[118:121], v[158:161], v[190:193], v[118:121]
	v_mfma_f32_16x16x32_bf16 v[110:113], v[150:153], v[212:215], v[110:113]
	v_mfma_f32_16x16x32_bf16 v[106:109], v[158:161], v[212:215], v[106:109]
	v_mfma_f32_16x16x32_bf16 v[98:101], v[150:153], v[220:223], v[98:101]
	v_mfma_f32_16x16x32_bf16 v[90:93], v[158:161], v[220:223], v[90:93]
	v_mfma_f32_16x16x32_bf16 v[114:117], v[162:165], v[178:181], v[114:117]
	v_mfma_f32_16x16x32_bf16 v[102:105], v[170:173], v[178:181], v[102:105]
	v_mfma_f32_16x16x32_bf16 v[94:97], v[162:165], v[186:189], v[94:97]
	v_mfma_f32_16x16x32_bf16 v[86:89], v[170:173], v[186:189], v[86:89]
	v_mfma_f32_16x16x32_bf16 v[82:85], v[162:165], v[194:197], v[82:85]
	v_mfma_f32_16x16x32_bf16 v[78:81], v[170:173], v[194:197], v[78:81]
	v_mfma_f32_16x16x32_bf16 v[74:77], v[162:165], v[216:219], v[74:77]
	v_mfma_f32_16x16x32_bf16 v[70:73], v[170:173], v[216:219], v[70:73]
	v_mfma_f32_16x16x32_bf16 v[114:117], v[166:169], v[182:185], v[114:117]
	v_mfma_f32_16x16x32_bf16 v[102:105], v[174:177], v[182:185], v[102:105]
	v_mfma_f32_16x16x32_bf16 v[94:97], v[166:169], v[190:193], v[94:97]
	v_mfma_f32_16x16x32_bf16 v[86:89], v[174:177], v[190:193], v[86:89]
	v_mfma_f32_16x16x32_bf16 v[82:85], v[166:169], v[212:215], v[82:85]
	v_mfma_f32_16x16x32_bf16 v[78:81], v[174:177], v[212:215], v[78:81]
	v_mfma_f32_16x16x32_bf16 v[74:77], v[166:169], v[220:223], v[74:77]
	v_mfma_f32_16x16x32_bf16 v[70:73], v[174:177], v[220:223], v[70:73]
	s_waitcnt vmcnt(8)
	s_barrier
	s_add_i32 s28, s63, s11
	v_lshl_add_u64 v[224:225], v[224:225], 0, s[36:37]
	s_mov_b32 m0, s28
	ds_read_b128 v[178:181], v145 offset:49152
	ds_read_b128 v[182:185], v145 offset:50176
	ds_read_b128 v[186:189], v145 offset:51200
	ds_read_b128 v[190:193], v145 offset:52224
	ds_read_b128 v[194:197], v145 offset:53248
	ds_read_b128 v[212:215], v145 offset:54272
	ds_read_b128 v[216:219], v145 offset:55296
	ds_read_b128 v[220:223], v145 offset:56320
	global_load_lds_dwordx4 v[224:225], off
	s_add_i32 m0, s28, 0x2000
	s_add_u32 s26, s26, 0x158080
	v_lshl_add_u64 v[224:225], v[226:227], 0, s[36:37]
	s_addc_u32 s27, s27, 0
	s_add_i32 s28, s65, s11
	global_load_lds_dwordx4 v[224:225], off
	v_lshl_add_u64 v[224:225], s[26:27], 0, v[4:5]
	s_mov_b32 m0, s28
	s_nop 0
	global_load_lds_dwordx4 v[224:225], off
	v_lshl_add_u64 v[224:225], s[26:27], 0, v[2:3]
	s_add_i32 m0, s28, 0x2000
	s_nop 0
	global_load_lds_dwordx4 v[224:225], off
	v_lshl_add_u64 v[224:225], v[228:229], 0, s[36:37]
	s_mov_b32 m0, s54
	s_nop 0
	global_load_lds_dwordx4 v[224:225], off
	v_lshl_add_u64 v[224:225], v[230:231], 0, s[36:37]
	s_mov_b32 m0, s55
	s_nop 0
	global_load_lds_dwordx4 v[224:225], off
	s_bitcmp1_b32 s101, 8
	s_cbranch_scc0 .Lmy_wv_7404
	s_waitcnt vmcnt(8)
.Lmy_wv_7404:
	s_waitcnt lgkmcnt(0)
	s_barrier
	s_waitcnt lgkmcnt(0)
	v_mfma_f32_16x16x32_bf16 v[66:69], v[146:149], v[178:181], v[66:69]
	v_mfma_f32_16x16x32_bf16 v[62:65], v[154:157], v[178:181], v[62:65]
	v_mfma_f32_16x16x32_bf16 v[58:61], v[146:149], v[186:189], v[58:61]
	v_mfma_f32_16x16x32_bf16 v[54:57], v[154:157], v[186:189], v[54:57]
	v_mfma_f32_16x16x32_bf16 v[50:53], v[146:149], v[194:197], v[50:53]
	v_mfma_f32_16x16x32_bf16 v[42:45], v[154:157], v[194:197], v[42:45]
	v_mfma_f32_16x16x32_bf16 v[34:37], v[146:149], v[216:219], v[34:37]
	v_mfma_f32_16x16x32_bf16 v[26:29], v[154:157], v[216:219], v[26:29]
	v_mfma_f32_16x16x32_bf16 v[66:69], v[150:153], v[182:185], v[66:69]
	v_mfma_f32_16x16x32_bf16 v[62:65], v[158:161], v[182:185], v[62:65]
	v_mfma_f32_16x16x32_bf16 v[58:61], v[150:153], v[190:193], v[58:61]
	v_mfma_f32_16x16x32_bf16 v[54:57], v[158:161], v[190:193], v[54:57]
	v_mfma_f32_16x16x32_bf16 v[50:53], v[150:153], v[212:215], v[50:53]
	v_mfma_f32_16x16x32_bf16 v[42:45], v[158:161], v[212:215], v[42:45]
	v_mfma_f32_16x16x32_bf16 v[34:37], v[150:153], v[220:223], v[34:37]
	v_mfma_f32_16x16x32_bf16 v[26:29], v[158:161], v[220:223], v[26:29]
	v_mfma_f32_16x16x32_bf16 v[46:49], v[162:165], v[178:181], v[46:49]
	v_mfma_f32_16x16x32_bf16 v[38:41], v[170:173], v[178:181], v[38:41]
	v_mfma_f32_16x16x32_bf16 v[30:33], v[162:165], v[186:189], v[30:33]
	v_mfma_f32_16x16x32_bf16 v[22:25], v[170:173], v[186:189], v[22:25]
	v_mfma_f32_16x16x32_bf16 v[18:21], v[162:165], v[194:197], v[18:21]
	v_mfma_f32_16x16x32_bf16 v[14:17], v[170:173], v[194:197], v[14:17]
	v_mfma_f32_16x16x32_bf16 v[10:13], v[162:165], v[216:219], v[10:13]
	v_mfma_f32_16x16x32_bf16 v[6:9], v[170:173], v[216:219], v[6:9]
	v_mfma_f32_16x16x32_bf16 v[46:49], v[166:169], v[182:185], v[46:49]
	v_mfma_f32_16x16x32_bf16 v[38:41], v[174:177], v[182:185], v[38:41]
	v_mfma_f32_16x16x32_bf16 v[30:33], v[166:169], v[190:193], v[30:33]
	v_mfma_f32_16x16x32_bf16 v[22:25], v[174:177], v[190:193], v[22:25]
	v_mfma_f32_16x16x32_bf16 v[18:21], v[166:169], v[212:215], v[18:21]
	v_mfma_f32_16x16x32_bf16 v[14:17], v[174:177], v[212:215], v[14:17]
	v_mfma_f32_16x16x32_bf16 v[10:13], v[166:169], v[220:223], v[10:13]
	v_mfma_f32_16x16x32_bf16 v[6:9], v[174:177], v[220:223], v[6:9]
	s_waitcnt vmcnt(8)
	s_barrier
	s_add_i32 s62, s62, 2
	s_add_u32 s24, s24, 0x100
	s_addc_u32 s25, s25, 0
	s_cmpk_gt_u32 s62, 0x53
	s_cbranch_scc0 .LBB0_281
	s_and_b64 vcc, exec, s[18:19]
	s_cbranch_vccz .LBB0_284
	s_barrier

; #define PG8_STAGE(bufoff, gbase, voff) do { _Pragma("unroll") for (int _i = 0; _i < 2; ++_i) \
;         __builtin_amdgcn_global_load_lds((const unsigned*)((const char*)(gbase) + (voff)[_i]), (LAS unsigned*)(lds + (bufoff) + ldsw + _i * 8192), 16, 0, 0); } while (0)
; #define PG8_LDA(dst, b, h) do { _Pragma("unroll") for (int m = 0; m < 4; ++m) _Pragma("unroll") for (int k = 0; k < 2; ++k) dst[m][k] = *(const LAS bf16x8*)(lds + PG8_SA(b, h) + aoff + m * 2048 + k * 1024); } while (0)
; #define PG8_LDB(dst, b, h) do { _Pragma("unroll") for (int n = 0; n < 2; ++n) _Pragma("unroll") for (int k = 0; k < 2; ++k) dst[n][k] = *(const LAS bf16x8*)(lds + PG8_SB(b, h) + boff + n * 2048 + k * 1024); } while (0)
; #define PG8_WAIT_V(n) asm volatile("s_waitcnt vmcnt(" #n ")" ::: "memory")
; #define PG8_WAIT_L(n) asm volatile("s_waitcnt lgkmcnt(" #n ")" ::: "memory")
; #define PG8_BAR __builtin_amdgcn_s_barrier()
; #define PG8_SCHED __builtin_amdgcn_sched_barrier(0)
; template <class Epi, class Sched>
; __device__ __forceinline__ void gemm_phase(LAS unsigned char* lds, const Gemm g, const Sched& S, const Epi& E) {
;     ...
;         const bool has_next = S.next(ui + 1, nxt);
;         const char* nA = has_next ? (const char*)g.A + (size_t)nxt.pm * tstepA + (size_t)nxt.ka * 2 : cA; const char* nB = has_next ? (const char*)g.Bt + (size_t)nxt.pn * tstepB : cB;
;         for (int t = 0; t < nt; t += 2) {
;             const bool last = (t == nt - 2);
;             const char* a1 = cA + (size_t)(t + 1) * kstep;
;             const char* a2 = last ? nA : cA + (size_t)(t + 2) * kstep; const char* b2 = last ? nB : cB + (size_t)(t + 2) * kstep;
;             const char* a3 = a2 + kstep; const char* b3 = b2 + kstep;
;             if (last && has_next) S.a_ready(nxt);
;             PG8_LDB(B0, 0, 0); PG8_LDB(B1, 0, 1); PG8_SCHED; PG8_LDA(At, 0, 0); PG8_STAGE(PG8_SA(1, 1), a1 + hstepA, voffA);
;             PG8_WAIT_V(8); PG8_WAIT_L(0); PG8_BAR; PG8_MMA(0, 0, At, B0); PG8_MMA(0, 1, At, B1); PG8_BAR; PG8_SCHED;
;     ...
; #pragma unroll
;         for (int a = 0; a < 2; ++a)
; #pragma unroll
;             for (int b = 0; b < 2; ++b)
; #pragma unroll
;                 for (int m = 0; m < 4; ++m)
; #pragma unroll
;                     for (int n = 0; n < 2; ++n) acc[a][b][m][n] = (f32x4){0.f, 0.f, 0.f, 0.f};
.LBB0_512:
	s_ashr_i32 s21, s20, 31
	s_lshl_b64 s[22:23], s[20:21], 20
	s_add_u32 s22, s47, s22
	s_addc_u32 s23, s48, s23
	s_and_b64 s[24:25], s[40:41], exec
	s_cselect_b32 s21, s23, s39
	s_cselect_b32 s27, s22, s38
	s_ashr_i32 s19, s18, 31
	s_lshl_b64 s[24:25], s[18:19], 20
	s_add_u32 s24, s34, s24
	s_addc_u32 s25, s46, s25
	s_and_b64 s[44:45], s[40:41], exec
	s_cselect_b32 s19, s25, s43
	s_cselect_b32 s29, s24, s42
	s_add_u32 s38, s38, 0x80080
	s_addc_u32 s39, s39, 0
	s_add_u32 s58, s42, 0x100
	v_mov_b32_e32 v6, 0
	s_addc_u32 s59, s43, 0
	s_mov_b32 s60, -2
	v_mov_b32_e32 v7, v6
	v_mov_b32_e32 v8, v6
	v_mov_b32_e32 v9, v6
	v_mov_b32_e32 v10, v6
	v_mov_b32_e32 v11, v6
	v_mov_b32_e32 v12, v6
	v_mov_b32_e32 v13, v6
	v_mov_b32_e32 v22, v6
	v_mov_b32_e32 v23, v6
	v_mov_b32_e32 v24, v6
	v_mov_b32_e32 v25, v6
	v_mov_b32_e32 v26, v6
	v_mov_b32_e32 v27, v6
	v_mov_b32_e32 v28, v6
	v_mov_b32_e32 v29, v6
	v_mov_b32_e32 v38, v6
	v_mov_b32_e32 v39, v6
	v_mov_b32_e32 v40, v6
	v_mov_b32_e32 v41, v6
	v_mov_b32_e32 v42, v6
	v_mov_b32_e32 v43, v6
	v_mov_b32_e32 v44, v6
	v_mov_b32_e32 v45, v6
	v_mov_b32_e32 v54, v6
	v_mov_b32_e32 v55, v6
	v_mov_b32_e32 v56, v6
	v_mov_b32_e32 v57, v6
	v_mov_b32_e32 v58, v6
	v_mov_b32_e32 v59, v6
	v_mov_b32_e32 v60, v6
	v_mov_b32_e32 v61, v6
	v_mov_b32_e32 v14, v6
	v_mov_b32_e32 v15, v6
	v_mov_b32_e32 v16, v6
	v_mov_b32_e32 v17, v6
	v_mov_b32_e32 v18, v6
	v_mov_b32_e32 v19, v6
	v_mov_b32_e32 v20, v6
	v_mov_b32_e32 v21, v6
	v_mov_b32_e32 v30, v6
	v_mov_b32_e32 v31, v6
	v_mov_b32_e32 v32, v6
	v_mov_b32_e32 v33, v6
	v_mov_b32_e32 v34, v6
	v_mov_b32_e32 v35, v6
	v_mov_b32_e32 v36, v6
	v_mov_b32_e32 v37, v6
	v_mov_b32_e32 v46, v6
	v_mov_b32_e32 v47, v6
	v_mov_b32_e32 v48, v6
	v_mov_b32_e32 v49, v6
	v_mov_b32_e32 v50, v6
	v_mov_b32_e32 v51, v6
	v_mov_b32_e32 v52, v6
	v_mov_b32_e32 v53, v6
	v_mov_b32_e32 v62, v6
	v_mov_b32_e32 v63, v6
	v_mov_b32_e32 v64, v6
	v_mov_b32_e32 v65, v6
	v_mov_b32_e32 v66, v6
	v_mov_b32_e32 v67, v6
	v_mov_b32_e32 v68, v6
	v_mov_b32_e32 v69, v6
	v_mov_b32_e32 v70, v6
	v_mov_b32_e32 v71, v6
	v_mov_b32_e32 v72, v6
	v_mov_b32_e32 v73, v6
	v_mov_b32_e32 v74, v6
	v_mov_b32_e32 v75, v6
	v_mov_b32_e32 v76, v6
	v_mov_b32_e32 v77, v6
	v_mov_b32_e32 v102, v6
	v_mov_b32_e32 v103, v6
	v_mov_b32_e32 v104, v6
	v_mov_b32_e32 v105, v6
	v_mov_b32_e32 v106, v6
	v_mov_b32_e32 v107, v6
	v_mov_b32_e32 v108, v6
	v_mov_b32_e32 v109, v6
	v_mov_b32_e32 v118, v6
	v_mov_b32_e32 v119, v6
	v_mov_b32_e32 v120, v6
	v_mov_b32_e32 v121, v6
	v_mov_b32_e32 v122, v6
	v_mov_b32_e32 v123, v6
	v_mov_b32_e32 v124, v6
	v_mov_b32_e32 v125, v6
	v_mov_b32_e32 v134, v6
	v_mov_b32_e32 v135, v6
	v_mov_b32_e32 v136, v6
	v_mov_b32_e32 v137, v6
	v_mov_b32_e32 v138, v6
	v_mov_b32_e32 v139, v6
	v_mov_b32_e32 v140, v6
	v_mov_b32_e32 v141, v6
	v_mov_b32_e32 v78, v6
	v_mov_b32_e32 v79, v6
	v_mov_b32_e32 v80, v6
	v_mov_b32_e32 v81, v6
	v_mov_b32_e32 v82, v6
	v_mov_b32_e32 v83, v6
	v_mov_b32_e32 v84, v6
	v_mov_b32_e32 v85, v6
	v_mov_b32_e32 v110, v6
	v_mov_b32_e32 v111, v6
	v_mov_b32_e32 v112, v6
	v_mov_b32_e32 v113, v6
	v_mov_b32_e32 v114, v6
	v_mov_b32_e32 v115, v6
	v_mov_b32_e32 v116, v6
	v_mov_b32_e32 v117, v6
	v_mov_b32_e32 v126, v6
	v_mov_b32_e32 v127, v6
	v_mov_b32_e32 v128, v6
	v_mov_b32_e32 v129, v6
	v_mov_b32_e32 v130, v6
	v_mov_b32_e32 v131, v6
	v_mov_b32_e32 v132, v6
	v_mov_b32_e32 v133, v6
	v_mov_b32_e32 v142, v6
	v_mov_b32_e32 v143, v6
	v_mov_b32_e32 v144, v6
	v_mov_b32_e32 v145, v6
	v_mov_b32_e32 v146, v6
	v_mov_b32_e32 v147, v6
	v_mov_b32_e32 v148, v6
	v_mov_b32_e32 v149, v6
	v_readfirstlane_b32 s101, v0
.LBB0_513:
	s_add_u32 s42, s38, 0xfff80080
	s_addc_u32 s43, s39, -1
	s_add_i32 s61, 0, 0x10000
	s_cmp_eq_u32 s60, 28
	s_cselect_b32 s45, s21, s43
	s_cselect_b32 s44, s27, s42
	s_cselect_b32 s43, s19, s59
	s_cselect_b32 s42, s29, s58
	s_add_i32 s64, 0, 0x14000
	v_add_u32_e32 v98, s61, v236
	v_add_u32_e32 v162, s64, v236
	ds_read_b128 v[86:89], v98
	ds_read_b128 v[90:93], v98 offset:1024
	ds_read_b128 v[94:97], v98 offset:2048
	ds_read_b128 v[98:101], v98 offset:3072
	ds_read_b128 v[150:153], v162
	ds_read_b128 v[154:157], v162 offset:1024
	ds_read_b128 v[158:161], v162 offset:2048
	ds_read_b128 v[162:165], v162 offset:3072
	v_lshl_add_u64 v[228:229], s[38:39], 0, v[224:225]
	s_add_i32 m0, s50, 0xc000
	ds_read_b128 v[166:169], v237
	ds_read_b128 v[170:173], v237 offset:1024
	ds_read_b128 v[174:177], v237 offset:2048
	ds_read_b128 v[178:181], v237 offset:3072
	ds_read_b128 v[182:185], v237 offset:4096
	ds_read_b128 v[186:189], v237 offset:5120
	ds_read_b128 v[190:193], v237 offset:6144
	ds_read_b128 v[194:197], v237 offset:7168
	global_load_lds_dwordx4 v[228:229], off
	v_lshl_add_u64 v[228:229], s[38:39], 0, v[226:227]
	s_add_i32 m0, s50, 0xe000
	s_nop 0
	global_load_lds_dwordx4 v[228:229], off
	s_bitcmp1_b32 s101, 8
	s_cbranch_scc0 .Lmy_wv_10721
	s_waitcnt vmcnt(8)
; #define PG8_STAGE(bufoff, gbase, voff) do { _Pragma("unroll") for (int _i = 0; _i < 2; ++_i) \
;         __builtin_amdgcn_global_load_lds((const unsigned*)((const char*)(gbase) + (voff)[_i]), (LAS unsigned*)(lds + (bufoff) + ldsw + _i * 8192), 16, 0, 0); } while (0)
; #define PG8_LDA(dst, b, h) do { _Pragma("unroll") for (int m = 0; m < 4; ++m) _Pragma("unroll") for (int k = 0; k < 2; ++k) dst[m][k] = *(const LAS bf16x8*)(lds + PG8_SA(b, h) + aoff + m * 2048 + k * 1024); } while (0)
; #define PG8_LDB(dst, b, h) do { _Pragma("unroll") for (int n = 0; n < 2; ++n) _Pragma("unroll") for (int k = 0; k < 2; ++k) dst[n][k] = *(const LAS bf16x8*)(lds + PG8_SB(b, h) + boff + n * 2048 + k * 1024); } while (0)
; #define PG8_MMA(ai, bj, At, Bt) do { __builtin_amdgcn_s_setprio(1); _Pragma("unroll") for (int m = 0; m < 4; ++m) _Pragma("unroll") for (int n = 0; n < 2; ++n) _Pragma("unroll") for (int k = 0; k < 2; ++k) \
;         acc[ai][bj][m][n] = __builtin_amdgcn_mfma_f32_16x16x32_bf16(Bt[n][k], At[m][k], acc[ai][bj][m][n], 0, 0, 0); __builtin_amdgcn_s_setprio(0); } while (0)
; #define PG8_WAIT_V(n) asm volatile("s_waitcnt vmcnt(" #n ")" ::: "memory")
; #define PG8_WAIT_L(n) asm volatile("s_waitcnt lgkmcnt(" #n ")" ::: "memory")
; #define PG8_BAR __builtin_amdgcn_s_barrier()
; #define PG8_SCHED __builtin_amdgcn_sched_barrier(0)
; template <class Epi, class Sched>
; __device__ __forceinline__ void gemm_phase(LAS unsigned char* lds, const Gemm g, const Sched& S, const Epi& E) {
;     ...
;             PG8_WAIT_V(8); PG8_WAIT_L(0); PG8_BAR; PG8_MMA(0, 0, At, B0); PG8_MMA(0, 1, At, B1); PG8_BAR; PG8_SCHED;
;             PG8_LDA(At, 0, 1); PG8_STAGE(PG8_SB(0, 0), b2, voffB); PG8_STAGE(PG8_SB(0, 1), b2 + hstepB, voffB); PG8_STAGE(PG8_SA(0, 0), a2, voffA);
;             PG8_WAIT_V(8); PG8_WAIT_L(0); PG8_BAR; PG8_MMA(1, 0, At, B0); PG8_MMA(1, 1, At, B1); PG8_BAR; PG8_SCHED;
;             PG8_LDB(B0, 1, 0); PG8_LDB(B1, 1, 1); PG8_SCHED; PG8_LDA(At, 1, 0); PG8_STAGE(PG8_SA(0, 1), a2 + hstepA, voffA);
.Lmy_wv_10721:
	s_waitcnt lgkmcnt(0)
	s_barrier
	s_waitcnt lgkmcnt(0)
	v_mfma_f32_16x16x32_bf16 v[146:149], v[86:89], v[166:169], v[146:149]
	v_mfma_f32_16x16x32_bf16 v[142:145], v[94:97], v[166:169], v[142:145]
	v_mfma_f32_16x16x32_bf16 v[130:133], v[86:89], v[174:177], v[130:133]
	v_mfma_f32_16x16x32_bf16 v[126:129], v[94:97], v[174:177], v[126:129]
	v_mfma_f32_16x16x32_bf16 v[114:117], v[86:89], v[182:185], v[114:117]
	v_mfma_f32_16x16x32_bf16 v[110:113], v[94:97], v[182:185], v[110:113]
	v_mfma_f32_16x16x32_bf16 v[82:85], v[86:89], v[190:193], v[82:85]
	v_mfma_f32_16x16x32_bf16 v[78:81], v[94:97], v[190:193], v[78:81]
	v_mfma_f32_16x16x32_bf16 v[146:149], v[90:93], v[170:173], v[146:149]
	v_mfma_f32_16x16x32_bf16 v[142:145], v[98:101], v[170:173], v[142:145]
	v_mfma_f32_16x16x32_bf16 v[130:133], v[90:93], v[178:181], v[130:133]
	v_mfma_f32_16x16x32_bf16 v[126:129], v[98:101], v[178:181], v[126:129]
	v_mfma_f32_16x16x32_bf16 v[114:117], v[90:93], v[186:189], v[114:117]
	v_mfma_f32_16x16x32_bf16 v[110:113], v[98:101], v[186:189], v[110:113]
	v_mfma_f32_16x16x32_bf16 v[82:85], v[90:93], v[194:197], v[82:85]
	v_mfma_f32_16x16x32_bf16 v[78:81], v[98:101], v[194:197], v[78:81]
	v_mfma_f32_16x16x32_bf16 v[138:141], v[150:153], v[166:169], v[138:141]
	v_mfma_f32_16x16x32_bf16 v[134:137], v[158:161], v[166:169], v[134:137]
	v_mfma_f32_16x16x32_bf16 v[122:125], v[150:153], v[174:177], v[122:125]
	v_mfma_f32_16x16x32_bf16 v[118:121], v[158:161], v[174:177], v[118:121]
	v_mfma_f32_16x16x32_bf16 v[106:109], v[150:153], v[182:185], v[106:109]
	v_mfma_f32_16x16x32_bf16 v[102:105], v[158:161], v[182:185], v[102:105]
	v_mfma_f32_16x16x32_bf16 v[74:77], v[150:153], v[190:193], v[74:77]
	v_mfma_f32_16x16x32_bf16 v[70:73], v[158:161], v[190:193], v[70:73]
	v_mfma_f32_16x16x32_bf16 v[138:141], v[154:157], v[170:173], v[138:141]
	v_mfma_f32_16x16x32_bf16 v[134:137], v[162:165], v[170:173], v[134:137]
	v_mfma_f32_16x16x32_bf16 v[122:125], v[154:157], v[178:181], v[122:125]
	v_mfma_f32_16x16x32_bf16 v[118:121], v[162:165], v[178:181], v[118:121]
	v_mfma_f32_16x16x32_bf16 v[106:109], v[154:157], v[186:189], v[106:109]
	v_mfma_f32_16x16x32_bf16 v[102:105], v[162:165], v[186:189], v[102:105]
	v_mfma_f32_16x16x32_bf16 v[74:77], v[154:157], v[194:197], v[74:77]
	v_mfma_f32_16x16x32_bf16 v[70:73], v[162:165], v[194:197], v[70:73]
	s_waitcnt vmcnt(8)
	s_barrier
	s_add_i32 s61, s61, s49
	v_lshl_add_u64 v[228:229], s[42:43], 0, v[212:213]
	s_mov_b32 m0, s61
	ds_read_b128 v[166:169], v237 offset:16384
	ds_read_b128 v[170:173], v237 offset:17408
	ds_read_b128 v[174:177], v237 offset:18432
	ds_read_b128 v[178:181], v237 offset:19456
	ds_read_b128 v[182:185], v237 offset:20480
	ds_read_b128 v[186:189], v237 offset:21504
	ds_read_b128 v[190:193], v237 offset:22528
	ds_read_b128 v[194:197], v237 offset:23552
	global_load_lds_dwordx4 v[228:229], off
	s_add_i32 m0, s61, 0x2000
	s_add_u32 s62, s42, 0x80000
	v_lshl_add_u64 v[230:231], s[42:43], 0, v[216:217]
	s_addc_u32 s63, s43, 0
	s_add_i32 s61, s64, s49
	global_load_lds_dwordx4 v[230:231], off
	v_lshl_add_u64 v[238:239], s[62:63], 0, v[212:213]
	s_mov_b32 m0, s61
	v_lshl_add_u64 v[240:241], s[44:45], 0, v[214:215]
	global_load_lds_dwordx4 v[238:239], off
	v_lshl_add_u64 v[238:239], s[62:63], 0, v[216:217]
	s_add_i32 m0, s61, 0x2000
	s_nop 0
	global_load_lds_dwordx4 v[238:239], off
	v_lshl_add_u64 v[238:239], s[44:45], 0, v[2:3]
	s_mov_b32 m0, s50
	s_nop 0
	global_load_lds_dwordx4 v[238:239], off
	s_mov_b32 m0, s51
	s_nop 0
	global_load_lds_dwordx4 v[240:241], off
	s_bitcmp1_b32 s101, 8
	s_cbranch_scc0 .Lmy_wv_10800
	s_waitcnt vmcnt(8)
.Lmy_wv_10800:
	s_waitcnt lgkmcnt(0)
	s_barrier
	s_waitcnt lgkmcnt(0)
	v_mfma_f32_16x16x32_bf16 v[66:69], v[86:89], v[166:169], v[66:69]
	v_mfma_f32_16x16x32_bf16 v[62:65], v[94:97], v[166:169], v[62:65]
	v_mfma_f32_16x16x32_bf16 v[50:53], v[86:89], v[174:177], v[50:53]
	v_mfma_f32_16x16x32_bf16 v[46:49], v[94:97], v[174:177], v[46:49]
	v_mfma_f32_16x16x32_bf16 v[34:37], v[86:89], v[182:185], v[34:37]
	v_mfma_f32_16x16x32_bf16 v[30:33], v[94:97], v[182:185], v[30:33]
	v_mfma_f32_16x16x32_bf16 v[18:21], v[86:89], v[190:193], v[18:21]
	v_mfma_f32_16x16x32_bf16 v[14:17], v[94:97], v[190:193], v[14:17]
	v_mfma_f32_16x16x32_bf16 v[66:69], v[90:93], v[170:173], v[66:69]
	v_mfma_f32_16x16x32_bf16 v[62:65], v[98:101], v[170:173], v[62:65]
	v_mfma_f32_16x16x32_bf16 v[50:53], v[90:93], v[178:181], v[50:53]
	v_mfma_f32_16x16x32_bf16 v[46:49], v[98:101], v[178:181], v[46:49]
	v_mfma_f32_16x16x32_bf16 v[34:37], v[90:93], v[186:189], v[34:37]
	v_mfma_f32_16x16x32_bf16 v[30:33], v[98:101], v[186:189], v[30:33]
	v_mfma_f32_16x16x32_bf16 v[18:21], v[90:93], v[194:197], v[18:21]
	v_mfma_f32_16x16x32_bf16 v[14:17], v[98:101], v[194:197], v[14:17]
	v_mfma_f32_16x16x32_bf16 v[58:61], v[150:153], v[166:169], v[58:61]
	v_mfma_f32_16x16x32_bf16 v[54:57], v[158:161], v[166:169], v[54:57]
	v_mfma_f32_16x16x32_bf16 v[42:45], v[150:153], v[174:177], v[42:45]
	v_mfma_f32_16x16x32_bf16 v[38:41], v[158:161], v[174:177], v[38:41]
	v_mfma_f32_16x16x32_bf16 v[26:29], v[150:153], v[182:185], v[26:29]
	v_mfma_f32_16x16x32_bf16 v[22:25], v[158:161], v[182:185], v[22:25]
	v_mfma_f32_16x16x32_bf16 v[10:13], v[150:153], v[190:193], v[10:13]
	v_mfma_f32_16x16x32_bf16 v[6:9], v[158:161], v[190:193], v[6:9]
	v_mfma_f32_16x16x32_bf16 v[58:61], v[154:157], v[170:173], v[58:61]
	v_mfma_f32_16x16x32_bf16 v[54:57], v[162:165], v[170:173], v[54:57]
	v_mfma_f32_16x16x32_bf16 v[42:45], v[154:157], v[178:181], v[42:45]
	v_mfma_f32_16x16x32_bf16 v[38:41], v[162:165], v[178:181], v[38:41]
	v_mfma_f32_16x16x32_bf16 v[26:29], v[154:157], v[186:189], v[26:29]
	v_mfma_f32_16x16x32_bf16 v[22:25], v[162:165], v[186:189], v[22:25]
	v_mfma_f32_16x16x32_bf16 v[10:13], v[154:157], v[194:197], v[10:13]
	v_mfma_f32_16x16x32_bf16 v[6:9], v[162:165], v[194:197], v[6:9]
	s_waitcnt vmcnt(8)
	s_barrier
	s_add_i32 s61, 0, 0x18000
	s_add_i32 s62, 0, 0x1c000
	v_add_u32_e32 v98, s61, v236
	v_add_u32_e32 v162, s62, v236
	ds_read_b128 v[86:89], v98
	ds_read_b128 v[90:93], v98 offset:1024
	ds_read_b128 v[94:97], v98 offset:2048
	ds_read_b128 v[98:101], v98 offset:3072
	ds_read_b128 v[150:153], v162
	ds_read_b128 v[154:157], v162 offset:1024
	ds_read_b128 v[158:161], v162 offset:2048
	ds_read_b128 v[162:165], v162 offset:3072
	s_add_u32 s44, s44, 0x80000
	s_addc_u32 s45, s45, 0
	s_mov_b32 m0, s52
	v_lshl_add_u64 v[242:243], s[44:45], 0, v[2:3]
	ds_read_b128 v[166:169], v237 offset:32768
	ds_read_b128 v[170:173], v237 offset:33792
	ds_read_b128 v[174:177], v237 offset:34816
	ds_read_b128 v[178:181], v237 offset:35840
	ds_read_b128 v[182:185], v237 offset:36864
	ds_read_b128 v[186:189], v237 offset:37888
	ds_read_b128 v[190:193], v237 offset:38912
	ds_read_b128 v[194:197], v237 offset:39936
	global_load_lds_dwordx4 v[242:243], off
	v_lshl_add_u64 v[242:243], s[44:45], 0, v[214:215]
	s_mov_b32 m0, s53
	s_nop 0
	global_load_lds_dwordx4 v[242:243], off
	s_bitcmp1_b32 s101, 8
	s_cbranch_scc0 .Lmy_wv_10876
	s_waitcnt vmcnt(8)
; #define PG8_STAGE(bufoff, gbase, voff) do { _Pragma("unroll") for (int _i = 0; _i < 2; ++_i) \
;         __builtin_amdgcn_global_load_lds((const unsigned*)((const char*)(gbase) + (voff)[_i]), (LAS unsigned*)(lds + (bufoff) + ldsw + _i * 8192), 16, 0, 0); } while (0)
; #define PG8_LDA(dst, b, h) do { _Pragma("unroll") for (int m = 0; m < 4; ++m) _Pragma("unroll") for (int k = 0; k < 2; ++k) dst[m][k] = *(const LAS bf16x8*)(lds + PG8_SA(b, h) + aoff + m * 2048 + k * 1024); } while (0)
; #define PG8_LDB(dst, b, h) do { _Pragma("unroll") for (int n = 0; n < 2; ++n) _Pragma("unroll") for (int k = 0; k < 2; ++k) dst[n][k] = *(const LAS bf16x8*)(lds + PG8_SB(b, h) + boff + n * 2048 + k * 1024); } while (0)
; #define PG8_MMA(ai, bj, At, Bt) do { __builtin_amdgcn_s_setprio(1); _Pragma("unroll") for (int m = 0; m < 4; ++m) _Pragma("unroll") for (int n = 0; n < 2; ++n) _Pragma("unroll") for (int k = 0; k < 2; ++k) \
;         acc[ai][bj][m][n] = __builtin_amdgcn_mfma_f32_16x16x32_bf16(Bt[n][k], At[m][k], acc[ai][bj][m][n], 0, 0, 0); __builtin_amdgcn_s_setprio(0); } while (0)
; #define PG8_WAIT_V(n) asm volatile("s_waitcnt vmcnt(" #n ")" ::: "memory")
; #define PG8_WAIT_L(n) asm volatile("s_waitcnt lgkmcnt(" #n ")" ::: "memory")
; #define PG8_BAR __builtin_amdgcn_s_barrier()
; #define PG8_SCHED __builtin_amdgcn_sched_barrier(0)
; template <class Epi, class Sched>
; __device__ __forceinline__ void gemm_phase(LAS unsigned char* lds, const Gemm g, const Sched& S, const Epi& E) {
;     ...
;             PG8_LDB(B0, 1, 0); PG8_LDB(B1, 1, 1); PG8_SCHED; PG8_LDA(At, 1, 0); PG8_STAGE(PG8_SA(0, 1), a2 + hstepA, voffA);
;             PG8_WAIT_V(8); PG8_WAIT_L(0); PG8_BAR; PG8_MMA(0, 0, At, B0); PG8_MMA(0, 1, At, B1); PG8_BAR; PG8_SCHED;
;             PG8_LDA(At, 1, 1); PG8_STAGE(PG8_SB(1, 0), b3, voffB); PG8_STAGE(PG8_SB(1, 1), b3 + hstepB, voffB); PG8_STAGE(PG8_SA(1, 0), a3, voffA);
;             PG8_WAIT_V(8); PG8_WAIT_L(0); PG8_BAR; PG8_MMA(1, 0, At, B0); PG8_MMA(1, 1, At, B1); PG8_BAR; PG8_SCHED;
;         }
.Lmy_wv_10876:
	s_waitcnt lgkmcnt(0)
	s_barrier
	s_waitcnt lgkmcnt(0)
	v_mfma_f32_16x16x32_bf16 v[146:149], v[86:89], v[166:169], v[146:149]
	v_mfma_f32_16x16x32_bf16 v[142:145], v[94:97], v[166:169], v[142:145]
	v_mfma_f32_16x16x32_bf16 v[130:133], v[86:89], v[174:177], v[130:133]
	v_mfma_f32_16x16x32_bf16 v[126:129], v[94:97], v[174:177], v[126:129]
	v_mfma_f32_16x16x32_bf16 v[114:117], v[86:89], v[182:185], v[114:117]
	v_mfma_f32_16x16x32_bf16 v[110:113], v[94:97], v[182:185], v[110:113]
	v_mfma_f32_16x16x32_bf16 v[82:85], v[86:89], v[190:193], v[82:85]
	v_mfma_f32_16x16x32_bf16 v[78:81], v[94:97], v[190:193], v[78:81]
	v_mfma_f32_16x16x32_bf16 v[146:149], v[90:93], v[170:173], v[146:149]
	v_mfma_f32_16x16x32_bf16 v[142:145], v[98:101], v[170:173], v[142:145]
	v_mfma_f32_16x16x32_bf16 v[130:133], v[90:93], v[178:181], v[130:133]
	v_mfma_f32_16x16x32_bf16 v[126:129], v[98:101], v[178:181], v[126:129]
	v_mfma_f32_16x16x32_bf16 v[114:117], v[90:93], v[186:189], v[114:117]
	v_mfma_f32_16x16x32_bf16 v[110:113], v[98:101], v[186:189], v[110:113]
	v_mfma_f32_16x16x32_bf16 v[82:85], v[90:93], v[194:197], v[82:85]
	v_mfma_f32_16x16x32_bf16 v[78:81], v[98:101], v[194:197], v[78:81]
	v_mfma_f32_16x16x32_bf16 v[138:141], v[150:153], v[166:169], v[138:141]
	v_mfma_f32_16x16x32_bf16 v[134:137], v[158:161], v[166:169], v[134:137]
	v_mfma_f32_16x16x32_bf16 v[122:125], v[150:153], v[174:177], v[122:125]
	v_mfma_f32_16x16x32_bf16 v[118:121], v[158:161], v[174:177], v[118:121]
	v_mfma_f32_16x16x32_bf16 v[106:109], v[150:153], v[182:185], v[106:109]
	v_mfma_f32_16x16x32_bf16 v[102:105], v[158:161], v[182:185], v[102:105]
	v_mfma_f32_16x16x32_bf16 v[74:77], v[150:153], v[190:193], v[74:77]
	v_mfma_f32_16x16x32_bf16 v[70:73], v[158:161], v[190:193], v[70:73]
	v_mfma_f32_16x16x32_bf16 v[138:141], v[154:157], v[170:173], v[138:141]
	v_mfma_f32_16x16x32_bf16 v[134:137], v[162:165], v[170:173], v[134:137]
	v_mfma_f32_16x16x32_bf16 v[122:125], v[154:157], v[178:181], v[122:125]
	v_mfma_f32_16x16x32_bf16 v[118:121], v[162:165], v[178:181], v[118:121]
	v_mfma_f32_16x16x32_bf16 v[106:109], v[154:157], v[186:189], v[106:109]
	v_mfma_f32_16x16x32_bf16 v[102:105], v[162:165], v[186:189], v[102:105]
	v_mfma_f32_16x16x32_bf16 v[74:77], v[154:157], v[194:197], v[74:77]
	v_mfma_f32_16x16x32_bf16 v[70:73], v[162:165], v[194:197], v[70:73]
	s_waitcnt vmcnt(8)
	s_barrier
	s_add_i32 s44, s61, s49
	v_lshl_add_u64 v[228:229], v[228:229], 0, s[36:37]
	s_mov_b32 m0, s44
	ds_read_b128 v[166:169], v237 offset:49152
	ds_read_b128 v[170:173], v237 offset:50176
	ds_read_b128 v[174:177], v237 offset:51200
	ds_read_b128 v[178:181], v237 offset:52224
	ds_read_b128 v[182:185], v237 offset:53248
	ds_read_b128 v[186:189], v237 offset:54272
	ds_read_b128 v[190:193], v237 offset:55296
	ds_read_b128 v[194:197], v237 offset:56320
	global_load_lds_dwordx4 v[228:229], off
	s_add_i32 m0, s44, 0x2000
	s_add_u32 s42, s42, 0x80080
	v_lshl_add_u64 v[228:229], v[230:231], 0, s[36:37]
	s_addc_u32 s43, s43, 0
	s_add_i32 s44, s62, s49
	global_load_lds_dwordx4 v[228:229], off
	v_lshl_add_u64 v[228:229], s[42:43], 0, v[212:213]
	s_mov_b32 m0, s44
	s_nop 0
	global_load_lds_dwordx4 v[228:229], off
	v_lshl_add_u64 v[228:229], s[42:43], 0, v[216:217]
	s_add_i32 m0, s44, 0x2000
	s_nop 0
	global_load_lds_dwordx4 v[228:229], off
	v_lshl_add_u64 v[228:229], v[238:239], 0, s[36:37]
	s_mov_b32 m0, s54
	s_nop 0
	global_load_lds_dwordx4 v[228:229], off
	v_lshl_add_u64 v[228:229], v[240:241], 0, s[36:37]
	s_mov_b32 m0, s55
	s_nop 0
	global_load_lds_dwordx4 v[228:229], off
	s_bitcmp1_b32 s101, 8
	s_cbranch_scc0 .Lmy_wv_10956
	s_waitcnt vmcnt(8)
.Lmy_wv_10956:
	s_waitcnt lgkmcnt(0)
	s_barrier
	s_waitcnt lgkmcnt(0)
	v_mfma_f32_16x16x32_bf16 v[66:69], v[86:89], v[166:169], v[66:69]
	v_mfma_f32_16x16x32_bf16 v[62:65], v[94:97], v[166:169], v[62:65]
	v_mfma_f32_16x16x32_bf16 v[50:53], v[86:89], v[174:177], v[50:53]
	v_mfma_f32_16x16x32_bf16 v[46:49], v[94:97], v[174:177], v[46:49]
	v_mfma_f32_16x16x32_bf16 v[34:37], v[86:89], v[182:185], v[34:37]
	v_mfma_f32_16x16x32_bf16 v[30:33], v[94:97], v[182:185], v[30:33]
	v_mfma_f32_16x16x32_bf16 v[18:21], v[86:89], v[190:193], v[18:21]
	v_mfma_f32_16x16x32_bf16 v[14:17], v[94:97], v[190:193], v[14:17]
	v_mfma_f32_16x16x32_bf16 v[66:69], v[90:93], v[170:173], v[66:69]
	v_mfma_f32_16x16x32_bf16 v[62:65], v[98:101], v[170:173], v[62:65]
	v_mfma_f32_16x16x32_bf16 v[50:53], v[90:93], v[178:181], v[50:53]
	v_mfma_f32_16x16x32_bf16 v[46:49], v[98:101], v[178:181], v[46:49]
	v_mfma_f32_16x16x32_bf16 v[34:37], v[90:93], v[186:189], v[34:37]
	v_mfma_f32_16x16x32_bf16 v[30:33], v[98:101], v[186:189], v[30:33]
	v_mfma_f32_16x16x32_bf16 v[18:21], v[90:93], v[194:197], v[18:21]
	v_mfma_f32_16x16x32_bf16 v[14:17], v[98:101], v[194:197], v[14:17]
	v_mfma_f32_16x16x32_bf16 v[58:61], v[150:153], v[166:169], v[58:61]
	v_mfma_f32_16x16x32_bf16 v[54:57], v[158:161], v[166:169], v[54:57]
	v_mfma_f32_16x16x32_bf16 v[42:45], v[150:153], v[174:177], v[42:45]
	v_mfma_f32_16x16x32_bf16 v[38:41], v[158:161], v[174:177], v[38:41]
	v_mfma_f32_16x16x32_bf16 v[26:29], v[150:153], v[182:185], v[26:29]
	v_mfma_f32_16x16x32_bf16 v[22:25], v[158:161], v[182:185], v[22:25]
	v_mfma_f32_16x16x32_bf16 v[10:13], v[150:153], v[190:193], v[10:13]
	v_mfma_f32_16x16x32_bf16 v[6:9], v[158:161], v[190:193], v[6:9]
	v_mfma_f32_16x16x32_bf16 v[58:61], v[154:157], v[170:173], v[58:61]
	v_mfma_f32_16x16x32_bf16 v[54:57], v[162:165], v[170:173], v[54:57]
	v_mfma_f32_16x16x32_bf16 v[42:45], v[154:157], v[178:181], v[42:45]
	v_mfma_f32_16x16x32_bf16 v[38:41], v[162:165], v[178:181], v[38:41]
	v_mfma_f32_16x16x32_bf16 v[26:29], v[154:157], v[186:189], v[26:29]
	v_mfma_f32_16x16x32_bf16 v[22:25], v[162:165], v[186:189], v[22:25]
	v_mfma_f32_16x16x32_bf16 v[10:13], v[154:157], v[194:197], v[10:13]
	v_mfma_f32_16x16x32_bf16 v[6:9], v[162:165], v[194:197], v[6:9]
	s_waitcnt vmcnt(8)
	s_barrier
	s_add_i32 s60, s60, 2
	s_add_u32 s38, s38, 0x100
	s_addc_u32 s39, s39, 0
	s_add_u32 s58, s58, 0x100
	s_addc_u32 s59, s59, 0
	s_cmp_gt_u32 s60, 29
	s_cbranch_scc0 .LBB0_513
	s_and_b64 vcc, exec, s[16:17]
	s_cbranch_vccz .LBB0_516
	s_barrier

; __device__ __forceinline__ float log2_gamma(int hd) { const float e = ldexpf(1.0f, -5 - hd); float p = 1.0f / 7.0f; p = p * e + 1.0f / 6.0f; p = p * e + 0.2f; p = p * e + 0.25f; p = p * e + 1.0f / 3.0f; p = p * e + 0.5f; p = p * e + 1.0f; return -1.44269504089f * e * p; }
; #define PG8_STAGE(bufoff, gbase, voff) do { _Pragma("unroll") for (int _i = 0; _i < 2; ++_i) \
;         __builtin_amdgcn_global_load_lds((const unsigned*)((const char*)(gbase) + (voff)[_i]), (LAS unsigned*)(lds + (bufoff) + ldsw + _i * 8192), 16, 0, 0); } while (0)
; #define PG8_WAIT_V(n) asm volatile("s_waitcnt vmcnt(" #n ")" ::: "memory")
; #define PG8_BAR __builtin_amdgcn_s_barrier()
;     __device__ __forceinline__ void operator()(const f32x4 (&acc)[2][2][4][2], const Unit& u, int wr, int wc, int fr, int fq) const {
;         const int row0 = u.pm * BM + wr * 64 + fr, j0 = wc * 32 + 8 * fq;
;         if (u.pn < 16) {
;             const int hd = u.pn & 7; const bool isq = u.pn < 8;
;             const float l2g = log2_gamma(hd);
;             f32x4 TB[2][6];
; template <class Epi, class Sched>
; __device__ __forceinline__ void gemm_phase(LAS unsigned char* lds, const Gemm g, const Sched& S, const Epi& E) {
;     ...
;     PG8_STAGE(PG8_SB(0, 0), cB, voffB); PG8_STAGE(PG8_SB(0, 1), cB + hstepB, voffB); PG8_STAGE(PG8_SA(0, 0), cA, voffA); PG8_STAGE(PG8_SA(0, 1), cA + hstepA, voffA);
;     if (wr == 1) PG8_BAR;
;     PG8_WAIT_V(2); PG8_BAR;
;     PG8_STAGE(PG8_SB(1, 0), cB + kstep, voffB); PG8_STAGE(PG8_SA(1, 0), cA + kstep, voffA); PG8_STAGE(PG8_SB(1, 1), cB + hstepB + kstep, voffB);
;     PG8_WAIT_V(6); PG8_BAR;
.LBB0_649:
	s_add_u32 s8, s14, 0xd000000
	v_lshrrev_b32_e32 v20, 1, v4
	s_addc_u32 s9, s15, 0
	v_and_b32_e32 v189, 15, v4
	v_and_b32_e32 v21, 24, v20
	s_add_u32 s10, s14, 0x100000
	v_lshlrev_b32_e32 v20, 1, v21
	v_lshlrev_b32_e32 v22, 6, v189
	v_lshlrev_b32_e32 v4, 2, v4
	s_addc_u32 s11, s15, 0
	s_and_b32 s18, s13, 3
	v_or_b32_e32 v23, v22, v20
	s_lshl_b32 s13, s16, 13
	v_and_b32_e32 v4, 32, v4
	s_add_i32 m0, s47, 0x18000
	v_lshl_add_u64 v[12:13], v[12:13], 0, s[36:37]
	s_lshl_b32 s51, s16, 6
	v_bitop3_b32 v24, v23, s13, v4 bitop3:0xde
	s_lshl_b32 s13, s18, 12
	s_waitcnt vmcnt(2)
	s_barrier
	global_load_lds_dwordx4 v[12:13], off
	v_lshl_add_u64 v[10:11], v[10:11], 0, s[36:37]
	s_add_i32 m0, s47, 0x1a000
	s_add_i32 s52, s47, 0x8000
	s_add_i32 s53, s47, 0xa000
	global_load_lds_dwordx4 v[10:11], off
	v_lshl_add_u64 v[6:7], v[6:7], 0, s[36:37]
	s_mov_b32 m0, s52
	s_add_u32 s16, s28, 0x80080
	global_load_lds_dwordx4 v[6:7], off
	v_lshl_add_u64 v[6:7], v[8:9], 0, s[36:37]
	s_mov_b32 m0, s53
	s_addc_u32 s17, s29, 0
	global_load_lds_dwordx4 v[6:7], off
	s_add_i32 m0, s47, 0x1c000
	v_lshl_add_u64 v[6:7], s[16:17], 0, v[182:183]
	global_load_lds_dwordx4 v[6:7], off
	v_lshl_add_u64 v[6:7], s[16:17], 0, v[186:187]
	s_add_i32 m0, s47, 0x1e000
	v_lshl_or_b32 v188, s18, 5, v21
	global_load_lds_dwordx4 v[6:7], off
	v_bitop3_b32 v231, v23, s13, v4 bitop3:0xde
	v_lshlrev_b32_e32 v4, 2, v188
	v_lshl_add_u64 v[6:7], s[14:15], 0, v[4:5]
	s_mov_b64 s[16:17], 0x200000
	s_cmpk_lt_u32 s12, 0x100
	v_lshl_add_u64 v[190:191], v[6:7], 0, s[16:17]
	s_mov_b64 s[16:17], 0x600000
	s_cselect_b64 s[12:13], -1, 0
	v_lshl_add_u64 v[192:193], v[6:7], 0, s[16:17]
	s_lshl_b32 s16, s18, 10
	s_add_u32 s14, s14, s16
	s_addc_u32 s15, s15, 0
	v_mov_b32_e32 v23, v5
	v_lshl_add_u64 v[6:7], s[14:15], 0, v[22:23]
	v_mov_b32_e32 v21, v5
	v_lshlrev_b32_e32 v4, 15, v14
	v_lshl_add_u64 v[6:7], v[6:7], 0, v[20:21]
	s_mov_b64 s[14:15], 0x5000000
	v_and_b32_e32 v4, 0xffff0000, v4
	v_lshl_add_u64 v[194:195], v[6:7], 0, s[14:15]
	v_lshl_add_u32 v4, v15, 12, v4
	v_and_b32_e32 v6, 1, v14
	v_lshl_or_b32 v4, v6, 6, v4
	v_lshl_add_u32 v196, v16, 1, v4
	v_lshlrev_b32_e32 v4, 15, v17
	v_and_b32_e32 v4, 0xffff0000, v4
	s_waitcnt vmcnt(6)
	v_lshl_add_u32 v4, v18, 12, v4
	v_and_b32_e32 v6, 1, v17
	v_lshl_or_b32 v4, v6, 6, v4
	v_mov_b32_e32 v197, v5
	v_lshl_add_u32 v212, v19, 1, v4
	v_mov_b32_e32 v213, v5
	s_mov_b32 s54, 0
	v_add_u32_e32 v235, 0, v24
	s_barrier
	s_branch .LBB0_652
	s_nop 0
	s_nop 0
	s_nop 0
	s_nop 0
	s_nop 0
	s_nop 0
	s_nop 0
	s_nop 0
	s_nop 0
	s_nop 0
	s_nop 0
	s_nop 0
	s_nop 0
	s_nop 0
	s_nop 0
	s_nop 0
	s_nop 0
	s_nop 0
	s_nop 0
	s_nop 0
	s_nop 0
	s_nop 0
	s_nop 0
	s_nop 0
	s_nop 0
	s_nop 0
	s_nop 0
	s_nop 0
	s_nop 0
	s_nop 0
	s_nop 0
	s_nop 0
	s_nop 0
	s_nop 0
	s_nop 0
	s_nop 0
	s_nop 0
	s_nop 0
	s_nop 0
	s_nop 0
	s_nop 0
	s_nop 0
	s_nop 0
	s_nop 0
	s_nop 0
	s_nop 0
	s_nop 0
	s_nop 0
	s_nop 0
	s_nop 0
	s_nop 0
	s_nop 0
	s_nop 0
	s_nop 0
	s_nop 0

; #define PG8_STAGE(bufoff, gbase, voff) do { _Pragma("unroll") for (int _i = 0; _i < 2; ++_i) \
;         __builtin_amdgcn_global_load_lds((const unsigned*)((const char*)(gbase) + (voff)[_i]), (LAS unsigned*)(lds + (bufoff) + ldsw + _i * 8192), 16, 0, 0); } while (0)
; #define PG8_LDA(dst, b, h) do { _Pragma("unroll") for (int m = 0; m < 4; ++m) _Pragma("unroll") for (int k = 0; k < 2; ++k) dst[m][k] = *(const LAS bf16x8*)(lds + PG8_SA(b, h) + aoff + m * 2048 + k * 1024); } while (0)
; #define PG8_LDB(dst, b, h) do { _Pragma("unroll") for (int n = 0; n < 2; ++n) _Pragma("unroll") for (int k = 0; k < 2; ++k) dst[n][k] = *(const LAS bf16x8*)(lds + PG8_SB(b, h) + boff + n * 2048 + k * 1024); } while (0)
; #define PG8_WAIT_V(n) asm volatile("s_waitcnt vmcnt(" #n ")" ::: "memory")
; #define PG8_WAIT_L(n) asm volatile("s_waitcnt lgkmcnt(" #n ")" ::: "memory")
; #define PG8_BAR __builtin_amdgcn_s_barrier()
; #define PG8_SCHED __builtin_amdgcn_sched_barrier(0)
; template <class Epi, class Sched>
; __device__ __forceinline__ void gemm_phase(LAS unsigned char* lds, const Gemm g, const Sched& S, const Epi& E) {
;     ...
;         const bool has_next = S.next(ui + 1, nxt);
;         const char* nA = has_next ? (const char*)g.A + (size_t)nxt.pm * tstepA + (size_t)nxt.ka * 2 : cA; const char* nB = has_next ? (const char*)g.Bt + (size_t)nxt.pn * tstepB : cB;
;         for (int t = 0; t < nt; t += 2) {
;             const bool last = (t == nt - 2);
;             const char* a1 = cA + (size_t)(t + 1) * kstep;
;             const char* a2 = last ? nA : cA + (size_t)(t + 2) * kstep; const char* b2 = last ? nB : cB + (size_t)(t + 2) * kstep;
;             const char* a3 = a2 + kstep; const char* b3 = b2 + kstep;
;             if (last && has_next) S.a_ready(nxt);
;             PG8_LDB(B0, 0, 0); PG8_LDB(B1, 0, 1); PG8_SCHED; PG8_LDA(At, 0, 0); PG8_STAGE(PG8_SA(1, 1), a1 + hstepA, voffA);
;             PG8_WAIT_V(8); PG8_WAIT_L(0); PG8_BAR; PG8_MMA(0, 0, At, B0); PG8_MMA(0, 1, At, B1); PG8_BAR; PG8_SCHED;
;     ...
; #pragma unroll
;         for (int a = 0; a < 2; ++a)
; #pragma unroll
;             for (int b = 0; b < 2; ++b)
; #pragma unroll
;                 for (int m = 0; m < 4; ++m)
; #pragma unroll
;                     for (int n = 0; n < 2; ++n) acc[a][b][m][n] = (f32x4){0.f, 0.f, 0.f, 0.f};
.LBB0_654:
	s_ashr_i32 s17, s16, 31
	s_lshl_b64 s[18:19], s[16:17], 20
	s_add_u32 s18, s42, s18
	s_addc_u32 s19, s43, s19
	s_and_b64 s[20:21], s[38:39], exec
	s_cselect_b32 s17, s19, s27
	s_cselect_b32 s23, s18, s26
	s_ashr_i32 s15, s14, 31
	s_lshl_b64 s[20:21], s[14:15], 20
	s_add_u32 s20, s44, s20
	s_addc_u32 s21, s45, s21
	s_and_b64 s[40:41], s[38:39], exec
	s_cselect_b32 s15, s21, s29
	s_cselect_b32 s25, s20, s28
	s_add_u32 s26, s26, 0x80080
	s_addc_u32 s27, s27, 0
	s_add_u32 s34, s28, 0x100
	v_mov_b32_e32 v6, 0
	s_addc_u32 s55, s29, 0
	s_mov_b32 s56, -2
	v_mov_b32_e32 v7, v6
	v_mov_b32_e32 v8, v6
	v_mov_b32_e32 v9, v6
	v_mov_b32_e32 v10, v6
	v_mov_b32_e32 v11, v6
	v_mov_b32_e32 v12, v6
	v_mov_b32_e32 v13, v6
	v_mov_b32_e32 v22, v6
	v_mov_b32_e32 v23, v6
	v_mov_b32_e32 v24, v6
	v_mov_b32_e32 v25, v6
	v_mov_b32_e32 v26, v6
	v_mov_b32_e32 v27, v6
	v_mov_b32_e32 v28, v6
	v_mov_b32_e32 v29, v6
	v_mov_b32_e32 v38, v6
	v_mov_b32_e32 v39, v6
	v_mov_b32_e32 v40, v6
	v_mov_b32_e32 v41, v6
	v_mov_b32_e32 v42, v6
	v_mov_b32_e32 v43, v6
	v_mov_b32_e32 v44, v6
	v_mov_b32_e32 v45, v6
	v_mov_b32_e32 v54, v6
	v_mov_b32_e32 v55, v6
	v_mov_b32_e32 v56, v6
	v_mov_b32_e32 v57, v6
	v_mov_b32_e32 v58, v6
	v_mov_b32_e32 v59, v6
	v_mov_b32_e32 v60, v6
	v_mov_b32_e32 v61, v6
	v_mov_b32_e32 v14, v6
	v_mov_b32_e32 v15, v6
	v_mov_b32_e32 v16, v6
	v_mov_b32_e32 v17, v6
	v_mov_b32_e32 v18, v6
	v_mov_b32_e32 v19, v6
	v_mov_b32_e32 v20, v6
	v_mov_b32_e32 v21, v6
	v_mov_b32_e32 v30, v6
	v_mov_b32_e32 v31, v6
	v_mov_b32_e32 v32, v6
	v_mov_b32_e32 v33, v6
	v_mov_b32_e32 v34, v6
	v_mov_b32_e32 v35, v6
	v_mov_b32_e32 v36, v6
	v_mov_b32_e32 v37, v6
	v_mov_b32_e32 v46, v6
	v_mov_b32_e32 v47, v6
	v_mov_b32_e32 v48, v6
	v_mov_b32_e32 v49, v6
	v_mov_b32_e32 v50, v6
	v_mov_b32_e32 v51, v6
	v_mov_b32_e32 v52, v6
	v_mov_b32_e32 v53, v6
	v_mov_b32_e32 v62, v6
	v_mov_b32_e32 v63, v6
	v_mov_b32_e32 v64, v6
	v_mov_b32_e32 v65, v6
	v_mov_b32_e32 v66, v6
	v_mov_b32_e32 v67, v6
	v_mov_b32_e32 v68, v6
	v_mov_b32_e32 v69, v6
	v_mov_b32_e32 v70, v6
	v_mov_b32_e32 v71, v6
	v_mov_b32_e32 v72, v6
	v_mov_b32_e32 v73, v6
	v_mov_b32_e32 v74, v6
	v_mov_b32_e32 v75, v6
	v_mov_b32_e32 v76, v6
	v_mov_b32_e32 v77, v6
	v_mov_b32_e32 v86, v6
	v_mov_b32_e32 v87, v6
	v_mov_b32_e32 v88, v6
	v_mov_b32_e32 v89, v6
	v_mov_b32_e32 v90, v6
	v_mov_b32_e32 v91, v6
	v_mov_b32_e32 v92, v6
	v_mov_b32_e32 v93, v6
	v_mov_b32_e32 v102, v6
	v_mov_b32_e32 v103, v6
	v_mov_b32_e32 v104, v6
	v_mov_b32_e32 v105, v6
	v_mov_b32_e32 v106, v6
	v_mov_b32_e32 v107, v6
	v_mov_b32_e32 v108, v6
	v_mov_b32_e32 v109, v6
	v_mov_b32_e32 v118, v6
	v_mov_b32_e32 v119, v6
	v_mov_b32_e32 v120, v6
	v_mov_b32_e32 v121, v6
	v_mov_b32_e32 v122, v6
	v_mov_b32_e32 v123, v6
	v_mov_b32_e32 v124, v6
	v_mov_b32_e32 v125, v6
	v_mov_b32_e32 v78, v6
	v_mov_b32_e32 v79, v6
	v_mov_b32_e32 v80, v6
	v_mov_b32_e32 v81, v6
	v_mov_b32_e32 v82, v6
	v_mov_b32_e32 v83, v6
	v_mov_b32_e32 v84, v6
	v_mov_b32_e32 v85, v6
	v_mov_b32_e32 v94, v6
	v_mov_b32_e32 v95, v6
	v_mov_b32_e32 v96, v6
	v_mov_b32_e32 v97, v6
	v_mov_b32_e32 v98, v6
	v_mov_b32_e32 v99, v6
	v_mov_b32_e32 v100, v6
	v_mov_b32_e32 v101, v6
	v_mov_b32_e32 v110, v6
	v_mov_b32_e32 v111, v6
	v_mov_b32_e32 v112, v6
	v_mov_b32_e32 v113, v6
	v_mov_b32_e32 v114, v6
	v_mov_b32_e32 v115, v6
	v_mov_b32_e32 v116, v6
	v_mov_b32_e32 v117, v6
	v_mov_b32_e32 v126, v6
	v_mov_b32_e32 v127, v6
	v_mov_b32_e32 v128, v6
	v_mov_b32_e32 v129, v6
	v_mov_b32_e32 v130, v6
	v_mov_b32_e32 v131, v6
	v_mov_b32_e32 v132, v6
	v_mov_b32_e32 v133, v6
	v_readfirstlane_b32 s101, v0
.LBB0_655:
	s_add_u32 s28, s26, 0xfff80080
	s_addc_u32 s29, s27, -1
	s_add_i32 s57, 0, 0x10000
	s_cmp_eq_u32 s56, 28
	s_cselect_b32 s41, s17, s29
	s_cselect_b32 s40, s23, s28
	v_add_u32_e32 v4, s57, v231
	s_cselect_b32 s29, s15, s55
	s_cselect_b32 s28, s25, s34
	s_add_i32 s60, 0, 0x14000
	ds_read_b128 v[134:137], v4
	ds_read_b128 v[138:141], v4 offset:1024
	ds_read_b128 v[142:145], v4 offset:2048
	ds_read_b128 v[146:149], v4 offset:3072
	v_add_u32_e32 v4, s60, v231
	ds_read_b128 v[150:153], v4
	ds_read_b128 v[154:157], v4 offset:1024
	ds_read_b128 v[158:161], v4 offset:2048
	ds_read_b128 v[162:165], v4 offset:3072
	v_lshl_add_u64 v[236:237], s[26:27], 0, v[196:197]
	s_add_i32 m0, s47, 0xc000
	ds_read_b128 v[166:169], v235
	ds_read_b128 v[170:173], v235 offset:1024
	ds_read_b128 v[174:177], v235 offset:2048
	ds_read_b128 v[178:181], v235 offset:3072
	ds_read_b128 v[214:217], v235 offset:4096
	ds_read_b128 v[218:221], v235 offset:5120
	ds_read_b128 v[222:225], v235 offset:6144
	ds_read_b128 v[226:229], v235 offset:7168
	global_load_lds_dwordx4 v[236:237], off
	v_lshl_add_u64 v[236:237], s[26:27], 0, v[212:213]
	s_add_i32 m0, s47, 0xe000
	s_nop 0
	global_load_lds_dwordx4 v[236:237], off
	s_bitcmp1_b32 s101, 8
	s_cbranch_scc0 .Lmy_wv_15021
	s_waitcnt vmcnt(8)
; #define PG8_STAGE(bufoff, gbase, voff) do { _Pragma("unroll") for (int _i = 0; _i < 2; ++_i) \
;         __builtin_amdgcn_global_load_lds((const unsigned*)((const char*)(gbase) + (voff)[_i]), (LAS unsigned*)(lds + (bufoff) + ldsw + _i * 8192), 16, 0, 0); } while (0)
; #define PG8_LDA(dst, b, h) do { _Pragma("unroll") for (int m = 0; m < 4; ++m) _Pragma("unroll") for (int k = 0; k < 2; ++k) dst[m][k] = *(const LAS bf16x8*)(lds + PG8_SA(b, h) + aoff + m * 2048 + k * 1024); } while (0)
; #define PG8_LDB(dst, b, h) do { _Pragma("unroll") for (int n = 0; n < 2; ++n) _Pragma("unroll") for (int k = 0; k < 2; ++k) dst[n][k] = *(const LAS bf16x8*)(lds + PG8_SB(b, h) + boff + n * 2048 + k * 1024); } while (0)
; #define PG8_MMA(ai, bj, At, Bt) do { __builtin_amdgcn_s_setprio(1); _Pragma("unroll") for (int m = 0; m < 4; ++m) _Pragma("unroll") for (int n = 0; n < 2; ++n) _Pragma("unroll") for (int k = 0; k < 2; ++k) \
;         acc[ai][bj][m][n] = __builtin_amdgcn_mfma_f32_16x16x32_bf16(Bt[n][k], At[m][k], acc[ai][bj][m][n], 0, 0, 0); __builtin_amdgcn_s_setprio(0); } while (0)
; #define PG8_WAIT_V(n) asm volatile("s_waitcnt vmcnt(" #n ")" ::: "memory")
; #define PG8_WAIT_L(n) asm volatile("s_waitcnt lgkmcnt(" #n ")" ::: "memory")
; #define PG8_BAR __builtin_amdgcn_s_barrier()
; #define PG8_SCHED __builtin_amdgcn_sched_barrier(0)
; template <class Epi, class Sched>
; __device__ __forceinline__ void gemm_phase(LAS unsigned char* lds, const Gemm g, const Sched& S, const Epi& E) {
;     ...
;             PG8_LDB(B0, 0, 0); PG8_LDB(B1, 0, 1); PG8_SCHED; PG8_LDA(At, 0, 0); PG8_STAGE(PG8_SA(1, 1), a1 + hstepA, voffA);
;             PG8_WAIT_V(8); PG8_WAIT_L(0); PG8_BAR; PG8_MMA(0, 0, At, B0); PG8_MMA(0, 1, At, B1); PG8_BAR; PG8_SCHED;
;             PG8_LDA(At, 0, 1); PG8_STAGE(PG8_SB(0, 0), b2, voffB); PG8_STAGE(PG8_SB(0, 1), b2 + hstepB, voffB); PG8_STAGE(PG8_SA(0, 0), a2, voffA);
;             PG8_WAIT_V(8); PG8_WAIT_L(0); PG8_BAR; PG8_MMA(1, 0, At, B0); PG8_MMA(1, 1, At, B1); PG8_BAR; PG8_SCHED;
;             PG8_LDB(B0, 1, 0); PG8_LDB(B1, 1, 1); PG8_SCHED; PG8_LDA(At, 1, 0); PG8_STAGE(PG8_SA(0, 1), a2 + hstepA, voffA);
.Lmy_wv_15021:
	s_waitcnt lgkmcnt(0)
	s_barrier
	s_waitcnt lgkmcnt(0)
	v_mfma_f32_16x16x32_bf16 v[130:133], v[134:137], v[166:169], v[130:133]
	v_mfma_f32_16x16x32_bf16 v[126:129], v[142:145], v[166:169], v[126:129]
	v_mfma_f32_16x16x32_bf16 v[114:117], v[134:137], v[174:177], v[114:117]
	v_mfma_f32_16x16x32_bf16 v[110:113], v[142:145], v[174:177], v[110:113]
	v_mfma_f32_16x16x32_bf16 v[98:101], v[134:137], v[214:217], v[98:101]
	v_mfma_f32_16x16x32_bf16 v[94:97], v[142:145], v[214:217], v[94:97]
	v_mfma_f32_16x16x32_bf16 v[82:85], v[134:137], v[222:225], v[82:85]
	v_mfma_f32_16x16x32_bf16 v[78:81], v[142:145], v[222:225], v[78:81]
	v_mfma_f32_16x16x32_bf16 v[130:133], v[138:141], v[170:173], v[130:133]
	v_mfma_f32_16x16x32_bf16 v[126:129], v[146:149], v[170:173], v[126:129]
	v_mfma_f32_16x16x32_bf16 v[114:117], v[138:141], v[178:181], v[114:117]
	v_mfma_f32_16x16x32_bf16 v[110:113], v[146:149], v[178:181], v[110:113]
	v_mfma_f32_16x16x32_bf16 v[98:101], v[138:141], v[218:221], v[98:101]
	v_mfma_f32_16x16x32_bf16 v[94:97], v[146:149], v[218:221], v[94:97]
	v_mfma_f32_16x16x32_bf16 v[82:85], v[138:141], v[226:229], v[82:85]
	v_mfma_f32_16x16x32_bf16 v[78:81], v[146:149], v[226:229], v[78:81]
	v_mfma_f32_16x16x32_bf16 v[122:125], v[150:153], v[166:169], v[122:125]
	v_mfma_f32_16x16x32_bf16 v[118:121], v[158:161], v[166:169], v[118:121]
	v_mfma_f32_16x16x32_bf16 v[106:109], v[150:153], v[174:177], v[106:109]
	v_mfma_f32_16x16x32_bf16 v[102:105], v[158:161], v[174:177], v[102:105]
	v_mfma_f32_16x16x32_bf16 v[90:93], v[150:153], v[214:217], v[90:93]
	v_mfma_f32_16x16x32_bf16 v[86:89], v[158:161], v[214:217], v[86:89]
	v_mfma_f32_16x16x32_bf16 v[74:77], v[150:153], v[222:225], v[74:77]
	v_mfma_f32_16x16x32_bf16 v[70:73], v[158:161], v[222:225], v[70:73]
	v_mfma_f32_16x16x32_bf16 v[122:125], v[154:157], v[170:173], v[122:125]
	v_mfma_f32_16x16x32_bf16 v[118:121], v[162:165], v[170:173], v[118:121]
	v_mfma_f32_16x16x32_bf16 v[106:109], v[154:157], v[178:181], v[106:109]
	v_mfma_f32_16x16x32_bf16 v[102:105], v[162:165], v[178:181], v[102:105]
	v_mfma_f32_16x16x32_bf16 v[90:93], v[154:157], v[218:221], v[90:93]
	v_mfma_f32_16x16x32_bf16 v[86:89], v[162:165], v[218:221], v[86:89]
	v_mfma_f32_16x16x32_bf16 v[74:77], v[154:157], v[226:229], v[74:77]
	v_mfma_f32_16x16x32_bf16 v[70:73], v[162:165], v[226:229], v[70:73]
	s_waitcnt vmcnt(8)
	s_barrier
	s_add_i32 s57, s57, s46
	v_lshl_add_u64 v[236:237], s[28:29], 0, v[182:183]
	s_mov_b32 m0, s57
	ds_read_b128 v[166:169], v235 offset:16384
	ds_read_b128 v[170:173], v235 offset:17408
	ds_read_b128 v[174:177], v235 offset:18432
	ds_read_b128 v[178:181], v235 offset:19456
	ds_read_b128 v[214:217], v235 offset:20480
	ds_read_b128 v[218:221], v235 offset:21504
	ds_read_b128 v[222:225], v235 offset:22528
	ds_read_b128 v[226:229], v235 offset:23552
	global_load_lds_dwordx4 v[236:237], off
	s_add_i32 m0, s57, 0x2000
	s_add_u32 s58, s28, 0x80000
	v_lshl_add_u64 v[238:239], s[28:29], 0, v[186:187]
	s_addc_u32 s59, s29, 0
	s_add_i32 s57, s60, s46
	global_load_lds_dwordx4 v[238:239], off
	v_lshl_add_u64 v[240:241], s[58:59], 0, v[182:183]
	s_mov_b32 m0, s57
	v_lshl_add_u64 v[242:243], s[40:41], 0, v[184:185]
	global_load_lds_dwordx4 v[240:241], off
	v_lshl_add_u64 v[240:241], s[58:59], 0, v[186:187]
	s_add_i32 m0, s57, 0x2000
	s_nop 0
	global_load_lds_dwordx4 v[240:241], off
	v_lshl_add_u64 v[240:241], s[40:41], 0, v[2:3]
	s_mov_b32 m0, s47
	s_nop 0
	global_load_lds_dwordx4 v[240:241], off
	s_mov_b32 m0, s48
	s_nop 0
	global_load_lds_dwordx4 v[242:243], off
	s_bitcmp1_b32 s101, 8
	s_cbranch_scc0 .Lmy_wv_15100
	s_waitcnt vmcnt(8)
.Lmy_wv_15100:
	s_waitcnt lgkmcnt(0)
	s_barrier
	s_waitcnt lgkmcnt(0)
	v_mfma_f32_16x16x32_bf16 v[66:69], v[134:137], v[166:169], v[66:69]
	v_mfma_f32_16x16x32_bf16 v[62:65], v[142:145], v[166:169], v[62:65]
	v_mfma_f32_16x16x32_bf16 v[50:53], v[134:137], v[174:177], v[50:53]
	v_mfma_f32_16x16x32_bf16 v[46:49], v[142:145], v[174:177], v[46:49]
	v_mfma_f32_16x16x32_bf16 v[34:37], v[134:137], v[214:217], v[34:37]
	v_mfma_f32_16x16x32_bf16 v[30:33], v[142:145], v[214:217], v[30:33]
	v_mfma_f32_16x16x32_bf16 v[18:21], v[134:137], v[222:225], v[18:21]
	v_mfma_f32_16x16x32_bf16 v[14:17], v[142:145], v[222:225], v[14:17]
	v_mfma_f32_16x16x32_bf16 v[66:69], v[138:141], v[170:173], v[66:69]
	v_mfma_f32_16x16x32_bf16 v[62:65], v[146:149], v[170:173], v[62:65]
	v_mfma_f32_16x16x32_bf16 v[50:53], v[138:141], v[178:181], v[50:53]
	v_mfma_f32_16x16x32_bf16 v[46:49], v[146:149], v[178:181], v[46:49]
	v_mfma_f32_16x16x32_bf16 v[34:37], v[138:141], v[218:221], v[34:37]
	v_mfma_f32_16x16x32_bf16 v[30:33], v[146:149], v[218:221], v[30:33]
	v_mfma_f32_16x16x32_bf16 v[18:21], v[138:141], v[226:229], v[18:21]
	v_mfma_f32_16x16x32_bf16 v[14:17], v[146:149], v[226:229], v[14:17]
	v_mfma_f32_16x16x32_bf16 v[58:61], v[150:153], v[166:169], v[58:61]
	v_mfma_f32_16x16x32_bf16 v[54:57], v[158:161], v[166:169], v[54:57]
	v_mfma_f32_16x16x32_bf16 v[42:45], v[150:153], v[174:177], v[42:45]
	v_mfma_f32_16x16x32_bf16 v[38:41], v[158:161], v[174:177], v[38:41]
	v_mfma_f32_16x16x32_bf16 v[26:29], v[150:153], v[214:217], v[26:29]
	v_mfma_f32_16x16x32_bf16 v[22:25], v[158:161], v[214:217], v[22:25]
	v_mfma_f32_16x16x32_bf16 v[10:13], v[150:153], v[222:225], v[10:13]
	v_mfma_f32_16x16x32_bf16 v[6:9], v[158:161], v[222:225], v[6:9]
	v_mfma_f32_16x16x32_bf16 v[58:61], v[154:157], v[170:173], v[58:61]
	v_mfma_f32_16x16x32_bf16 v[54:57], v[162:165], v[170:173], v[54:57]
	v_mfma_f32_16x16x32_bf16 v[42:45], v[154:157], v[178:181], v[42:45]
	v_mfma_f32_16x16x32_bf16 v[38:41], v[162:165], v[178:181], v[38:41]
	v_mfma_f32_16x16x32_bf16 v[26:29], v[154:157], v[218:221], v[26:29]
	v_mfma_f32_16x16x32_bf16 v[22:25], v[162:165], v[218:221], v[22:25]
	v_mfma_f32_16x16x32_bf16 v[10:13], v[154:157], v[226:229], v[10:13]
	v_mfma_f32_16x16x32_bf16 v[6:9], v[162:165], v[226:229], v[6:9]
	s_waitcnt vmcnt(8)
	s_barrier
	s_add_i32 s57, 0, 0x18000
	v_add_u32_e32 v4, s57, v231
	s_add_i32 s58, 0, 0x1c000
	ds_read_b128 v[134:137], v4
	ds_read_b128 v[138:141], v4 offset:1024
	ds_read_b128 v[142:145], v4 offset:2048
	ds_read_b128 v[146:149], v4 offset:3072
	v_add_u32_e32 v4, s58, v231
	ds_read_b128 v[150:153], v4
	ds_read_b128 v[154:157], v4 offset:1024
	ds_read_b128 v[158:161], v4 offset:2048
	ds_read_b128 v[162:165], v4 offset:3072
	s_add_u32 s40, s40, 0x80000
	s_addc_u32 s41, s41, 0
	s_mov_b32 m0, s49
	v_lshl_add_u64 v[244:245], s[40:41], 0, v[2:3]
	ds_read_b128 v[166:169], v235 offset:32768
	ds_read_b128 v[170:173], v235 offset:33792
	ds_read_b128 v[174:177], v235 offset:34816
	ds_read_b128 v[178:181], v235 offset:35840
	ds_read_b128 v[214:217], v235 offset:36864
	ds_read_b128 v[218:221], v235 offset:37888
	ds_read_b128 v[222:225], v235 offset:38912
	ds_read_b128 v[226:229], v235 offset:39936
	global_load_lds_dwordx4 v[244:245], off
	v_lshl_add_u64 v[244:245], s[40:41], 0, v[184:185]
	s_mov_b32 m0, s50
	s_nop 0
	global_load_lds_dwordx4 v[244:245], off
	s_bitcmp1_b32 s101, 8
	s_cbranch_scc0 .Lmy_wv_15176
	s_waitcnt vmcnt(8)
; #define PG8_STAGE(bufoff, gbase, voff) do { _Pragma("unroll") for (int _i = 0; _i < 2; ++_i) \
;         __builtin_amdgcn_global_load_lds((const unsigned*)((const char*)(gbase) + (voff)[_i]), (LAS unsigned*)(lds + (bufoff) + ldsw + _i * 8192), 16, 0, 0); } while (0)
; #define PG8_LDA(dst, b, h) do { _Pragma("unroll") for (int m = 0; m < 4; ++m) _Pragma("unroll") for (int k = 0; k < 2; ++k) dst[m][k] = *(const LAS bf16x8*)(lds + PG8_SA(b, h) + aoff + m * 2048 + k * 1024); } while (0)
; #define PG8_MMA(ai, bj, At, Bt) do { __builtin_amdgcn_s_setprio(1); _Pragma("unroll") for (int m = 0; m < 4; ++m) _Pragma("unroll") for (int n = 0; n < 2; ++n) _Pragma("unroll") for (int k = 0; k < 2; ++k) \
;         acc[ai][bj][m][n] = __builtin_amdgcn_mfma_f32_16x16x32_bf16(Bt[n][k], At[m][k], acc[ai][bj][m][n], 0, 0, 0); __builtin_amdgcn_s_setprio(0); } while (0)
; #define PG8_WAIT_V(n) asm volatile("s_waitcnt vmcnt(" #n ")" ::: "memory")
; #define PG8_WAIT_L(n) asm volatile("s_waitcnt lgkmcnt(" #n ")" ::: "memory")
; #define PG8_BAR __builtin_amdgcn_s_barrier()
; #define PG8_SCHED __builtin_amdgcn_sched_barrier(0)
; template <class Epi, class Sched>
; __device__ __forceinline__ void gemm_phase(LAS unsigned char* lds, const Gemm g, const Sched& S, const Epi& E) {
;     ...
;             PG8_WAIT_V(8); PG8_WAIT_L(0); PG8_BAR; PG8_MMA(0, 0, At, B0); PG8_MMA(0, 1, At, B1); PG8_BAR; PG8_SCHED;
;             PG8_LDA(At, 1, 1); PG8_STAGE(PG8_SB(1, 0), b3, voffB); PG8_STAGE(PG8_SB(1, 1), b3 + hstepB, voffB); PG8_STAGE(PG8_SA(1, 0), a3, voffA);
;             PG8_WAIT_V(8); PG8_WAIT_L(0); PG8_BAR; PG8_MMA(1, 0, At, B0); PG8_MMA(1, 1, At, B1); PG8_BAR; PG8_SCHED;
;         }
;         if (wr == 0) PG8_BAR;
.Lmy_wv_15176:
	s_waitcnt lgkmcnt(0)
	s_barrier
	s_waitcnt lgkmcnt(0)
	v_mfma_f32_16x16x32_bf16 v[130:133], v[134:137], v[166:169], v[130:133]
	v_mfma_f32_16x16x32_bf16 v[126:129], v[142:145], v[166:169], v[126:129]
	v_mfma_f32_16x16x32_bf16 v[114:117], v[134:137], v[174:177], v[114:117]
	v_mfma_f32_16x16x32_bf16 v[110:113], v[142:145], v[174:177], v[110:113]
	v_mfma_f32_16x16x32_bf16 v[98:101], v[134:137], v[214:217], v[98:101]
	v_mfma_f32_16x16x32_bf16 v[94:97], v[142:145], v[214:217], v[94:97]
	v_mfma_f32_16x16x32_bf16 v[82:85], v[134:137], v[222:225], v[82:85]
	v_mfma_f32_16x16x32_bf16 v[78:81], v[142:145], v[222:225], v[78:81]
	v_mfma_f32_16x16x32_bf16 v[130:133], v[138:141], v[170:173], v[130:133]
	v_mfma_f32_16x16x32_bf16 v[126:129], v[146:149], v[170:173], v[126:129]
	v_mfma_f32_16x16x32_bf16 v[114:117], v[138:141], v[178:181], v[114:117]
	v_mfma_f32_16x16x32_bf16 v[110:113], v[146:149], v[178:181], v[110:113]
	v_mfma_f32_16x16x32_bf16 v[98:101], v[138:141], v[218:221], v[98:101]
	v_mfma_f32_16x16x32_bf16 v[94:97], v[146:149], v[218:221], v[94:97]
	v_mfma_f32_16x16x32_bf16 v[82:85], v[138:141], v[226:229], v[82:85]
	v_mfma_f32_16x16x32_bf16 v[78:81], v[146:149], v[226:229], v[78:81]
	v_mfma_f32_16x16x32_bf16 v[122:125], v[150:153], v[166:169], v[122:125]
	v_mfma_f32_16x16x32_bf16 v[118:121], v[158:161], v[166:169], v[118:121]
	v_mfma_f32_16x16x32_bf16 v[106:109], v[150:153], v[174:177], v[106:109]
	v_mfma_f32_16x16x32_bf16 v[102:105], v[158:161], v[174:177], v[102:105]
	v_mfma_f32_16x16x32_bf16 v[90:93], v[150:153], v[214:217], v[90:93]
	v_mfma_f32_16x16x32_bf16 v[86:89], v[158:161], v[214:217], v[86:89]
	v_mfma_f32_16x16x32_bf16 v[74:77], v[150:153], v[222:225], v[74:77]
	v_mfma_f32_16x16x32_bf16 v[70:73], v[158:161], v[222:225], v[70:73]
	v_mfma_f32_16x16x32_bf16 v[122:125], v[154:157], v[170:173], v[122:125]
	v_mfma_f32_16x16x32_bf16 v[118:121], v[162:165], v[170:173], v[118:121]
	v_mfma_f32_16x16x32_bf16 v[106:109], v[154:157], v[178:181], v[106:109]
	v_mfma_f32_16x16x32_bf16 v[102:105], v[162:165], v[178:181], v[102:105]
	v_mfma_f32_16x16x32_bf16 v[90:93], v[154:157], v[218:221], v[90:93]
	v_mfma_f32_16x16x32_bf16 v[86:89], v[162:165], v[218:221], v[86:89]
	v_mfma_f32_16x16x32_bf16 v[74:77], v[154:157], v[226:229], v[74:77]
	v_mfma_f32_16x16x32_bf16 v[70:73], v[162:165], v[226:229], v[70:73]
	s_waitcnt vmcnt(8)
	s_barrier
	s_add_i32 s40, s57, s46
	v_lshl_add_u64 v[236:237], v[236:237], 0, s[36:37]
	s_mov_b32 m0, s40
	ds_read_b128 v[166:169], v235 offset:49152
	ds_read_b128 v[170:173], v235 offset:50176
	ds_read_b128 v[174:177], v235 offset:51200
	ds_read_b128 v[178:181], v235 offset:52224
	ds_read_b128 v[214:217], v235 offset:53248
	ds_read_b128 v[218:221], v235 offset:54272
	ds_read_b128 v[222:225], v235 offset:55296
	ds_read_b128 v[226:229], v235 offset:56320
	global_load_lds_dwordx4 v[236:237], off
	s_add_i32 m0, s40, 0x2000
	s_add_u32 s28, s28, 0x80080
	v_lshl_add_u64 v[236:237], v[238:239], 0, s[36:37]
	s_addc_u32 s29, s29, 0
	s_add_i32 s40, s58, s46
	global_load_lds_dwordx4 v[236:237], off
	v_lshl_add_u64 v[236:237], s[28:29], 0, v[182:183]
	s_mov_b32 m0, s40
	s_nop 0
	global_load_lds_dwordx4 v[236:237], off
	v_lshl_add_u64 v[236:237], s[28:29], 0, v[186:187]
	s_add_i32 m0, s40, 0x2000
	s_nop 0
	global_load_lds_dwordx4 v[236:237], off
	v_lshl_add_u64 v[236:237], v[240:241], 0, s[36:37]
	s_mov_b32 m0, s52
	s_nop 0
	global_load_lds_dwordx4 v[236:237], off
	v_lshl_add_u64 v[236:237], v[242:243], 0, s[36:37]
	s_mov_b32 m0, s53
	s_nop 0
	global_load_lds_dwordx4 v[236:237], off
	s_bitcmp1_b32 s101, 8
	s_cbranch_scc0 .Lmy_wv_15256
	s_waitcnt vmcnt(8)
.Lmy_wv_15256:
	s_waitcnt lgkmcnt(0)
	s_barrier
	s_waitcnt lgkmcnt(0)
	v_mfma_f32_16x16x32_bf16 v[66:69], v[134:137], v[166:169], v[66:69]
	v_mfma_f32_16x16x32_bf16 v[62:65], v[142:145], v[166:169], v[62:65]
	v_mfma_f32_16x16x32_bf16 v[50:53], v[134:137], v[174:177], v[50:53]
	v_mfma_f32_16x16x32_bf16 v[46:49], v[142:145], v[174:177], v[46:49]
	v_mfma_f32_16x16x32_bf16 v[34:37], v[134:137], v[214:217], v[34:37]
	v_mfma_f32_16x16x32_bf16 v[30:33], v[142:145], v[214:217], v[30:33]
	v_mfma_f32_16x16x32_bf16 v[18:21], v[134:137], v[222:225], v[18:21]
	v_mfma_f32_16x16x32_bf16 v[14:17], v[142:145], v[222:225], v[14:17]
	v_mfma_f32_16x16x32_bf16 v[66:69], v[138:141], v[170:173], v[66:69]
	v_mfma_f32_16x16x32_bf16 v[62:65], v[146:149], v[170:173], v[62:65]
	v_mfma_f32_16x16x32_bf16 v[50:53], v[138:141], v[178:181], v[50:53]
	v_mfma_f32_16x16x32_bf16 v[46:49], v[146:149], v[178:181], v[46:49]
	v_mfma_f32_16x16x32_bf16 v[34:37], v[138:141], v[218:221], v[34:37]
	v_mfma_f32_16x16x32_bf16 v[30:33], v[146:149], v[218:221], v[30:33]
	v_mfma_f32_16x16x32_bf16 v[18:21], v[138:141], v[226:229], v[18:21]
	v_mfma_f32_16x16x32_bf16 v[14:17], v[146:149], v[226:229], v[14:17]
	v_mfma_f32_16x16x32_bf16 v[58:61], v[150:153], v[166:169], v[58:61]
	v_mfma_f32_16x16x32_bf16 v[54:57], v[158:161], v[166:169], v[54:57]
	v_mfma_f32_16x16x32_bf16 v[42:45], v[150:153], v[174:177], v[42:45]
	v_mfma_f32_16x16x32_bf16 v[38:41], v[158:161], v[174:177], v[38:41]
	v_mfma_f32_16x16x32_bf16 v[26:29], v[150:153], v[214:217], v[26:29]
	v_mfma_f32_16x16x32_bf16 v[22:25], v[158:161], v[214:217], v[22:25]
	v_mfma_f32_16x16x32_bf16 v[10:13], v[150:153], v[222:225], v[10:13]
	v_mfma_f32_16x16x32_bf16 v[6:9], v[158:161], v[222:225], v[6:9]
	v_mfma_f32_16x16x32_bf16 v[58:61], v[154:157], v[170:173], v[58:61]
	v_mfma_f32_16x16x32_bf16 v[54:57], v[162:165], v[170:173], v[54:57]
	v_mfma_f32_16x16x32_bf16 v[42:45], v[154:157], v[178:181], v[42:45]
	v_mfma_f32_16x16x32_bf16 v[38:41], v[162:165], v[178:181], v[38:41]
	v_mfma_f32_16x16x32_bf16 v[26:29], v[154:157], v[218:221], v[26:29]
	v_mfma_f32_16x16x32_bf16 v[22:25], v[162:165], v[218:221], v[22:25]
	v_mfma_f32_16x16x32_bf16 v[10:13], v[154:157], v[226:229], v[10:13]
	v_mfma_f32_16x16x32_bf16 v[6:9], v[162:165], v[226:229], v[6:9]
	s_waitcnt vmcnt(8)
	s_barrier
	s_add_i32 s56, s56, 2
	s_add_u32 s26, s26, 0x100
	s_addc_u32 s27, s27, 0
	s_add_u32 s34, s34, 0x100
	s_addc_u32 s55, s55, 0
	s_cmp_gt_u32 s56, 29
	s_cbranch_scc0 .LBB0_655
	s_and_b64 vcc, exec, s[12:13]
	s_cbranch_vccz .LBB0_658
	s_barrier

; #define PG8_STAGE(bufoff, gbase, voff) do { _Pragma("unroll") for (int _i = 0; _i < 2; ++_i) \
;         __builtin_amdgcn_global_load_lds((const unsigned*)((const char*)(gbase) + (voff)[_i]), (LAS unsigned*)(lds + (bufoff) + ldsw + _i * 8192), 16, 0, 0); } while (0)
; #define PG8_WAIT_V(n) asm volatile("s_waitcnt vmcnt(" #n ")" ::: "memory")
; #define PG8_BAR __builtin_amdgcn_s_barrier()
; template <class Epi, class Sched>
; __device__ __forceinline__ void gemm_phase(LAS unsigned char* lds, const Gemm g, const Sched& S, const Epi& E) {
;     ...
;     const int aoff = lds_byte(wr * 64 + fr, fq * 8), boff = lds_byte(wc * 32 + fr, fq * 8);
;     ...
;     Unit cur, nxt; int ui = 0;
;     if (!S.next(0, cur)) return;
;     f32x4 acc[2][2][4][2];
; #pragma unroll
;     for (int a = 0; a < 2; ++a)
; #pragma unroll
;         for (int b = 0; b < 2; ++b)
; #pragma unroll
;             for (int m = 0; m < 4; ++m)
; #pragma unroll
;                 for (int n = 0; n < 2; ++n) acc[a][b][m][n] = (f32x4){0.f, 0.f, 0.f, 0.f};
;     bf16x8 At[4][2], B0[2][2], B1[2][2];
;     const char* cA = (const char*)g.A + (size_t)cur.pm * tstepA + (size_t)cur.ka * 2; const char* cB = (const char*)g.Bt + (size_t)cur.pn * tstepB;
;     S.a_ready(cur);
;     PG8_STAGE(PG8_SB(0, 0), cB, voffB); PG8_STAGE(PG8_SB(0, 1), cB + hstepB, voffB); PG8_STAGE(PG8_SA(0, 0), cA, voffA); PG8_STAGE(PG8_SA(0, 1), cA + hstepA, voffA);
;     if (wr == 1) PG8_BAR;
;     PG8_WAIT_V(2); PG8_BAR;
;     PG8_STAGE(PG8_SB(1, 0), cB + kstep, voffB); PG8_STAGE(PG8_SA(1, 0), cA + kstep, voffA); PG8_STAGE(PG8_SB(1, 1), cB + hstepB + kstep, voffB);
;     PG8_WAIT_V(6); PG8_BAR;
;     ...
;         for (int a = 0; a < 2; ++a)
; #pragma unroll
;             for (int b = 0; b < 2; ++b)
; #pragma unroll
;                 for (int m = 0; m < 4; ++m)
; #pragma unroll
;                     for (int n = 0; n < 2; ++n) acc[a][b][m][n] = (f32x4){0.f, 0.f, 0.f, 0.f};
;         cur = nxt; cA = nA; cB = nB; ++ui;
.LBB0_995:
	v_mov_b32_e32 v139, v5
	v_lshl_add_u64 v[10:11], s[24:25], 0, v[138:139]
	v_mov_b32_e32 v135, v5
	v_lshl_add_u64 v[12:13], s[24:25], 0, v[134:135]
	v_mov_b32_e32 v141, v5
	s_add_i32 m0, s58, 0x18000
	v_lshl_add_u64 v[10:11], v[10:11], 0, s[36:37]
	v_lshl_add_u64 v[18:19], s[26:27], 0, v[140:141]
	v_mov_b32_e32 v137, v5
	s_waitcnt vmcnt(2)
	s_barrier
	global_load_lds_dwordx4 v[10:11], off
	v_lshl_add_u64 v[10:11], v[12:13], 0, s[36:37]
	s_add_i32 m0, s58, 0x1a000
	s_add_i32 s62, s58, 0x8000
	v_lshl_add_u64 v[20:21], s[26:27], 0, v[136:137]
	global_load_lds_dwordx4 v[10:11], off
	v_lshl_add_u64 v[10:11], v[18:19], 0, s[36:37]
	s_mov_b32 m0, s62
	s_add_i32 s63, s58, 0xa000
	v_lshl_add_u64 v[14:15], s[4:5], 0, v[138:139]
	global_load_lds_dwordx4 v[10:11], off
	v_lshl_add_u64 v[10:11], v[20:21], 0, s[36:37]
	s_mov_b32 m0, s63
	v_lshl_add_u64 v[16:17], s[4:5], 0, v[134:135]
	global_load_lds_dwordx4 v[10:11], off
	s_add_i32 m0, s58, 0x1c000
	v_lshl_add_u64 v[10:11], v[14:15], 0, s[36:37]
	global_load_lds_dwordx4 v[10:11], off
	v_lshl_add_u64 v[10:11], v[16:17], 0, s[36:37]
	s_add_i32 m0, s58, 0x1e000
	v_and_b32_e32 v168, 15, v169
	global_load_lds_dwordx4 v[10:11], off
	v_and_b32_e32 v9, 48, v169
	v_lshlrev_b32_e32 v10, 2, v169
	s_and_b32 s54, s50, 3
	s_lshr_b32 s64, s6, 6
	v_lshl_or_b32 v9, v168, 6, v9
	s_lshl_b32 s4, s52, 13
	v_and_b32_e32 v10, 32, v10
	v_bitop3_b32 v11, v9, s4, v10 bitop3:0xde
	s_lshl_b32 s4, s54, 12
	s_add_i32 s65, s64, -2
	s_cmpk_lt_u32 s51, 0x100
	v_bitop3_b32 v148, v9, s4, v10 bitop3:0xde
	s_cselect_b64 s[28:29], -1, 0
	s_add_u32 s4, s34, 0x80
	v_add_u32_e32 v4, v8, v4
	s_addc_u32 s5, 0, 0
	v_add_lshl_u32 v4, v4, v7, 1
	v_add_u32_e32 v2, v6, v2
	v_lshl_add_u64 v[142:143], s[4:5], 0, v[4:5]
	v_add_lshl_u32 v4, v2, v3, 1
	s_waitcnt vmcnt(6)
	v_lshl_add_u64 v[144:145], s[4:5], 0, v[4:5]
	v_mov_b32_e32 v4, v5
	v_mov_b32_e32 v2, v5
	v_mov_b32_e32 v3, v5
	v_add_u32_e32 v149, 0, v11
	v_mov_b64_e32 v[8:9], v[4:5]
	v_mov_b64_e32 v[12:13], v[4:5]
	v_mov_b64_e32 v[16:17], v[4:5]
	v_mov_b64_e32 v[20:21], v[4:5]
	v_mov_b64_e32 v[24:25], v[4:5]
	v_mov_b64_e32 v[32:33], v[4:5]
	v_mov_b64_e32 v[40:41], v[4:5]
	v_mov_b64_e32 v[48:49], v[4:5]
	v_mov_b64_e32 v[28:29], v[4:5]
	v_mov_b64_e32 v[36:37], v[4:5]
	v_mov_b64_e32 v[44:45], v[4:5]
	v_mov_b64_e32 v[52:53], v[4:5]
	v_mov_b64_e32 v[56:57], v[4:5]
	v_mov_b64_e32 v[60:61], v[4:5]
	v_mov_b64_e32 v[64:65], v[4:5]
	v_mov_b64_e32 v[68:69], v[4:5]
	v_mov_b64_e32 v[72:73], v[4:5]
	v_mov_b64_e32 v[76:77], v[4:5]
	v_mov_b64_e32 v[80:81], v[4:5]
	v_mov_b64_e32 v[84:85], v[4:5]
	v_mov_b64_e32 v[88:89], v[4:5]
	v_mov_b64_e32 v[96:97], v[4:5]
	v_mov_b64_e32 v[104:105], v[4:5]
	v_mov_b64_e32 v[116:117], v[4:5]
	v_mov_b64_e32 v[92:93], v[4:5]
	v_mov_b64_e32 v[100:101], v[4:5]
	v_mov_b64_e32 v[108:109], v[4:5]
	v_mov_b64_e32 v[112:113], v[4:5]
	v_mov_b64_e32 v[120:121], v[4:5]
	v_mov_b64_e32 v[124:125], v[4:5]
	v_mov_b64_e32 v[128:129], v[4:5]
	v_mov_b64_e32 v[132:133], v[4:5]
	v_readlane_b32 s4, v254, 13
	s_mov_b32 s66, 0
	v_mov_b64_e32 v[6:7], v[2:3]
	v_mov_b64_e32 v[10:11], v[2:3]
	v_mov_b64_e32 v[14:15], v[2:3]
	v_mov_b64_e32 v[18:19], v[2:3]
	v_mov_b64_e32 v[22:23], v[2:3]
	v_mov_b64_e32 v[30:31], v[2:3]
	v_mov_b64_e32 v[38:39], v[2:3]
	v_mov_b64_e32 v[46:47], v[2:3]
	v_mov_b64_e32 v[26:27], v[2:3]
	v_mov_b64_e32 v[34:35], v[2:3]
	v_mov_b64_e32 v[42:43], v[2:3]
	v_mov_b64_e32 v[50:51], v[2:3]
	v_mov_b64_e32 v[54:55], v[2:3]
	v_mov_b64_e32 v[58:59], v[2:3]
	v_mov_b64_e32 v[62:63], v[2:3]
	v_mov_b64_e32 v[66:67], v[2:3]
	v_mov_b64_e32 v[70:71], v[2:3]
	v_mov_b64_e32 v[74:75], v[2:3]
	v_mov_b64_e32 v[78:79], v[2:3]
	v_mov_b64_e32 v[82:83], v[2:3]
	v_mov_b64_e32 v[86:87], v[2:3]
	v_mov_b64_e32 v[94:95], v[2:3]
	v_mov_b64_e32 v[102:103], v[2:3]
	v_mov_b64_e32 v[114:115], v[2:3]
	v_mov_b64_e32 v[90:91], v[2:3]
	v_mov_b64_e32 v[98:99], v[2:3]
	v_mov_b64_e32 v[106:107], v[2:3]
	v_mov_b64_e32 v[110:111], v[2:3]
	v_mov_b64_e32 v[118:119], v[2:3]
	v_mov_b64_e32 v[122:123], v[2:3]
	v_mov_b64_e32 v[126:127], v[2:3]
	v_mov_b64_e32 v[130:131], v[2:3]
	s_mov_b32 s6, s4
	v_readlane_b32 s53, v253, 61
	s_barrier
	s_branch .LBB0_998
	s_nop 0
	s_nop 0
	s_nop 0
	s_nop 0
	s_nop 0
	s_nop 0
	s_nop 0
	s_nop 0
	s_nop 0
	s_nop 0
	s_nop 0
	s_nop 0
	s_nop 0
	s_nop 0
	s_nop 0
	s_nop 0
	s_nop 0
	s_nop 0
	s_nop 0
	s_nop 0
	s_nop 0
	s_nop 0
	s_nop 0
	s_nop 0
	s_nop 0
	s_nop 0
	s_nop 0
	s_nop 0
	s_nop 0
	s_nop 0
	s_nop 0
	s_nop 0
	s_nop 0
	s_nop 0
	s_nop 0
	s_nop 0
	s_nop 0
	s_nop 0
	s_nop 0
	s_nop 0
	s_nop 0
	s_nop 0
.LBB0_996:
	v_mov_b32_e32 v4, v5
	v_mov_b32_e32 v2, v5
	v_mov_b32_e32 v3, v5
	v_mov_b64_e32 v[8:9], v[4:5]
	v_mov_b64_e32 v[12:13], v[4:5]
	v_mov_b64_e32 v[16:17], v[4:5]
	v_mov_b64_e32 v[20:21], v[4:5]
	v_mov_b64_e32 v[24:25], v[4:5]
	v_mov_b64_e32 v[32:33], v[4:5]
	v_mov_b64_e32 v[40:41], v[4:5]
	v_mov_b64_e32 v[48:49], v[4:5]
	v_mov_b64_e32 v[28:29], v[4:5]
	v_mov_b64_e32 v[36:37], v[4:5]
	v_mov_b64_e32 v[44:45], v[4:5]
	v_mov_b64_e32 v[52:53], v[4:5]
	v_mov_b64_e32 v[56:57], v[4:5]
	v_mov_b64_e32 v[60:61], v[4:5]
	v_mov_b64_e32 v[64:65], v[4:5]
	v_mov_b64_e32 v[68:69], v[4:5]
	v_mov_b64_e32 v[72:73], v[4:5]
	v_mov_b64_e32 v[76:77], v[4:5]
	v_mov_b64_e32 v[80:81], v[4:5]
	v_mov_b64_e32 v[84:85], v[4:5]
	v_mov_b64_e32 v[88:89], v[4:5]
	v_mov_b64_e32 v[96:97], v[4:5]
	v_mov_b64_e32 v[104:105], v[4:5]
	v_mov_b64_e32 v[116:117], v[4:5]
	v_mov_b64_e32 v[92:93], v[4:5]
	v_mov_b64_e32 v[100:101], v[4:5]
	v_mov_b64_e32 v[108:109], v[4:5]
	v_mov_b64_e32 v[112:113], v[4:5]
	v_mov_b64_e32 v[120:121], v[4:5]
	v_mov_b64_e32 v[124:125], v[4:5]
	v_mov_b64_e32 v[128:129], v[4:5]
	v_mov_b64_e32 v[132:133], v[4:5]
	v_mov_b64_e32 v[6:7], v[2:3]
	v_mov_b64_e32 v[10:11], v[2:3]
	v_mov_b64_e32 v[14:15], v[2:3]
	v_mov_b64_e32 v[18:19], v[2:3]
	v_mov_b64_e32 v[22:23], v[2:3]
	v_mov_b64_e32 v[30:31], v[2:3]
	v_mov_b64_e32 v[38:39], v[2:3]
	v_mov_b64_e32 v[46:47], v[2:3]
	v_mov_b64_e32 v[26:27], v[2:3]
	v_mov_b64_e32 v[34:35], v[2:3]
	v_mov_b64_e32 v[42:43], v[2:3]
	v_mov_b64_e32 v[50:51], v[2:3]
	v_mov_b64_e32 v[54:55], v[2:3]
	v_mov_b64_e32 v[58:59], v[2:3]
	v_mov_b64_e32 v[62:63], v[2:3]
	v_mov_b64_e32 v[66:67], v[2:3]
	v_mov_b64_e32 v[70:71], v[2:3]
	v_mov_b64_e32 v[74:75], v[2:3]
	v_mov_b64_e32 v[78:79], v[2:3]
	v_mov_b64_e32 v[82:83], v[2:3]
	v_mov_b64_e32 v[86:87], v[2:3]
	v_mov_b64_e32 v[94:95], v[2:3]
	v_mov_b64_e32 v[102:103], v[2:3]
	v_mov_b64_e32 v[114:115], v[2:3]
	v_mov_b64_e32 v[90:91], v[2:3]
	v_mov_b64_e32 v[98:99], v[2:3]
	v_mov_b64_e32 v[106:107], v[2:3]
	v_mov_b64_e32 v[110:111], v[2:3]
	v_mov_b64_e32 v[118:119], v[2:3]
	v_mov_b64_e32 v[122:123], v[2:3]
	v_mov_b64_e32 v[126:127], v[2:3]
	v_mov_b64_e32 v[130:131], v[2:3]
	s_mov_b32 s6, s67
	s_mov_b32 s53, s68
	s_mov_b64 s[24:25], s[44:45]
	s_mov_b64 s[26:27], s[4:5]
	s_mov_b32 s66, s69

; #define PG8_STAGE(bufoff, gbase, voff) do { _Pragma("unroll") for (int _i = 0; _i < 2; ++_i) \
;         __builtin_amdgcn_global_load_lds((const unsigned*)((const char*)(gbase) + (voff)[_i]), (LAS unsigned*)(lds + (bufoff) + ldsw + _i * 8192), 16, 0, 0); } while (0)
; #define PG8_LDA(dst, b, h) do { _Pragma("unroll") for (int m = 0; m < 4; ++m) _Pragma("unroll") for (int k = 0; k < 2; ++k) dst[m][k] = *(const LAS bf16x8*)(lds + PG8_SA(b, h) + aoff + m * 2048 + k * 1024); } while (0)
; #define PG8_LDB(dst, b, h) do { _Pragma("unroll") for (int n = 0; n < 2; ++n) _Pragma("unroll") for (int k = 0; k < 2; ++k) dst[n][k] = *(const LAS bf16x8*)(lds + PG8_SB(b, h) + boff + n * 2048 + k * 1024); } while (0)
; #define PG8_MMA(ai, bj, At, Bt) do { __builtin_amdgcn_s_setprio(1); _Pragma("unroll") for (int m = 0; m < 4; ++m) _Pragma("unroll") for (int n = 0; n < 2; ++n) _Pragma("unroll") for (int k = 0; k < 2; ++k) \
;         acc[ai][bj][m][n] = __builtin_amdgcn_mfma_f32_16x16x32_bf16(Bt[n][k], At[m][k], acc[ai][bj][m][n], 0, 0, 0); __builtin_amdgcn_s_setprio(0); } while (0)
; #define PG8_WAIT_V(n) asm volatile("s_waitcnt vmcnt(" #n ")" ::: "memory")
; #define PG8_WAIT_L(n) asm volatile("s_waitcnt lgkmcnt(" #n ")" ::: "memory")
; #define PG8_BAR __builtin_amdgcn_s_barrier()
; #define PG8_SCHED __builtin_amdgcn_sched_barrier(0)
; template <class Epi, class Sched>
; __device__ __forceinline__ void gemm_phase(LAS unsigned char* lds, const Gemm g, const Sched& S, const Epi& E) {
;     ...
;         for (int t = 0; t < nt; t += 2) {
;             const bool last = (t == nt - 2);
;             const char* a1 = cA + (size_t)(t + 1) * kstep;
;             const char* a2 = last ? nA : cA + (size_t)(t + 2) * kstep; const char* b2 = last ? nB : cB + (size_t)(t + 2) * kstep;
;             const char* a3 = a2 + kstep; const char* b3 = b2 + kstep;
;             if (last && has_next) S.a_ready(nxt);
;             PG8_LDB(B0, 0, 0); PG8_LDB(B1, 0, 1); PG8_SCHED; PG8_LDA(At, 0, 0); PG8_STAGE(PG8_SA(1, 1), a1 + hstepA, voffA);
;             PG8_WAIT_V(8); PG8_WAIT_L(0); PG8_BAR; PG8_MMA(0, 0, At, B0); PG8_MMA(0, 1, At, B1); PG8_BAR; PG8_SCHED;
;             PG8_LDA(At, 0, 1); PG8_STAGE(PG8_SB(0, 0), b2, voffB); PG8_STAGE(PG8_SB(0, 1), b2 + hstepB, voffB); PG8_STAGE(PG8_SA(0, 0), a2, voffA);
.LBB0_1008:
	s_mov_b32 s48, 0
	s_mov_b64 s[46:47], 0x100
	v_mov_b64_e32 v[2:3], v[144:145]
	v_mov_b64_e32 v[146:147], v[142:143]
	v_readfirstlane_b32 s101, v0
.LBB0_1009:
	s_add_i32 s43, s48, 2
	s_add_u32 s70, s26, s46
	s_addc_u32 s49, s27, s47
	s_add_u32 s72, s24, s46
	s_addc_u32 s71, s25, s47
	s_add_i32 s73, 0, 0x10000
	s_cmp_eq_u32 s65, s48
	s_cselect_b32 s49, s5, s49
	s_cselect_b32 s48, s4, s70
	v_add_u32_e32 v4, s73, v148
	s_cselect_b32 s71, s45, s71
	s_cselect_b32 s70, s44, s72
	s_add_i32 s72, 0, 0x14000
	ds_read_b128 v[150:153], v4
	ds_read_b128 v[154:157], v4 offset:1024
	ds_read_b128 v[158:161], v4 offset:2048
	ds_read_b128 v[162:165], v4 offset:3072
	v_add_u32_e32 v4, s72, v148
	ds_read_b128 v[170:173], v4
	ds_read_b128 v[174:177], v4 offset:1024
	ds_read_b128 v[178:181], v4 offset:2048
	ds_read_b128 v[182:185], v4 offset:3072
	v_lshl_add_u64 v[166:167], s[26:27], 0, v[146:147]
	s_add_i32 m0, s58, 0xc000
	ds_read_b128 v[186:189], v149
	ds_read_b128 v[190:193], v149 offset:1024
	ds_read_b128 v[194:197], v149 offset:2048
	ds_read_b128 v[212:215], v149 offset:3072
	ds_read_b128 v[216:219], v149 offset:4096
	ds_read_b128 v[220:223], v149 offset:5120
	ds_read_b128 v[224:227], v149 offset:6144
	ds_read_b128 v[228:231], v149 offset:7168
	global_load_lds_dwordx4 v[166:167], off
	v_lshl_add_u64 v[166:167], s[26:27], 0, v[2:3]
	s_add_i32 m0, s58, 0xe000
	s_nop 0
	global_load_lds_dwordx4 v[166:167], off
	s_bitcmp1_b32 s101, 8
	s_cbranch_scc0 .Lmy_wv_25661
	s_waitcnt vmcnt(8)
.Lmy_wv_25661:
	s_waitcnt lgkmcnt(0)
	s_barrier
	s_waitcnt lgkmcnt(0)
	v_mfma_f32_16x16x32_bf16 v[130:133], v[150:153], v[186:189], v[130:133]
	v_mfma_f32_16x16x32_bf16 v[126:129], v[158:161], v[186:189], v[126:129]
	v_mfma_f32_16x16x32_bf16 v[122:125], v[150:153], v[194:197], v[122:125]
	v_mfma_f32_16x16x32_bf16 v[118:121], v[158:161], v[194:197], v[118:121]
	v_mfma_f32_16x16x32_bf16 v[110:113], v[150:153], v[216:219], v[110:113]
	v_mfma_f32_16x16x32_bf16 v[106:109], v[158:161], v[216:219], v[106:109]
	v_mfma_f32_16x16x32_bf16 v[98:101], v[150:153], v[224:227], v[98:101]
	v_mfma_f32_16x16x32_bf16 v[90:93], v[158:161], v[224:227], v[90:93]
	v_mfma_f32_16x16x32_bf16 v[130:133], v[154:157], v[190:193], v[130:133]
	v_mfma_f32_16x16x32_bf16 v[126:129], v[162:165], v[190:193], v[126:129]
	v_mfma_f32_16x16x32_bf16 v[122:125], v[154:157], v[212:215], v[122:125]
	v_mfma_f32_16x16x32_bf16 v[118:121], v[162:165], v[212:215], v[118:121]
	v_mfma_f32_16x16x32_bf16 v[110:113], v[154:157], v[220:223], v[110:113]
	v_mfma_f32_16x16x32_bf16 v[106:109], v[162:165], v[220:223], v[106:109]
	v_mfma_f32_16x16x32_bf16 v[98:101], v[154:157], v[228:231], v[98:101]
	v_mfma_f32_16x16x32_bf16 v[90:93], v[162:165], v[228:231], v[90:93]
	v_mfma_f32_16x16x32_bf16 v[114:117], v[170:173], v[186:189], v[114:117]
	v_mfma_f32_16x16x32_bf16 v[102:105], v[178:181], v[186:189], v[102:105]
	v_mfma_f32_16x16x32_bf16 v[94:97], v[170:173], v[194:197], v[94:97]
	v_mfma_f32_16x16x32_bf16 v[86:89], v[178:181], v[194:197], v[86:89]
	v_mfma_f32_16x16x32_bf16 v[82:85], v[170:173], v[216:219], v[82:85]
	v_mfma_f32_16x16x32_bf16 v[78:81], v[178:181], v[216:219], v[78:81]
	v_mfma_f32_16x16x32_bf16 v[74:77], v[170:173], v[224:227], v[74:77]
	v_mfma_f32_16x16x32_bf16 v[70:73], v[178:181], v[224:227], v[70:73]
	v_mfma_f32_16x16x32_bf16 v[114:117], v[174:177], v[190:193], v[114:117]
	v_mfma_f32_16x16x32_bf16 v[102:105], v[182:185], v[190:193], v[102:105]
	v_mfma_f32_16x16x32_bf16 v[94:97], v[174:177], v[212:215], v[94:97]
	v_mfma_f32_16x16x32_bf16 v[86:89], v[182:185], v[212:215], v[86:89]
	v_mfma_f32_16x16x32_bf16 v[82:85], v[174:177], v[220:223], v[82:85]
	v_mfma_f32_16x16x32_bf16 v[78:81], v[182:185], v[220:223], v[78:81]
	v_mfma_f32_16x16x32_bf16 v[74:77], v[174:177], v[228:231], v[74:77]
	v_mfma_f32_16x16x32_bf16 v[70:73], v[182:185], v[228:231], v[70:73]
	s_waitcnt vmcnt(8)
	s_barrier
	s_add_i32 s73, s73, s57
	v_lshl_add_u64 v[166:167], s[70:71], 0, v[138:139]
	s_mov_b32 m0, s73
	ds_read_b128 v[186:189], v149 offset:16384
	ds_read_b128 v[190:193], v149 offset:17408
	ds_read_b128 v[194:197], v149 offset:18432
	ds_read_b128 v[212:215], v149 offset:19456
	ds_read_b128 v[216:219], v149 offset:20480
	ds_read_b128 v[220:223], v149 offset:21504
	ds_read_b128 v[224:227], v149 offset:22528
	ds_read_b128 v[228:231], v149 offset:23552
	global_load_lds_dwordx4 v[166:167], off
	s_add_i32 m0, s73, 0x2000
	v_lshl_add_u64 v[236:237], s[70:71], 0, v[134:135]
	s_add_u32 s70, s70, s55
	s_addc_u32 s71, s71, 0
	s_add_i32 s72, s72, s57
	global_load_lds_dwordx4 v[236:237], off
	v_lshl_add_u64 v[238:239], s[70:71], 0, v[138:139]
	s_mov_b32 m0, s72
	v_lshl_add_u64 v[240:241], s[70:71], 0, v[134:135]
	global_load_lds_dwordx4 v[238:239], off
	s_add_i32 m0, s72, 0x2000
	v_lshl_add_u64 v[242:243], s[48:49], 0, v[140:141]
	global_load_lds_dwordx4 v[240:241], off
	s_mov_b32 m0, s58
	v_lshl_add_u64 v[244:245], s[48:49], 0, v[136:137]
	global_load_lds_dwordx4 v[242:243], off
	s_mov_b32 m0, s59
	s_nop 0
	global_load_lds_dwordx4 v[244:245], off
	s_bitcmp1_b32 s101, 8
	s_cbranch_scc0 .Lmy_wv_25738
	s_waitcnt vmcnt(8)
; #define PG8_STAGE(bufoff, gbase, voff) do { _Pragma("unroll") for (int _i = 0; _i < 2; ++_i) \
;         __builtin_amdgcn_global_load_lds((const unsigned*)((const char*)(gbase) + (voff)[_i]), (LAS unsigned*)(lds + (bufoff) + ldsw + _i * 8192), 16, 0, 0); } while (0)
; #define PG8_LDA(dst, b, h) do { _Pragma("unroll") for (int m = 0; m < 4; ++m) _Pragma("unroll") for (int k = 0; k < 2; ++k) dst[m][k] = *(const LAS bf16x8*)(lds + PG8_SA(b, h) + aoff + m * 2048 + k * 1024); } while (0)
; #define PG8_LDB(dst, b, h) do { _Pragma("unroll") for (int n = 0; n < 2; ++n) _Pragma("unroll") for (int k = 0; k < 2; ++k) dst[n][k] = *(const LAS bf16x8*)(lds + PG8_SB(b, h) + boff + n * 2048 + k * 1024); } while (0)
; #define PG8_MMA(ai, bj, At, Bt) do { __builtin_amdgcn_s_setprio(1); _Pragma("unroll") for (int m = 0; m < 4; ++m) _Pragma("unroll") for (int n = 0; n < 2; ++n) _Pragma("unroll") for (int k = 0; k < 2; ++k) \
;         acc[ai][bj][m][n] = __builtin_amdgcn_mfma_f32_16x16x32_bf16(Bt[n][k], At[m][k], acc[ai][bj][m][n], 0, 0, 0); __builtin_amdgcn_s_setprio(0); } while (0)
; #define PG8_WAIT_V(n) asm volatile("s_waitcnt vmcnt(" #n ")" ::: "memory")
; #define PG8_WAIT_L(n) asm volatile("s_waitcnt lgkmcnt(" #n ")" ::: "memory")
; #define PG8_BAR __builtin_amdgcn_s_barrier()
; #define PG8_SCHED __builtin_amdgcn_sched_barrier(0)
; template <class Epi, class Sched>
; __device__ __forceinline__ void gemm_phase(LAS unsigned char* lds, const Gemm g, const Sched& S, const Epi& E) {
;     ...
;             PG8_WAIT_V(8); PG8_WAIT_L(0); PG8_BAR; PG8_MMA(1, 0, At, B0); PG8_MMA(1, 1, At, B1); PG8_BAR; PG8_SCHED;
;             PG8_LDB(B0, 1, 0); PG8_LDB(B1, 1, 1); PG8_SCHED; PG8_LDA(At, 1, 0); PG8_STAGE(PG8_SA(0, 1), a2 + hstepA, voffA);
.Lmy_wv_25738:
	s_waitcnt lgkmcnt(0)
	s_barrier
	s_waitcnt lgkmcnt(0)
	v_mfma_f32_16x16x32_bf16 v[66:69], v[150:153], v[186:189], v[66:69]
	v_mfma_f32_16x16x32_bf16 v[62:65], v[158:161], v[186:189], v[62:65]
	v_mfma_f32_16x16x32_bf16 v[58:61], v[150:153], v[194:197], v[58:61]
	v_mfma_f32_16x16x32_bf16 v[54:57], v[158:161], v[194:197], v[54:57]
	v_mfma_f32_16x16x32_bf16 v[50:53], v[150:153], v[216:219], v[50:53]
	v_mfma_f32_16x16x32_bf16 v[42:45], v[158:161], v[216:219], v[42:45]
	v_mfma_f32_16x16x32_bf16 v[34:37], v[150:153], v[224:227], v[34:37]
	v_mfma_f32_16x16x32_bf16 v[26:29], v[158:161], v[224:227], v[26:29]
	v_mfma_f32_16x16x32_bf16 v[66:69], v[154:157], v[190:193], v[66:69]
	v_mfma_f32_16x16x32_bf16 v[62:65], v[162:165], v[190:193], v[62:65]
	v_mfma_f32_16x16x32_bf16 v[58:61], v[154:157], v[212:215], v[58:61]
	v_mfma_f32_16x16x32_bf16 v[54:57], v[162:165], v[212:215], v[54:57]
	v_mfma_f32_16x16x32_bf16 v[50:53], v[154:157], v[220:223], v[50:53]
	v_mfma_f32_16x16x32_bf16 v[42:45], v[162:165], v[220:223], v[42:45]
	v_mfma_f32_16x16x32_bf16 v[34:37], v[154:157], v[228:231], v[34:37]
	v_mfma_f32_16x16x32_bf16 v[26:29], v[162:165], v[228:231], v[26:29]
	v_mfma_f32_16x16x32_bf16 v[46:49], v[170:173], v[186:189], v[46:49]
	v_mfma_f32_16x16x32_bf16 v[38:41], v[178:181], v[186:189], v[38:41]
	v_mfma_f32_16x16x32_bf16 v[30:33], v[170:173], v[194:197], v[30:33]
	v_mfma_f32_16x16x32_bf16 v[22:25], v[178:181], v[194:197], v[22:25]
	v_mfma_f32_16x16x32_bf16 v[18:21], v[170:173], v[216:219], v[18:21]
	v_mfma_f32_16x16x32_bf16 v[14:17], v[178:181], v[216:219], v[14:17]
	v_mfma_f32_16x16x32_bf16 v[10:13], v[170:173], v[224:227], v[10:13]
	v_mfma_f32_16x16x32_bf16 v[6:9], v[178:181], v[224:227], v[6:9]
	v_mfma_f32_16x16x32_bf16 v[46:49], v[174:177], v[190:193], v[46:49]
	v_mfma_f32_16x16x32_bf16 v[38:41], v[182:185], v[190:193], v[38:41]
	v_mfma_f32_16x16x32_bf16 v[30:33], v[174:177], v[212:215], v[30:33]
	v_mfma_f32_16x16x32_bf16 v[22:25], v[182:185], v[212:215], v[22:25]
	v_mfma_f32_16x16x32_bf16 v[18:21], v[174:177], v[220:223], v[18:21]
	v_mfma_f32_16x16x32_bf16 v[14:17], v[182:185], v[220:223], v[14:17]
	v_mfma_f32_16x16x32_bf16 v[10:13], v[174:177], v[228:231], v[10:13]
	v_mfma_f32_16x16x32_bf16 v[6:9], v[182:185], v[228:231], v[6:9]
	s_waitcnt vmcnt(8)
	s_barrier
	s_add_i32 s70, 0, 0x18000
	v_add_u32_e32 v4, s70, v148
	s_add_i32 s71, 0, 0x1c000
	ds_read_b128 v[150:153], v4
	ds_read_b128 v[154:157], v4 offset:1024
	ds_read_b128 v[158:161], v4 offset:2048
	ds_read_b128 v[162:165], v4 offset:3072
	v_add_u32_e32 v4, s71, v148
	ds_read_b128 v[170:173], v4
	ds_read_b128 v[174:177], v4 offset:1024
	ds_read_b128 v[178:181], v4 offset:2048
	ds_read_b128 v[182:185], v4 offset:3072
	s_add_u32 s48, s48, s34
	s_addc_u32 s49, s49, 0
	s_mov_b32 m0, s60
	v_lshl_add_u64 v[246:247], s[48:49], 0, v[140:141]
	ds_read_b128 v[186:189], v149 offset:32768
	ds_read_b128 v[190:193], v149 offset:33792
	ds_read_b128 v[194:197], v149 offset:34816
	ds_read_b128 v[212:215], v149 offset:35840
	ds_read_b128 v[216:219], v149 offset:36864
	ds_read_b128 v[220:223], v149 offset:37888
	ds_read_b128 v[224:227], v149 offset:38912
	ds_read_b128 v[228:231], v149 offset:39936
	global_load_lds_dwordx4 v[246:247], off
	v_lshl_add_u64 v[246:247], s[48:49], 0, v[136:137]
	s_mov_b32 m0, s61
	s_nop 0
	global_load_lds_dwordx4 v[246:247], off
	s_bitcmp1_b32 s101, 8
	s_cbranch_scc0 .Lmy_wv_25814
	s_waitcnt vmcnt(8)
; #define PG8_STAGE(bufoff, gbase, voff) do { _Pragma("unroll") for (int _i = 0; _i < 2; ++_i) \
;         __builtin_amdgcn_global_load_lds((const unsigned*)((const char*)(gbase) + (voff)[_i]), (LAS unsigned*)(lds + (bufoff) + ldsw + _i * 8192), 16, 0, 0); } while (0)
; #define PG8_LDA(dst, b, h) do { _Pragma("unroll") for (int m = 0; m < 4; ++m) _Pragma("unroll") for (int k = 0; k < 2; ++k) dst[m][k] = *(const LAS bf16x8*)(lds + PG8_SA(b, h) + aoff + m * 2048 + k * 1024); } while (0)
; #define PG8_MMA(ai, bj, At, Bt) do { __builtin_amdgcn_s_setprio(1); _Pragma("unroll") for (int m = 0; m < 4; ++m) _Pragma("unroll") for (int n = 0; n < 2; ++n) _Pragma("unroll") for (int k = 0; k < 2; ++k) \
;         acc[ai][bj][m][n] = __builtin_amdgcn_mfma_f32_16x16x32_bf16(Bt[n][k], At[m][k], acc[ai][bj][m][n], 0, 0, 0); __builtin_amdgcn_s_setprio(0); } while (0)
; #define PG8_WAIT_V(n) asm volatile("s_waitcnt vmcnt(" #n ")" ::: "memory")
; #define PG8_WAIT_L(n) asm volatile("s_waitcnt lgkmcnt(" #n ")" ::: "memory")
; #define PG8_BAR __builtin_amdgcn_s_barrier()
; #define PG8_SCHED __builtin_amdgcn_sched_barrier(0)
; template <class Epi, class Sched>
; __device__ __forceinline__ void gemm_phase(LAS unsigned char* lds, const Gemm g, const Sched& S, const Epi& E) {
;     ...
;             PG8_WAIT_V(8); PG8_WAIT_L(0); PG8_BAR; PG8_MMA(0, 0, At, B0); PG8_MMA(0, 1, At, B1); PG8_BAR; PG8_SCHED;
;             PG8_LDA(At, 1, 1); PG8_STAGE(PG8_SB(1, 0), b3, voffB); PG8_STAGE(PG8_SB(1, 1), b3 + hstepB, voffB); PG8_STAGE(PG8_SA(1, 0), a3, voffA);
;             PG8_WAIT_V(8); PG8_WAIT_L(0); PG8_BAR; PG8_MMA(1, 0, At, B0); PG8_MMA(1, 1, At, B1); PG8_BAR; PG8_SCHED;
;         }
;         if (wr == 0) PG8_BAR;
.Lmy_wv_25814:
	s_waitcnt lgkmcnt(0)
	s_barrier
	s_waitcnt lgkmcnt(0)
	v_mfma_f32_16x16x32_bf16 v[130:133], v[150:153], v[186:189], v[130:133]
	v_mfma_f32_16x16x32_bf16 v[126:129], v[158:161], v[186:189], v[126:129]
	v_mfma_f32_16x16x32_bf16 v[122:125], v[150:153], v[194:197], v[122:125]
	v_mfma_f32_16x16x32_bf16 v[118:121], v[158:161], v[194:197], v[118:121]
	v_mfma_f32_16x16x32_bf16 v[110:113], v[150:153], v[216:219], v[110:113]
	v_mfma_f32_16x16x32_bf16 v[106:109], v[158:161], v[216:219], v[106:109]
	v_mfma_f32_16x16x32_bf16 v[98:101], v[150:153], v[224:227], v[98:101]
	v_mfma_f32_16x16x32_bf16 v[90:93], v[158:161], v[224:227], v[90:93]
	v_mfma_f32_16x16x32_bf16 v[130:133], v[154:157], v[190:193], v[130:133]
	v_mfma_f32_16x16x32_bf16 v[126:129], v[162:165], v[190:193], v[126:129]
	v_mfma_f32_16x16x32_bf16 v[122:125], v[154:157], v[212:215], v[122:125]
	v_mfma_f32_16x16x32_bf16 v[118:121], v[162:165], v[212:215], v[118:121]
	v_mfma_f32_16x16x32_bf16 v[110:113], v[154:157], v[220:223], v[110:113]
	v_mfma_f32_16x16x32_bf16 v[106:109], v[162:165], v[220:223], v[106:109]
	v_mfma_f32_16x16x32_bf16 v[98:101], v[154:157], v[228:231], v[98:101]
	v_mfma_f32_16x16x32_bf16 v[90:93], v[162:165], v[228:231], v[90:93]
	v_mfma_f32_16x16x32_bf16 v[114:117], v[170:173], v[186:189], v[114:117]
	v_mfma_f32_16x16x32_bf16 v[102:105], v[178:181], v[186:189], v[102:105]
	v_mfma_f32_16x16x32_bf16 v[94:97], v[170:173], v[194:197], v[94:97]
	v_mfma_f32_16x16x32_bf16 v[86:89], v[178:181], v[194:197], v[86:89]
	v_mfma_f32_16x16x32_bf16 v[82:85], v[170:173], v[216:219], v[82:85]
	v_mfma_f32_16x16x32_bf16 v[78:81], v[178:181], v[216:219], v[78:81]
	v_mfma_f32_16x16x32_bf16 v[74:77], v[170:173], v[224:227], v[74:77]
	v_mfma_f32_16x16x32_bf16 v[70:73], v[178:181], v[224:227], v[70:73]
	v_mfma_f32_16x16x32_bf16 v[114:117], v[174:177], v[190:193], v[114:117]
	v_mfma_f32_16x16x32_bf16 v[102:105], v[182:185], v[190:193], v[102:105]
	v_mfma_f32_16x16x32_bf16 v[94:97], v[174:177], v[212:215], v[94:97]
	v_mfma_f32_16x16x32_bf16 v[86:89], v[182:185], v[212:215], v[86:89]
	v_mfma_f32_16x16x32_bf16 v[82:85], v[174:177], v[220:223], v[82:85]
	v_mfma_f32_16x16x32_bf16 v[78:81], v[182:185], v[220:223], v[78:81]
	v_mfma_f32_16x16x32_bf16 v[74:77], v[174:177], v[228:231], v[74:77]
	v_mfma_f32_16x16x32_bf16 v[70:73], v[182:185], v[228:231], v[70:73]
	s_waitcnt vmcnt(8)
	s_barrier
	s_add_i32 s48, s70, s57
	v_lshl_add_u64 v[166:167], v[166:167], 0, s[36:37]
	s_mov_b32 m0, s48
	ds_read_b128 v[186:189], v149 offset:49152
	ds_read_b128 v[190:193], v149 offset:50176
	ds_read_b128 v[194:197], v149 offset:51200
	ds_read_b128 v[212:215], v149 offset:52224
	ds_read_b128 v[216:219], v149 offset:53248
	ds_read_b128 v[220:223], v149 offset:54272
	ds_read_b128 v[224:227], v149 offset:55296
	ds_read_b128 v[228:231], v149 offset:56320
	global_load_lds_dwordx4 v[166:167], off
	v_lshl_add_u64 v[166:167], v[236:237], 0, s[36:37]
	s_add_i32 m0, s48, 0x2000
	s_add_i32 s48, s71, s57
	global_load_lds_dwordx4 v[166:167], off
	v_lshl_add_u64 v[166:167], v[238:239], 0, s[36:37]
	s_mov_b32 m0, s48
	s_nop 0
	global_load_lds_dwordx4 v[166:167], off
	v_lshl_add_u64 v[166:167], v[240:241], 0, s[36:37]
	s_add_i32 m0, s48, 0x2000
	s_nop 0
	global_load_lds_dwordx4 v[166:167], off
	v_lshl_add_u64 v[166:167], v[242:243], 0, s[36:37]
	s_mov_b32 m0, s62
	s_nop 0
	global_load_lds_dwordx4 v[166:167], off
	v_lshl_add_u64 v[166:167], v[244:245], 0, s[36:37]
	s_mov_b32 m0, s63
	s_nop 0
	global_load_lds_dwordx4 v[166:167], off
	s_bitcmp1_b32 s101, 8
	s_cbranch_scc0 .Lmy_wv_25892
	s_waitcnt vmcnt(8)
.Lmy_wv_25892:
	s_waitcnt lgkmcnt(0)
	s_barrier
	s_waitcnt lgkmcnt(0)
	v_mfma_f32_16x16x32_bf16 v[66:69], v[150:153], v[186:189], v[66:69]
	v_mfma_f32_16x16x32_bf16 v[62:65], v[158:161], v[186:189], v[62:65]
	v_mfma_f32_16x16x32_bf16 v[58:61], v[150:153], v[194:197], v[58:61]
	v_mfma_f32_16x16x32_bf16 v[54:57], v[158:161], v[194:197], v[54:57]
	v_mfma_f32_16x16x32_bf16 v[50:53], v[150:153], v[216:219], v[50:53]
	v_mfma_f32_16x16x32_bf16 v[42:45], v[158:161], v[216:219], v[42:45]
	v_mfma_f32_16x16x32_bf16 v[34:37], v[150:153], v[224:227], v[34:37]
	v_mfma_f32_16x16x32_bf16 v[26:29], v[158:161], v[224:227], v[26:29]
	v_mfma_f32_16x16x32_bf16 v[66:69], v[154:157], v[190:193], v[66:69]
	v_mfma_f32_16x16x32_bf16 v[62:65], v[162:165], v[190:193], v[62:65]
	v_mfma_f32_16x16x32_bf16 v[58:61], v[154:157], v[212:215], v[58:61]
	v_mfma_f32_16x16x32_bf16 v[54:57], v[162:165], v[212:215], v[54:57]
	v_mfma_f32_16x16x32_bf16 v[50:53], v[154:157], v[220:223], v[50:53]
	v_mfma_f32_16x16x32_bf16 v[42:45], v[162:165], v[220:223], v[42:45]
	v_mfma_f32_16x16x32_bf16 v[34:37], v[154:157], v[228:231], v[34:37]
	v_mfma_f32_16x16x32_bf16 v[26:29], v[162:165], v[228:231], v[26:29]
	v_mfma_f32_16x16x32_bf16 v[46:49], v[170:173], v[186:189], v[46:49]
	v_mfma_f32_16x16x32_bf16 v[38:41], v[178:181], v[186:189], v[38:41]
	v_mfma_f32_16x16x32_bf16 v[30:33], v[170:173], v[194:197], v[30:33]
	v_mfma_f32_16x16x32_bf16 v[22:25], v[178:181], v[194:197], v[22:25]
	v_mfma_f32_16x16x32_bf16 v[18:21], v[170:173], v[216:219], v[18:21]
	v_mfma_f32_16x16x32_bf16 v[14:17], v[178:181], v[216:219], v[14:17]
	v_mfma_f32_16x16x32_bf16 v[10:13], v[170:173], v[224:227], v[10:13]
	v_mfma_f32_16x16x32_bf16 v[6:9], v[178:181], v[224:227], v[6:9]
	v_mfma_f32_16x16x32_bf16 v[46:49], v[174:177], v[190:193], v[46:49]
	v_mfma_f32_16x16x32_bf16 v[38:41], v[182:185], v[190:193], v[38:41]
	v_mfma_f32_16x16x32_bf16 v[30:33], v[174:177], v[212:215], v[30:33]
	v_mfma_f32_16x16x32_bf16 v[22:25], v[182:185], v[212:215], v[22:25]
	v_mfma_f32_16x16x32_bf16 v[18:21], v[174:177], v[220:223], v[18:21]
	v_mfma_f32_16x16x32_bf16 v[14:17], v[182:185], v[220:223], v[14:17]
	v_mfma_f32_16x16x32_bf16 v[10:13], v[174:177], v[228:231], v[10:13]
	v_mfma_f32_16x16x32_bf16 v[6:9], v[182:185], v[228:231], v[6:9]
	s_waitcnt vmcnt(8)
	s_barrier
	s_add_u32 s46, s46, 0x100
	s_addc_u32 s47, s47, 0
	v_lshl_add_u64 v[146:147], v[146:147], 0, s[30:31]
	v_lshl_add_u64 v[2:3], v[2:3], 0, s[30:31]
	s_cmp_ge_u32 s43, s64
	s_mov_b32 s48, s43
	s_cbranch_scc0 .LBB0_1009
	s_and_b64 vcc, exec, s[28:29]
	s_cbranch_vccz .LBB0_1012
	s_barrier
